# silu gate chains: two independent multiplies moved into the wait states after v_exp and v_rcp, replacing the two s_nop per element
# speedup vs baseline: 1.0082x; 1.0002x over previous
; #define LAS __attribute__((address_space(3)))
; #define MFMA32(a, b, c) __builtin_amdgcn_mfma_f32_32x32x16_bf16((a), (b), (c), 0, 0, 0)
; DI void gla_stage3(const Ctx& c0, int layer, int unit, int cb, LAS unsigned char* lds) {
;     ...
;     const size_t row0 = (size_t)b * SEQ + n * 64 + 32 * cb;
;     LAS unsigned char* R = lds + c.wid * G3_BYTES;
;     const LAS unsigned char* Re = R + (4 * hi) * G3_PITCH + r * 2;
;     const bf16* qgp = (const bf16*)(c.ws + O_QG) + (row0 + r) * 256 + h * 64 + 8 * hi;
;     const float* sp = (const float*)(c.ws + O_UPD) + (size_t)unit * 8192;
;     const float* gn = c.a->in[I_GNORM] + (size_t)layer * 128;
;     bf16x8 qf[4];
; #pragma unroll
;     for (int s = 0; s < 4; ++s) qf[s] = *(const bf16x8*)(qgp + 16 * s);
;     f32x16 o[4];
; #pragma unroll
;     for (int vb = 0; vb < 4; ++vb) {
;         o[vb] = f32x16{};
; #pragma unroll
;         for (int s = 0; s < 4; ++s) { const float* s0 = sp + (size_t)(16 * s + 8 * hi) * 128 + 32 * vb + r;
;             const bf16x8 bfv = pack8(s0[0], s0[128], s0[256], s0[384], s0[512], s0[640], s0[768], s0[896]);
;             o[vb] = MFMA32(qf[s], bfv, o[vb]); }
;         asm volatile("" ::: "memory");
;     }
.LBB0_604:
	s_mov_b64 s[2:3], s[84:85]
	s_mov_b64 s[0:1], s[86:87]
	s_ashr_i32 s2, s35, 8
	s_ashr_i32 s3, s2, 31
	s_lshl_b64 s[2:3], s[2:3], 12
	s_and_b32 s5, s8, 0xfc0
	s_or_b32 s2, s2, s5
	s_or_b64 s[2:3], s[2:3], s[6:7]
	v_mov_b32_e32 v3, s3
	v_or_b32_e32 v2, s2, v152
	s_bfe_u32 s4, s35, 0x20006
	v_lshlrev_b64 v[2:3], 9, v[2:3]
	v_lshl_add_u64 v[2:3], s[0:1], 0, v[2:3]
	s_lshl_b32 s10, s4, 7
	v_lshl_add_u64 v[2:3], v[2:3], 0, s[10:11]
	v_lshl_add_u64 v[2:3], v[2:3], 0, v[86:87]
	v_lshl_add_u64 v[4:5], v[2:3], 0, s[16:17]
	v_add_co_u32_e32 v2, vcc, s13, v2
	v_lshl_add_u64 v[90:91], s[0:1], 0, v[84:85]
	s_nop 0
	v_addc_co_u32_e32 v3, vcc, 0, v3, vcc
	global_load_dwordx4 v[50:53], v[2:3], off
	global_load_dwordx4 v[110:113], v[4:5], off offset:96
	global_load_dwordx4 v[106:109], v[4:5], off offset:64
	global_load_dwordx4 v[102:105], v[4:5], off offset:32
	v_add_co_u32_e32 v2, vcc, s24, v90
	s_lshl_b64 s[2:3], s[2:3], 10
	s_nop 0
	v_addc_co_u32_e32 v3, vcc, -1, v91, vcc
	v_add_co_u32_e32 v58, vcc, s28, v90
	global_load_dword v2, v[2:3], off
	s_nop 0
	v_addc_co_u32_e32 v59, vcc, -1, v91, vcc
	global_load_dword v3, v[58:59], off offset:384
	global_load_dword v4, v[58:59], off offset:896
	global_load_dword v5, v[58:59], off offset:1408
	global_load_dword v6, v[58:59], off offset:1920
	global_load_dword v7, v[58:59], off offset:2432
	global_load_dword v8, v[58:59], off offset:2944
	global_load_dword v9, v[58:59], off offset:3456
	v_add_co_u32_e32 v18, vcc, s25, v90
	s_lshl_b32 s4, s4, 8
	s_nop 0
	v_addc_co_u32_e32 v19, vcc, -1, v91, vcc
	v_add_co_u32_e32 v114, vcc, s29, v90
	global_load_dword v18, v[18:19], off
	s_nop 0
	v_addc_co_u32_e32 v115, vcc, -1, v91, vcc
	global_load_dword v19, v[114:115], off offset:384
	global_load_dword v20, v[114:115], off offset:896
	global_load_dword v21, v[114:115], off offset:1408
	global_load_dword v22, v[114:115], off offset:1920
	global_load_dword v23, v[114:115], off offset:2432
	global_load_dword v24, v[114:115], off offset:2944
	global_load_dword v25, v[114:115], off offset:3456
	s_add_u32 s0, s0, s2
	s_addc_u32 s1, s1, s3
	s_add_u32 s0, s0, s4
	s_addc_u32 s1, s1, 0
	s_add_i32 s35, s35, s12
	s_add_i32 s8, s8, s9
	v_lshl_add_u64 v[84:85], v[84:85], 0, s[14:15]
	s_cmpk_lt_i32 s35, 0x800
	v_add_co_u32_e32 v26, vcc, s26, v90
	s_nop 1
	v_addc_co_u32_e32 v27, vcc, -1, v91, vcc
	v_add_co_u32_e32 v118, vcc, s30, v90
	global_load_dword v26, v[26:27], off
	s_nop 0
	v_addc_co_u32_e32 v119, vcc, -1, v91, vcc
	global_load_dword v27, v[118:119], off offset:384
	global_load_dword v28, v[118:119], off offset:896
	global_load_dword v29, v[118:119], off offset:1408
	global_load_dword v30, v[118:119], off offset:1920
	global_load_dword v31, v[118:119], off offset:2432
	global_load_dword v32, v[118:119], off offset:2944
	global_load_dword v33, v[118:119], off offset:3456
	v_add_co_u32_e32 v42, vcc, s27, v90
	s_nop 1
	v_addc_co_u32_e32 v43, vcc, -1, v91, vcc
	v_add_co_u32_e32 v120, vcc, s31, v90
	global_load_dword v42, v[42:43], off
	s_nop 0
	v_addc_co_u32_e32 v121, vcc, -1, v91, vcc
	global_load_dword v43, v[120:121], off offset:384
	global_load_dword v44, v[120:121], off offset:896
	global_load_dword v45, v[120:121], off offset:1408
	global_load_dword v46, v[120:121], off offset:1920
	global_load_dword v47, v[120:121], off offset:2432
	global_load_dword v48, v[120:121], off offset:2944
	global_load_dword v49, v[120:121], off offset:3456
	s_waitcnt vmcnt(16) lgkmcnt(0)
	global_load_dword v41, v[114:115], off offset:3584
	global_load_dword v40, v[114:115], off offset:3072
	global_load_dword v39, v[114:115], off offset:2560
	global_load_dword v38, v[114:115], off offset:2048
	global_load_dword v37, v[114:115], off offset:1536
	global_load_dword v36, v[114:115], off offset:1024
	global_load_dword v35, v[114:115], off offset:512
	global_load_dword v34, v[114:115], off
	global_load_dword v145, v[58:59], off offset:3584
	global_load_dword v146, v[58:59], off offset:3072
	global_load_dword v143, v[58:59], off offset:2560
	global_load_dword v144, v[58:59], off offset:2048
	global_load_dword v141, v[58:59], off offset:1536
	global_load_dword v142, v[58:59], off offset:1024
	global_load_dword v139, v[58:59], off offset:512
	global_load_dword v140, v[58:59], off
	v_cvt_pk_bf16_f32 v2, v2, v3
	v_cvt_pk_bf16_f32 v3, v4, v5
	v_cvt_pk_bf16_f32 v4, v6, v7
	v_cvt_pk_bf16_f32 v5, v8, v9
	v_cvt_pk_bf16_f32 v18, v18, v19
	s_nop 0
	v_mfma_f32_32x32x16_bf16 v[2:17], v[50:53], v[2:5], 0
	v_cvt_pk_bf16_f32 v19, v20, v21
	v_cvt_pk_bf16_f32 v20, v22, v23
	v_cvt_pk_bf16_f32 v21, v24, v25
	s_nop 1
	v_mfma_f32_32x32x16_bf16 v[2:17], v[102:105], v[18:21], v[2:17]
	s_waitcnt vmcnt(24) lgkmcnt(0)
	global_load_dword v63, v[114:115], off offset:3712
	global_load_dword v62, v[114:115], off offset:3200
	global_load_dword v61, v[114:115], off offset:2688
	global_load_dword v60, v[114:115], off offset:2176
	global_load_dword v57, v[114:115], off offset:1664
	global_load_dword v56, v[114:115], off offset:1152
	global_load_dword v55, v[114:115], off offset:640
	global_load_dword v54, v[114:115], off offset:128
	global_load_dword v173, v[58:59], off offset:3712
	global_load_dword v176, v[58:59], off offset:3200
	global_load_dword v171, v[58:59], off offset:2688
	global_load_dword v174, v[58:59], off offset:2176
	global_load_dword v169, v[58:59], off offset:1664
	global_load_dword v172, v[58:59], off offset:1152
	global_load_dword v167, v[58:59], off offset:640
	global_load_dword v170, v[58:59], off offset:128
	global_load_dword v157, v[118:119], off offset:3584
	global_load_dword v160, v[118:119], off offset:3072
	global_load_dword v155, v[118:119], off offset:2560
	global_load_dword v158, v[118:119], off offset:2048
	global_load_dword v149, v[118:119], off offset:1536
	global_load_dword v156, v[118:119], off offset:1024
	global_load_dword v147, v[118:119], off offset:512
	global_load_dword v148, v[118:119], off
	v_cvt_pk_bf16_f32 v26, v26, v27
	v_cvt_pk_bf16_f32 v27, v28, v29
	v_cvt_pk_bf16_f32 v28, v30, v31
	v_cvt_pk_bf16_f32 v29, v32, v33
	s_nop 1
	v_mfma_f32_32x32x16_bf16 v[2:17], v[106:109], v[26:29], v[2:17]
	v_cmp_lt_i32_e32 vcc, v94, v95
	s_waitcnt vmcnt(20) lgkmcnt(0)
; #define MFMA32(a, b, c) __builtin_amdgcn_mfma_f32_32x32x16_bf16((a), (b), (c), 0, 0, 0)
; DI void gla_stage3(const Ctx& c0, int layer, int unit, int cb, LAS unsigned char* lds) {
;     ...
; #pragma unroll
;     for (int vb = 0; vb < 4; ++vb) {
;         o[vb] = f32x16{};
; #pragma unroll
;         for (int s = 0; s < 4; ++s) { const float* s0 = sp + (size_t)(16 * s + 8 * hi) * 128 + 32 * vb + r;
;             const bf16x8 bfv = pack8(s0[0], s0[128], s0[256], s0[384], s0[512], s0[640], s0[768], s0[896]);
;             o[vb] = MFMA32(qf[s], bfv, o[vb]); }
;         asm volatile("" ::: "memory");
;     }
;     ...
;     for (int vb = 0; vb < 4; ++vb) { const float g = gn[32 * vb + r];
	global_load_dword v127, v[114:115], off offset:3840
	global_load_dword v126, v[114:115], off offset:3328
	global_load_dword v125, v[114:115], off offset:2816
	global_load_dword v124, v[114:115], off offset:2304
	global_load_dword v123, v[114:115], off offset:1792
	global_load_dword v122, v[114:115], off offset:1280
	global_load_dword v117, v[114:115], off offset:768
	global_load_dword v116, v[114:115], off offset:256
	global_load_dword v214, v[58:59], off offset:3840
	global_load_dword v212, v[58:59], off offset:3328
	global_load_dword v205, v[58:59], off offset:2816
	global_load_dword v210, v[58:59], off offset:2304
	global_load_dword v203, v[58:59], off offset:1792
	global_load_dword v208, v[58:59], off offset:1280
	global_load_dword v201, v[58:59], off offset:768
	global_load_dword v206, v[58:59], off offset:256
	global_load_dword v199, v[120:121], off offset:3712
	global_load_dword v204, v[120:121], off offset:3200
	global_load_dword v197, v[120:121], off offset:2688
	global_load_dword v202, v[120:121], off offset:2176
	global_load_dword v195, v[120:121], off offset:1664
	global_load_dword v200, v[120:121], off offset:1152
	global_load_dword v183, v[120:121], off offset:640
	global_load_dword v198, v[120:121], off offset:128
	global_load_dword v181, v[118:119], off offset:3712
	global_load_dword v196, v[118:119], off offset:3200
	global_load_dword v179, v[118:119], off offset:2688
	global_load_dword v182, v[118:119], off offset:2176
	global_load_dword v177, v[118:119], off offset:1664
	global_load_dword v180, v[118:119], off offset:1152
	global_load_dword v175, v[118:119], off offset:640
	global_load_dword v178, v[118:119], off offset:128
	global_load_dword v165, v[120:121], off offset:3584
	global_load_dword v168, v[120:121], off offset:3072
	global_load_dword v163, v[120:121], off offset:2560
	global_load_dword v166, v[120:121], off offset:2048
	global_load_dword v161, v[120:121], off offset:1536
	global_load_dword v164, v[120:121], off offset:1024
	global_load_dword v159, v[120:121], off offset:512
	global_load_dword v162, v[120:121], off
	v_cvt_pk_bf16_f32 v42, v42, v43
	v_cvt_pk_bf16_f32 v43, v44, v45
	v_cvt_pk_bf16_f32 v44, v46, v47
	v_cvt_pk_bf16_f32 v45, v48, v49
	s_nop 1
	v_mfma_f32_32x32x16_bf16 v[2:17], v[110:113], v[42:45], v[2:17]
	s_waitcnt vmcnt(40) lgkmcnt(0)
	global_load_dword v238, v[82:83], off offset:384
	global_load_dword v236, v[82:83], off offset:256
	global_load_dword v234, v[82:83], off offset:128
	global_load_dword v232, v[82:83], off
	global_load_dword v90, v[90:91], off
	global_load_dword v230, v[120:121], off offset:3328
	global_load_dword v219, v[120:121], off offset:2816
	global_load_dword v228, v[120:121], off offset:2304
	global_load_dword v217, v[120:121], off offset:1792
	global_load_dword v226, v[120:121], off offset:1280
	global_load_dword v215, v[120:121], off offset:768
	global_load_dword v224, v[120:121], off offset:256
	global_load_dword v213, v[118:119], off offset:3840
	global_load_dword v222, v[118:119], off offset:3328
	global_load_dword v211, v[118:119], off offset:2816
	global_load_dword v220, v[118:119], off offset:2304
	global_load_dword v209, v[118:119], off offset:1792
	global_load_dword v218, v[118:119], off offset:1280
	global_load_dword v207, v[118:119], off offset:768
	global_load_dword v216, v[118:119], off offset:256
	v_cvt_pk_bf16_f32 v18, v140, v139
	v_cvt_pk_bf16_f32 v34, v34, v35
	v_cvt_pk_bf16_f32 v19, v142, v141
	v_cvt_pk_bf16_f32 v35, v36, v37
	v_cvt_pk_bf16_f32 v20, v144, v143
	v_cvt_pk_bf16_f32 v36, v38, v39
	v_cvt_pk_bf16_f32 v21, v146, v145
	v_cvt_pk_bf16_f32 v37, v40, v41
	s_nop 0
	v_mfma_f32_32x32x16_bf16 v[18:33], v[50:53], v[18:21], 0
	v_mfma_f32_32x32x16_bf16 v[18:33], v[102:105], v[34:37], v[18:33]
	s_waitcnt vmcnt(60) lgkmcnt(0)
	v_cvt_pk_bf16_f32 v34, v148, v147
	v_cvt_pk_bf16_f32 v35, v156, v149
	v_cvt_pk_bf16_f32 v36, v158, v155
	v_cvt_pk_bf16_f32 v37, v160, v157
	s_nop 1
	v_mfma_f32_32x32x16_bf16 v[18:33], v[106:109], v[34:37], v[18:33]
	s_waitcnt vmcnt(20) lgkmcnt(0)
	v_cvt_pk_bf16_f32 v34, v162, v159
	v_cvt_pk_bf16_f32 v35, v164, v161
	v_cvt_pk_bf16_f32 v36, v166, v163
	v_cvt_pk_bf16_f32 v37, v168, v165
	s_nop 1
	v_mfma_f32_32x32x16_bf16 v[18:33], v[110:113], v[34:37], v[18:33]
	s_waitcnt vmcnt(62) lgkmcnt(0)
	v_cvt_pk_bf16_f32 v34, v170, v167
	v_cvt_pk_bf16_f32 v54, v54, v55
	v_cvt_pk_bf16_f32 v35, v172, v169
	v_cvt_pk_bf16_f32 v55, v56, v57
	v_cvt_pk_bf16_f32 v36, v174, v171
	v_cvt_pk_bf16_f32 v56, v60, v61
	v_cvt_pk_bf16_f32 v37, v176, v173
	v_cvt_pk_bf16_f32 v57, v62, v63
	s_nop 0
	v_mfma_f32_32x32x16_bf16 v[34:49], v[50:53], v[34:37], 0
	v_mfma_f32_32x32x16_bf16 v[34:49], v[102:105], v[54:57], v[34:49]
	s_waitcnt vmcnt(28) lgkmcnt(0)
	v_cvt_pk_bf16_f32 v54, v178, v175
	v_cvt_pk_bf16_f32 v55, v180, v177
	v_cvt_pk_bf16_f32 v56, v182, v179
	v_cvt_pk_bf16_f32 v57, v196, v181
	s_nop 1
	v_mfma_f32_32x32x16_bf16 v[34:49], v[106:109], v[54:57], v[34:49]
	s_waitcnt vmcnt(36) lgkmcnt(0)
	v_cvt_pk_bf16_f32 v54, v198, v183
	v_cvt_pk_bf16_f32 v55, v200, v195
	v_cvt_pk_bf16_f32 v56, v202, v197
	v_cvt_pk_bf16_f32 v57, v204, v199
	s_nop 1
	v_mfma_f32_32x32x16_bf16 v[34:49], v[110:113], v[54:57], v[34:49]
	s_nop 0
	s_nop 0
	s_waitcnt vmcnt(44) lgkmcnt(0)
	v_cvt_pk_bf16_f32 v54, v206, v201
	v_cvt_pk_bf16_f32 v114, v116, v117
	v_cvt_pk_bf16_f32 v55, v208, v203
	v_cvt_pk_bf16_f32 v115, v122, v123
	v_cvt_pk_bf16_f32 v56, v210, v205
	v_cvt_pk_bf16_f32 v116, v124, v125
	v_cvt_pk_bf16_f32 v57, v212, v214
	v_cvt_pk_bf16_f32 v117, v126, v127
	s_nop 0
	v_mfma_f32_32x32x16_bf16 v[50:65], v[50:53], v[54:57], 0
	v_mfma_f32_32x32x16_bf16 v[50:65], v[102:105], v[114:117], v[50:65]
	s_waitcnt vmcnt(0) lgkmcnt(0)
; #define LAS __attribute__((address_space(3)))
; #define LDS_WAIT() asm volatile("s_waitcnt lgkmcnt(0)" ::: "memory")
; DI float bf2f(bf16 b) { return __uint_as_float(((unsigned)b) << 16); }
; DI void g3_tile_in(const bf16* g, LAS unsigned char* R, int lane) {
; #pragma unroll
;     for (int it = 0; it < 8; ++it) { const int row = 4 * it + (lane >> 4), ch = lane & 15;
;         *(LAS u32x4*)(R + row * G3_PITCH + ch * 16) = *(const u32x4*)(g + (size_t)row * 512 + ch * 8); }
;     LDS_WAIT();
; DI void gla_stage3(const Ctx& c0, int layer, int unit, int cb, LAS unsigned char* lds) {
;     ...
;     g3_tile_in((const bf16*)(c.ws + O_OINTRA) + row0 * 512 + h * 128, R, lane);
; #pragma unroll
;     for (int vb = 0; vb < 4; ++vb) {
; #pragma unroll
;         for (int rg = 0; rg < 16; ++rg) o[vb][rg] += bf2f(*(const LAS bf16*)(Re + ((rg & 3) + 8 * (rg >> 2)) * G3_PITCH + 64 * vb));
;         asm volatile("" ::: "memory");
;     }
;     ...
;     g3_tile_in((const bf16*)(c.ws + O_GR) + row0 * 512 + h * 128, R, lane);
	v_cvt_pk_bf16_f32 v102, v216, v207
	v_cvt_pk_bf16_f32 v103, v218, v209
	v_cvt_pk_bf16_f32 v104, v220, v211
	v_cvt_pk_bf16_f32 v105, v222, v213
	s_nop 1
	v_mfma_f32_32x32x16_bf16 v[50:65], v[106:109], v[102:105], v[50:65]
	s_nop 0
	s_waitcnt vmcnt(8) lgkmcnt(0)
	v_cvt_pk_bf16_f32 v102, v224, v215
	v_cvt_pk_bf16_f32 v103, v226, v217
	v_cvt_pk_bf16_f32 v104, v228, v219
	v_cvt_pk_bf16_f32 v105, v230, v90
	v_lshl_add_u64 v[90:91], s[0:1], 0, v[88:89]
	v_lshl_add_u64 v[106:107], v[90:91], 0, s[18:19]
	v_mfma_f32_32x32x16_bf16 v[50:65], v[110:113], v[102:105], v[50:65]
	v_lshl_add_u64 v[102:103], v[106:107], 0, v[66:67]
	global_load_dwordx4 v[102:105], v[102:103], off
	s_waitcnt vmcnt(0) lgkmcnt(0)
	v_lshl_add_u64 v[168:169], v[90:91], 0, s[20:21]
	v_lshl_add_u64 v[140:141], v[168:169], 0, v[70:71]
	global_load_dwordx4 v[174:177], v[140:141], off
	v_lshl_add_u64 v[140:141], v[106:107], 0, v[70:71]
	global_load_dwordx4 v[146:149], v[140:141], off
	v_lshl_add_u64 v[144:145], v[106:107], 0, v[68:69]
	global_load_dwordx4 v[140:143], v[144:145], off
	ds_write_b128 v92, v[102:105]
	s_waitcnt vmcnt(0) lgkmcnt(0)
	v_lshl_add_u64 v[144:145], v[168:169], 0, v[76:77]
	global_load_dwordx4 v[200:203], v[144:145], off
	v_lshl_add_u64 v[144:145], v[168:169], 0, v[74:75]
	global_load_dwordx4 v[196:199], v[144:145], off
	v_lshl_add_u64 v[144:145], v[168:169], 0, v[72:73]
	global_load_dwordx4 v[178:181], v[144:145], off
	v_lshl_add_u64 v[144:145], v[106:107], 0, v[74:75]
	global_load_dwordx4 v[156:159], v[144:145], off
	v_lshl_add_u64 v[102:103], v[106:107], 0, v[72:73]
	global_load_dwordx4 v[102:105], v[102:103], off
	ds_write_b128 v92, v[140:143] offset:1088
	s_waitcnt vmcnt(5) lgkmcnt(0)
	v_lshl_add_u64 v[140:141], v[168:169], 0, v[78:79]
	global_load_dwordx4 v[204:207], v[140:141], off
	v_lshl_add_u64 v[140:141], v[106:107], 0, v[78:79]
	global_load_dwordx4 v[160:163], v[140:141], off
	v_lshl_add_u64 v[144:145], v[106:107], 0, v[76:77]
	global_load_dwordx4 v[140:143], v[144:145], off
	ds_write_b128 v92, v[146:149] offset:2176
	s_waitcnt vmcnt(3) lgkmcnt(0)
	v_lshl_add_u64 v[144:145], v[168:169], 0, v[66:67]
	global_load_dwordx4 v[164:167], v[144:145], off
	v_lshl_add_u64 v[148:149], v[106:107], 0, v[80:81]
	global_load_dwordx4 v[144:147], v[148:149], off
	ds_write_b128 v92, v[102:105] offset:3264
	s_waitcnt vmcnt(6) lgkmcnt(0)
	v_lshl_add_u64 v[148:149], v[168:169], 0, v[68:69]
	global_load_dwordx4 v[170:173], v[148:149], off
	ds_write_b128 v92, v[156:159] offset:4352
	s_waitcnt vmcnt(3) lgkmcnt(0)
	ds_write_b128 v92, v[140:143] offset:5440
	s_waitcnt vmcnt(4) lgkmcnt(0)
	ds_write_b128 v92, v[160:163] offset:6528
	s_waitcnt vmcnt(1) lgkmcnt(0)
	ds_write_b128 v92, v[144:147] offset:7616
	s_waitcnt lgkmcnt(0)
	ds_read_u16 v138, v1
	ds_read_u16 v137, v1 offset:272
	ds_read_u16 v136, v1 offset:544
	ds_read_u16 v135, v1 offset:816
	ds_read_u16 v134, v1 offset:2176
	ds_read_u16 v133, v1 offset:2448
	ds_read_u16 v132, v1 offset:2720
	ds_read_u16 v131, v1 offset:2992
	s_waitcnt lgkmcnt(0)
	v_lshlrev_b32_e32 v138, 16, v138
	v_add_f32_e32 v138, v2, v138
	v_lshlrev_b32_e32 v137, 16, v137
	v_add_f32_e32 v137, v3, v137
	v_lshlrev_b32_e32 v136, 16, v136
	v_add_f32_e32 v136, v4, v136
	v_lshlrev_b32_e32 v135, 16, v135
	v_add_f32_e32 v135, v5, v135
	v_lshlrev_b32_e32 v134, 16, v134
	v_add_f32_e32 v134, v6, v134
	v_lshlrev_b32_e32 v133, 16, v133
	v_add_f32_e32 v133, v7, v133
	v_lshlrev_b32_e32 v132, 16, v132
	v_add_f32_e32 v132, v8, v132
	v_lshlrev_b32_e32 v131, 16, v131
	v_add_f32_e32 v131, v9, v131
	ds_read_u16 v130, v1 offset:4352
	ds_read_u16 v129, v1 offset:4624
	ds_read_u16 v128, v1 offset:4896
	ds_read_u16 v127, v1 offset:5168
	ds_read_u16 v126, v1 offset:6528
	ds_read_u16 v125, v1 offset:6800
	ds_read_u16 v124, v1 offset:7072
	s_waitcnt lgkmcnt(0)
	v_lshlrev_b32_e32 v130, 16, v130
	v_add_f32_e32 v130, v10, v130
	v_lshlrev_b32_e32 v129, 16, v129
	v_add_f32_e32 v129, v11, v129
	v_lshlrev_b32_e32 v128, 16, v128
	v_add_f32_e32 v128, v12, v128
	v_lshlrev_b32_e32 v127, 16, v127
	v_add_f32_e32 v127, v13, v127
	v_lshlrev_b32_e32 v126, 16, v126
	v_add_f32_e32 v126, v14, v126
	v_lshlrev_b32_e32 v125, 16, v125
	v_add_f32_e32 v125, v15, v125
	v_lshlrev_b32_e32 v124, 16, v124
	v_add_f32_e32 v124, v16, v124
	ds_read_u16 v2, v1 offset:7344
	s_waitcnt lgkmcnt(0)
	v_lshlrev_b32_e32 v2, 16, v2
	v_add_f32_e32 v123, v17, v2
	ds_read_u16 v122, v1 offset:64
	ds_read_u16 v121, v1 offset:336
	ds_read_u16 v120, v1 offset:608
	ds_read_u16 v119, v1 offset:880
	ds_read_u16 v118, v1 offset:2240
	ds_read_u16 v117, v1 offset:2512
	ds_read_u16 v116, v1 offset:2784
	ds_read_u16 v115, v1 offset:3056
	s_waitcnt lgkmcnt(0)
	v_lshlrev_b32_e32 v122, 16, v122
	v_add_f32_e32 v122, v18, v122
	v_lshlrev_b32_e32 v121, 16, v121
	v_add_f32_e32 v121, v19, v121
	v_lshlrev_b32_e32 v120, 16, v120
	v_add_f32_e32 v120, v20, v120
	v_lshlrev_b32_e32 v119, 16, v119
	v_add_f32_e32 v119, v21, v119
	v_lshlrev_b32_e32 v118, 16, v118
	v_add_f32_e32 v118, v22, v118
	v_lshlrev_b32_e32 v117, 16, v117
	v_add_f32_e32 v117, v23, v117
	v_lshlrev_b32_e32 v116, 16, v116
	v_add_f32_e32 v116, v24, v116
	v_lshlrev_b32_e32 v115, 16, v115
	v_add_f32_e32 v115, v25, v115
	ds_read_u16 v114, v1 offset:4416
	ds_read_u16 v113, v1 offset:4688
	ds_read_u16 v112, v1 offset:4960
	ds_read_u16 v111, v1 offset:5232
	ds_read_u16 v110, v1 offset:6592
	ds_read_u16 v109, v1 offset:6864
	ds_read_u16 v108, v1 offset:7136
	s_waitcnt lgkmcnt(0)
; #define LAS __attribute__((address_space(3)))
; DI float bf2f(bf16 b) { return __uint_as_float(((unsigned)b) << 16); }
; DI void gla_stage3(const Ctx& c0, int layer, int unit, int cb, LAS unsigned char* lds) {
;     ...
; #pragma unroll
;     for (int vb = 0; vb < 4; ++vb) {
; #pragma unroll
;         for (int rg = 0; rg < 16; ++rg) o[vb][rg] += bf2f(*(const LAS bf16*)(Re + ((rg & 3) + 8 * (rg >> 2)) * G3_PITCH + 64 * vb));
;         asm volatile("" ::: "memory");
;     }
;     float rs[16];
; #pragma unroll
;     for (int rg = 0; rg < 16; ++rg) { float ss = o[0][rg] * o[0][rg] + o[1][rg] * o[1][rg] + o[2][rg] * o[2][rg] + o[3][rg] * o[3][rg];
;         ss += __shfl_xor(ss, 1); ss += __shfl_xor(ss, 2); ss += __shfl_xor(ss, 4); ss += __shfl_xor(ss, 8); ss += __shfl_xor(ss, 16);
;         rs[rg] = 1.f / sqrtf(ss * (1.f / 128.f) + EPS); }
	v_lshlrev_b32_e32 v114, 16, v114
	v_add_f32_e32 v114, v26, v114
	v_lshlrev_b32_e32 v113, 16, v113
	v_add_f32_e32 v113, v27, v113
	v_lshlrev_b32_e32 v112, 16, v112
	v_add_f32_e32 v112, v28, v112
	v_lshlrev_b32_e32 v111, 16, v111
	v_add_f32_e32 v111, v29, v111
	v_lshlrev_b32_e32 v110, 16, v110
	v_add_f32_e32 v110, v30, v110
	v_lshlrev_b32_e32 v109, 16, v109
	v_add_f32_e32 v109, v31, v109
	v_lshlrev_b32_e32 v108, 16, v108
	v_add_f32_e32 v108, v32, v108
	ds_read_u16 v2, v1 offset:7408
	s_waitcnt lgkmcnt(0)
	v_lshlrev_b32_e32 v2, 16, v2
	v_add_f32_e32 v107, v33, v2
	ds_read_u16 v2, v1 offset:128
	s_waitcnt lgkmcnt(0)
	v_lshlrev_b32_e32 v2, 16, v2
	v_add_f32_e32 v106, v34, v2
	ds_read_u16 v2, v1 offset:400
	s_waitcnt lgkmcnt(0)
	v_lshlrev_b32_e32 v2, 16, v2
	v_add_f32_e32 v105, v35, v2
	ds_read_u16 v2, v1 offset:672
	s_waitcnt lgkmcnt(0)
	v_lshlrev_b32_e32 v2, 16, v2
	v_add_f32_e32 v104, v36, v2
	ds_read_u16 v2, v1 offset:944
	s_waitcnt lgkmcnt(0)
	v_lshlrev_b32_e32 v2, 16, v2
	v_add_f32_e32 v103, v37, v2
	ds_read_u16 v2, v1 offset:2304
	s_waitcnt lgkmcnt(0)
	v_lshlrev_b32_e32 v2, 16, v2
	v_add_f32_e32 v102, v38, v2
	ds_read_u16 v2, v1 offset:2576
	s_waitcnt lgkmcnt(0)
	v_lshlrev_b32_e32 v2, 16, v2
	v_add_f32_e32 v39, v39, v2
	ds_read_u16 v2, v1 offset:2848
	s_waitcnt lgkmcnt(0)
	v_lshlrev_b32_e32 v2, 16, v2
	v_add_f32_e32 v38, v40, v2
	ds_read_u16 v2, v1 offset:3120
	s_waitcnt lgkmcnt(0)
	v_lshlrev_b32_e32 v2, 16, v2
	v_add_f32_e32 v37, v41, v2
	ds_read_u16 v36, v1 offset:4480
	ds_read_u16 v34, v1 offset:4752
	ds_read_u16 v33, v1 offset:5024
	ds_read_u16 v32, v1 offset:5296
	ds_read_u16 v30, v1 offset:6656
	ds_read_u16 v29, v1 offset:6928
	ds_read_u16 v28, v1 offset:7200
	s_waitcnt lgkmcnt(0)
	v_lshlrev_b32_e32 v36, 16, v36
	v_add_f32_e32 v36, v42, v36
	v_lshlrev_b32_e32 v34, 16, v34
	v_add_f32_e32 v34, v43, v34
	v_lshlrev_b32_e32 v33, 16, v33
	v_add_f32_e32 v33, v44, v33
	v_lshlrev_b32_e32 v32, 16, v32
	v_add_f32_e32 v32, v45, v32
	v_lshlrev_b32_e32 v30, 16, v30
	v_add_f32_e32 v30, v46, v30
	v_lshlrev_b32_e32 v29, 16, v29
	v_add_f32_e32 v29, v47, v29
	v_lshlrev_b32_e32 v28, 16, v28
	v_add_f32_e32 v28, v48, v28
	ds_read_u16 v2, v1 offset:7472
	s_waitcnt lgkmcnt(0)
	v_lshlrev_b32_e32 v2, 16, v2
	v_add_f32_e32 v26, v49, v2
	ds_read_u16 v19, v1 offset:192
	ds_read_u16 v18, v1 offset:464
	ds_read_u16 v17, v1 offset:736
	ds_read_u16 v16, v1 offset:1008
	ds_read_u16 v15, v1 offset:2368
	ds_read_u16 v14, v1 offset:2640
	ds_read_u16 v13, v1 offset:2912
	ds_read_u16 v12, v1 offset:3184
	s_waitcnt lgkmcnt(0)
	v_lshlrev_b32_e32 v19, 16, v19
	v_add_f32_e32 v19, v50, v19
	v_lshlrev_b32_e32 v18, 16, v18
	v_add_f32_e32 v18, v51, v18
	v_lshlrev_b32_e32 v17, 16, v17
	v_add_f32_e32 v17, v52, v17
	v_lshlrev_b32_e32 v16, 16, v16
	v_add_f32_e32 v16, v53, v16
	v_lshlrev_b32_e32 v15, 16, v15
	v_add_f32_e32 v15, v54, v15
	v_lshlrev_b32_e32 v14, 16, v14
	v_add_f32_e32 v14, v55, v14
	v_lshlrev_b32_e32 v13, 16, v13
	v_add_f32_e32 v13, v56, v13
	v_lshlrev_b32_e32 v12, 16, v12
	v_add_f32_e32 v12, v57, v12
	ds_read_u16 v11, v1 offset:4544
	ds_read_u16 v10, v1 offset:4816
	ds_read_u16 v9, v1 offset:5088
	ds_read_u16 v8, v1 offset:5360
	ds_read_u16 v7, v1 offset:6720
	ds_read_u16 v6, v1 offset:6992
	ds_read_u16 v5, v1 offset:7264
	s_waitcnt lgkmcnt(0)
	v_lshlrev_b32_e32 v11, 16, v11
	v_add_f32_e32 v11, v58, v11
	v_lshlrev_b32_e32 v10, 16, v10
	v_add_f32_e32 v10, v59, v10
	v_lshlrev_b32_e32 v9, 16, v9
	v_add_f32_e32 v9, v60, v9
	v_lshlrev_b32_e32 v8, 16, v8
	v_add_f32_e32 v8, v61, v8
	v_lshlrev_b32_e32 v7, 16, v7
	v_add_f32_e32 v7, v62, v7
	v_lshlrev_b32_e32 v6, 16, v6
	v_add_f32_e32 v6, v63, v6
	v_lshlrev_b32_e32 v5, 16, v5
	v_add_f32_e32 v5, v64, v5
	ds_read_u16 v2, v1 offset:7536
	s_waitcnt lgkmcnt(0)
	s_waitcnt lgkmcnt(0)
	v_lshlrev_b32_e32 v2, 16, v2
	v_add_f32_e32 v4, v65, v2
	v_cndmask_b32_e32 v2, v93, v94, vcc
	v_cmp_lt_i32_e32 vcc, v96, v95
	v_lshlrev_b32_e32 v2, 2, v2
	s_nop 0
	v_cndmask_b32_e32 v3, v93, v96, vcc
	v_cmp_lt_i32_e32 vcc, v97, v95
	v_lshlrev_b32_e32 v3, 2, v3
	s_nop 0
	v_cndmask_b32_e32 v20, v93, v97, vcc
	v_cmp_lt_i32_e32 vcc, v98, v95
	v_lshlrev_b32_e32 v20, 2, v20
	s_nop 0
	v_cndmask_b32_e32 v21, v93, v98, vcc
	v_cmp_lt_i32_e32 vcc, v99, v95
	v_lshlrev_b32_e32 v47, 2, v21
	s_nop 0
	v_cndmask_b32_e32 v21, v93, v99, vcc
	v_lshlrev_b32_e32 v48, 2, v21
	v_mul_f32_e32 v21, v122, v122
	v_fmac_f32_e32 v21, v138, v138
	v_fmac_f32_e32 v21, v106, v106
	v_fmac_f32_e32 v21, v19, v19
	s_nop 1
	v_add_f32_dpp v21, v21, v21 quad_perm:[1,0,3,2] row_mask:0xf bank_mask:0xf
	s_nop 1
	v_add_f32_dpp v21, v21, v21 quad_perm:[2,3,0,1] row_mask:0xf bank_mask:0xf
	s_nop 1
	v_add_f32_dpp v21, v21, v21 row_half_mirror row_mask:0xf bank_mask:0xf
	s_nop 1
	v_add_f32_dpp v21, v21, v21 row_mirror row_mask:0xf bank_mask:0xf
	v_mov_b32_e32 v22, v21
	v_mov_b32_e32 v23, v21
	s_nop 1
	v_permlane16_swap_b32_e32 v22, v23
	v_add_f32_e32 v21, v22, v23
	v_fmamk_f32 v21, v21, 0x3c000000, v100
	v_cmp_gt_f32_e32 vcc, s34, v21
	v_mul_f32_e32 v22, 0x4f800000, v21
	s_nop 0
	v_cndmask_b32_e32 v21, v21, v22, vcc
	v_sqrt_f32_e32 v22, v21
	s_nop 0
	v_add_u32_e32 v23, -1, v22
	v_fma_f32 v24, -v23, v22, v21
	v_cmp_ge_f32_e64 s[4:5], 0, v24
	v_add_u32_e32 v24, 1, v22
	s_nop 0
	v_cndmask_b32_e64 v23, v22, v23, s[4:5]
	v_fma_f32 v22, -v24, v22, v21
	v_cmp_lt_f32_e64 s[4:5], 0, v22
	s_nop 1
	v_cndmask_b32_e64 v22, v23, v24, s[4:5]
	v_mul_f32_e32 v23, 0x37800000, v22
	v_cndmask_b32_e32 v22, v22, v23, vcc
	v_cmp_class_f32_e32 vcc, v21, v101
	s_nop 1
	v_cndmask_b32_e32 v21, v22, v21, vcc
	s_nop 0
	v_div_scale_f32 v24, vcc, 1.0, v21, 1.0
	v_rcp_f32_e32 v46, v21
	v_mul_f32_e32 v21, v121, v121
; DI void gla_stage3(const Ctx& c0, int layer, int unit, int cb, LAS unsigned char* lds) {
;     ...
;     float rs[16];
; #pragma unroll
;     for (int rg = 0; rg < 16; ++rg) { float ss = o[0][rg] * o[0][rg] + o[1][rg] * o[1][rg] + o[2][rg] * o[2][rg] + o[3][rg] * o[3][rg];
;         ss += __shfl_xor(ss, 1); ss += __shfl_xor(ss, 2); ss += __shfl_xor(ss, 4); ss += __shfl_xor(ss, 8); ss += __shfl_xor(ss, 16);
;         rs[rg] = 1.f / sqrtf(ss * (1.f / 128.f) + EPS); }
	v_fmac_f32_e32 v21, v137, v137
	v_fmac_f32_e32 v21, v105, v105
	v_fmac_f32_e32 v21, v18, v18
	s_nop 1
	v_add_f32_dpp v21, v21, v21 quad_perm:[1,0,3,2] row_mask:0xf bank_mask:0xf
	v_mul_f32_e32 v19, v19, v46
	s_nop 1
	v_add_f32_dpp v21, v21, v21 quad_perm:[2,3,0,1] row_mask:0xf bank_mask:0xf
	s_nop 1
	v_add_f32_dpp v21, v21, v21 row_half_mirror row_mask:0xf bank_mask:0xf
	s_nop 1
	v_add_f32_dpp v21, v21, v21 row_mirror row_mask:0xf bank_mask:0xf
	v_mov_b32_e32 v22, v21
	v_mov_b32_e32 v23, v21
	s_nop 1
	v_permlane16_swap_b32_e32 v22, v23
	v_add_f32_e32 v21, v22, v23
	v_fmamk_f32 v21, v21, 0x3c000000, v100
	v_cmp_gt_f32_e32 vcc, s34, v21
	v_mul_f32_e32 v22, 0x4f800000, v21
	s_nop 0
	v_cndmask_b32_e32 v21, v21, v22, vcc
	v_sqrt_f32_e32 v22, v21
	s_nop 0
	v_add_u32_e32 v23, -1, v22
	v_fma_f32 v24, -v23, v22, v21
	v_cmp_ge_f32_e64 s[4:5], 0, v24
	v_add_u32_e32 v24, 1, v22
	s_nop 0
	v_cndmask_b32_e64 v23, v22, v23, s[4:5]
	v_fma_f32 v22, -v24, v22, v21
	v_cmp_lt_f32_e64 s[4:5], 0, v22
	s_nop 1
	v_cndmask_b32_e64 v22, v23, v24, s[4:5]
	v_mul_f32_e32 v23, 0x37800000, v22
	v_cndmask_b32_e32 v22, v22, v23, vcc
	v_cmp_class_f32_e32 vcc, v21, v101
	s_nop 1
	v_cndmask_b32_e32 v21, v22, v21, vcc
	s_nop 0
	v_div_scale_f32 v24, vcc, 1.0, v21, 1.0
	v_rcp_f32_e32 v45, v21
	v_mul_f32_e32 v21, v120, v120
	v_fmac_f32_e32 v21, v136, v136
	v_fmac_f32_e32 v21, v104, v104
	v_fmac_f32_e32 v21, v17, v17
	s_nop 1
	v_add_f32_dpp v21, v21, v21 quad_perm:[1,0,3,2] row_mask:0xf bank_mask:0xf
	v_mul_f32_e32 v18, v18, v45
	s_nop 1
	v_add_f32_dpp v21, v21, v21 quad_perm:[2,3,0,1] row_mask:0xf bank_mask:0xf
	s_nop 1
	v_add_f32_dpp v21, v21, v21 row_half_mirror row_mask:0xf bank_mask:0xf
	s_nop 1
	v_add_f32_dpp v21, v21, v21 row_mirror row_mask:0xf bank_mask:0xf
	v_mov_b32_e32 v22, v21
	v_mov_b32_e32 v23, v21
	s_nop 1
	v_permlane16_swap_b32_e32 v22, v23
	v_add_f32_e32 v21, v22, v23
	v_fmamk_f32 v21, v21, 0x3c000000, v100
	v_cmp_gt_f32_e32 vcc, s34, v21
	v_mul_f32_e32 v22, 0x4f800000, v21
	s_nop 0
	v_cndmask_b32_e32 v21, v21, v22, vcc
	v_sqrt_f32_e32 v22, v21
	s_nop 0
	v_add_u32_e32 v23, -1, v22
	v_fma_f32 v24, -v23, v22, v21
	v_cmp_ge_f32_e64 s[4:5], 0, v24
	v_add_u32_e32 v24, 1, v22
	s_nop 0
	v_cndmask_b32_e64 v23, v22, v23, s[4:5]
	v_fma_f32 v22, -v24, v22, v21
	v_cmp_lt_f32_e64 s[4:5], 0, v22
	s_nop 1
	v_cndmask_b32_e64 v22, v23, v24, s[4:5]
	v_mul_f32_e32 v23, 0x37800000, v22
	v_cndmask_b32_e32 v22, v22, v23, vcc
	v_cmp_class_f32_e32 vcc, v21, v101
	s_nop 1
	v_cndmask_b32_e32 v21, v22, v21, vcc
	s_nop 0
	v_div_scale_f32 v24, vcc, 1.0, v21, 1.0
	v_rcp_f32_e32 v44, v21
	v_mul_f32_e32 v21, v119, v119
	v_fmac_f32_e32 v21, v135, v135
	v_fmac_f32_e32 v21, v103, v103
	v_fmac_f32_e32 v21, v16, v16
	s_nop 1
	v_add_f32_dpp v21, v21, v21 quad_perm:[1,0,3,2] row_mask:0xf bank_mask:0xf
	v_mul_f32_e32 v17, v17, v44
	s_nop 1
	v_add_f32_dpp v21, v21, v21 quad_perm:[2,3,0,1] row_mask:0xf bank_mask:0xf
	s_nop 1
	v_add_f32_dpp v21, v21, v21 row_half_mirror row_mask:0xf bank_mask:0xf
	s_nop 1
	v_add_f32_dpp v21, v21, v21 row_mirror row_mask:0xf bank_mask:0xf
	v_mov_b32_e32 v22, v21
	v_mov_b32_e32 v23, v21
	s_nop 1
	v_permlane16_swap_b32_e32 v22, v23
	v_add_f32_e32 v21, v22, v23
	v_fmamk_f32 v21, v21, 0x3c000000, v100
	v_cmp_gt_f32_e32 vcc, s34, v21
	v_mul_f32_e32 v22, 0x4f800000, v21
	s_nop 0
	v_cndmask_b32_e32 v21, v21, v22, vcc
	v_sqrt_f32_e32 v22, v21
	s_nop 0
	v_add_u32_e32 v23, -1, v22
	v_fma_f32 v24, -v23, v22, v21
	v_cmp_ge_f32_e64 s[4:5], 0, v24
	v_add_u32_e32 v24, 1, v22
	s_nop 0
	v_cndmask_b32_e64 v23, v22, v23, s[4:5]
	v_fma_f32 v22, -v24, v22, v21
	v_cmp_lt_f32_e64 s[4:5], 0, v22
	s_nop 1
	v_cndmask_b32_e64 v22, v23, v24, s[4:5]
	v_mul_f32_e32 v23, 0x37800000, v22
	v_cndmask_b32_e32 v22, v22, v23, vcc
	v_cmp_class_f32_e32 vcc, v21, v101
	s_nop 1
	v_cndmask_b32_e32 v21, v22, v21, vcc
	s_nop 0
	v_div_scale_f32 v24, vcc, 1.0, v21, 1.0
	v_rcp_f32_e32 v43, v21
	v_mul_f32_e32 v21, v118, v118
	v_fmac_f32_e32 v21, v134, v134
	v_fmac_f32_e32 v21, v102, v102
	v_fmac_f32_e32 v21, v15, v15
	s_nop 1
	v_add_f32_dpp v21, v21, v21 quad_perm:[1,0,3,2] row_mask:0xf bank_mask:0xf
	v_mul_f32_e32 v16, v16, v43
	s_nop 1
	v_add_f32_dpp v21, v21, v21 quad_perm:[2,3,0,1] row_mask:0xf bank_mask:0xf
	s_nop 1
	v_add_f32_dpp v21, v21, v21 row_half_mirror row_mask:0xf bank_mask:0xf
	s_nop 1
	v_add_f32_dpp v21, v21, v21 row_mirror row_mask:0xf bank_mask:0xf
	v_mov_b32_e32 v22, v21
	v_mov_b32_e32 v23, v21
	s_nop 1
	v_permlane16_swap_b32_e32 v22, v23
	v_add_f32_e32 v21, v22, v23
	v_fmamk_f32 v21, v21, 0x3c000000, v100
	v_cmp_gt_f32_e32 vcc, s34, v21
	v_mul_f32_e32 v22, 0x4f800000, v21
	s_nop 0
	v_cndmask_b32_e32 v21, v21, v22, vcc
	v_sqrt_f32_e32 v22, v21
	s_nop 0
	v_add_u32_e32 v23, -1, v22
	v_fma_f32 v24, -v23, v22, v21
	v_cmp_ge_f32_e64 s[4:5], 0, v24
	v_add_u32_e32 v24, 1, v22
	s_nop 0
	v_cndmask_b32_e64 v23, v22, v23, s[4:5]
	v_fma_f32 v22, -v24, v22, v21
	v_cmp_lt_f32_e64 s[4:5], 0, v22
	s_nop 1
	v_cndmask_b32_e64 v22, v23, v24, s[4:5]
	v_mul_f32_e32 v23, 0x37800000, v22
	v_cndmask_b32_e32 v22, v22, v23, vcc
	v_cmp_class_f32_e32 vcc, v21, v101
	s_nop 1
	v_cndmask_b32_e32 v21, v22, v21, vcc
	s_nop 0
	v_div_scale_f32 v24, vcc, 1.0, v21, 1.0
	v_rcp_f32_e32 v42, v21
	v_mul_f32_e32 v21, v117, v117
	v_fmac_f32_e32 v21, v133, v133
	v_fmac_f32_e32 v21, v39, v39
	v_fmac_f32_e32 v21, v14, v14
	s_nop 1
	v_add_f32_dpp v21, v21, v21 quad_perm:[1,0,3,2] row_mask:0xf bank_mask:0xf
	v_mul_f32_e32 v15, v15, v42
	s_nop 1
	v_add_f32_dpp v21, v21, v21 quad_perm:[2,3,0,1] row_mask:0xf bank_mask:0xf
	s_nop 1
	v_add_f32_dpp v21, v21, v21 row_half_mirror row_mask:0xf bank_mask:0xf
	s_nop 1
	v_add_f32_dpp v21, v21, v21 row_mirror row_mask:0xf bank_mask:0xf
; DI void gla_stage3(const Ctx& c0, int layer, int unit, int cb, LAS unsigned char* lds) {
;     ...
;     float rs[16];
; #pragma unroll
;     for (int rg = 0; rg < 16; ++rg) { float ss = o[0][rg] * o[0][rg] + o[1][rg] * o[1][rg] + o[2][rg] * o[2][rg] + o[3][rg] * o[3][rg];
;         ss += __shfl_xor(ss, 1); ss += __shfl_xor(ss, 2); ss += __shfl_xor(ss, 4); ss += __shfl_xor(ss, 8); ss += __shfl_xor(ss, 16);
;         rs[rg] = 1.f / sqrtf(ss * (1.f / 128.f) + EPS); }
	v_mov_b32_e32 v22, v21
	v_mov_b32_e32 v23, v21
	s_nop 1
	v_permlane16_swap_b32_e32 v22, v23
	v_add_f32_e32 v21, v22, v23
	v_fmamk_f32 v21, v21, 0x3c000000, v100
	v_cmp_gt_f32_e32 vcc, s34, v21
	v_mul_f32_e32 v22, 0x4f800000, v21
	s_nop 0
	v_cndmask_b32_e32 v21, v21, v22, vcc
	v_sqrt_f32_e32 v22, v21
	s_nop 0
	v_add_u32_e32 v23, -1, v22
	v_fma_f32 v24, -v23, v22, v21
	v_cmp_ge_f32_e64 s[4:5], 0, v24
	v_add_u32_e32 v24, 1, v22
	s_nop 0
	v_cndmask_b32_e64 v23, v22, v23, s[4:5]
	v_fma_f32 v22, -v24, v22, v21
	v_cmp_lt_f32_e64 s[4:5], 0, v22
	s_nop 1
	v_cndmask_b32_e64 v22, v23, v24, s[4:5]
	v_mul_f32_e32 v23, 0x37800000, v22
	v_cndmask_b32_e32 v22, v22, v23, vcc
	v_cmp_class_f32_e32 vcc, v21, v101
	s_nop 1
	v_cndmask_b32_e32 v21, v22, v21, vcc
	s_nop 0
	v_div_scale_f32 v24, vcc, 1.0, v21, 1.0
	v_rcp_f32_e32 v41, v21
	v_mul_f32_e32 v21, v116, v116
	v_fmac_f32_e32 v21, v132, v132
	v_fmac_f32_e32 v21, v38, v38
	v_fmac_f32_e32 v21, v13, v13
	s_nop 1
	v_add_f32_dpp v21, v21, v21 quad_perm:[1,0,3,2] row_mask:0xf bank_mask:0xf
	v_mul_f32_e32 v39, v39, v41
	v_mul_f32_e32 v14, v14, v41
	s_nop 1
	v_add_f32_dpp v21, v21, v21 quad_perm:[2,3,0,1] row_mask:0xf bank_mask:0xf
	s_nop 1
	v_add_f32_dpp v21, v21, v21 row_half_mirror row_mask:0xf bank_mask:0xf
	s_nop 1
	v_add_f32_dpp v21, v21, v21 row_mirror row_mask:0xf bank_mask:0xf
	v_mov_b32_e32 v22, v21
	v_mov_b32_e32 v23, v21
	s_nop 1
	v_permlane16_swap_b32_e32 v22, v23
	v_add_f32_e32 v21, v22, v23
	v_fmamk_f32 v21, v21, 0x3c000000, v100
	v_cmp_gt_f32_e32 vcc, s34, v21
	v_mul_f32_e32 v22, 0x4f800000, v21
	s_nop 0
	v_cndmask_b32_e32 v21, v21, v22, vcc
	v_sqrt_f32_e32 v22, v21
	s_nop 0
	v_add_u32_e32 v23, -1, v22
	v_fma_f32 v24, -v23, v22, v21
	v_cmp_ge_f32_e64 s[4:5], 0, v24
	v_add_u32_e32 v24, 1, v22
	s_nop 0
	v_cndmask_b32_e64 v23, v22, v23, s[4:5]
	v_fma_f32 v22, -v24, v22, v21
	v_cmp_lt_f32_e64 s[4:5], 0, v22
	s_nop 1
	v_cndmask_b32_e64 v22, v23, v24, s[4:5]
	v_mul_f32_e32 v23, 0x37800000, v22
	v_cndmask_b32_e32 v22, v22, v23, vcc
	v_cmp_class_f32_e32 vcc, v21, v101
	s_nop 1
	v_cndmask_b32_e32 v21, v22, v21, vcc
	s_nop 0
	v_div_scale_f32 v24, vcc, 1.0, v21, 1.0
	v_rcp_f32_e32 v40, v21
	v_mul_f32_e32 v21, v115, v115
	v_fmac_f32_e32 v21, v131, v131
	v_fmac_f32_e32 v21, v37, v37
	v_fmac_f32_e32 v21, v12, v12
	s_nop 1
	v_add_f32_dpp v21, v21, v21 quad_perm:[1,0,3,2] row_mask:0xf bank_mask:0xf
	v_mul_f32_e32 v38, v38, v40
	v_mul_f32_e32 v13, v13, v40
	s_nop 1
	v_add_f32_dpp v21, v21, v21 quad_perm:[2,3,0,1] row_mask:0xf bank_mask:0xf
	s_nop 1
	v_add_f32_dpp v21, v21, v21 row_half_mirror row_mask:0xf bank_mask:0xf
	s_nop 1
	v_add_f32_dpp v21, v21, v21 row_mirror row_mask:0xf bank_mask:0xf
	v_mov_b32_e32 v22, v21
	v_mov_b32_e32 v23, v21
	s_nop 1
	v_permlane16_swap_b32_e32 v22, v23
	v_add_f32_e32 v21, v22, v23
	v_fmamk_f32 v21, v21, 0x3c000000, v100
	v_cmp_gt_f32_e32 vcc, s34, v21
	v_mul_f32_e32 v22, 0x4f800000, v21
	s_nop 0
	v_cndmask_b32_e32 v21, v21, v22, vcc
	v_sqrt_f32_e32 v22, v21
	s_nop 0
	v_add_u32_e32 v23, -1, v22
	v_fma_f32 v24, -v23, v22, v21
	v_cmp_ge_f32_e64 s[4:5], 0, v24
	v_add_u32_e32 v24, 1, v22
	s_nop 0
	v_cndmask_b32_e64 v23, v22, v23, s[4:5]
	v_fma_f32 v22, -v24, v22, v21
	v_cmp_lt_f32_e64 s[4:5], 0, v22
	s_nop 1
	v_cndmask_b32_e64 v22, v23, v24, s[4:5]
	v_mul_f32_e32 v23, 0x37800000, v22
	v_cndmask_b32_e32 v22, v22, v23, vcc
	v_cmp_class_f32_e32 vcc, v21, v101
	s_nop 1
	v_cndmask_b32_e32 v21, v22, v21, vcc
	s_nop 0
	v_div_scale_f32 v24, vcc, 1.0, v21, 1.0
	v_rcp_f32_e32 v35, v21
	v_mul_f32_e32 v21, v114, v114
	v_fmac_f32_e32 v21, v130, v130
	v_fmac_f32_e32 v21, v36, v36
	v_fmac_f32_e32 v21, v11, v11
	s_nop 1
	v_add_f32_dpp v21, v21, v21 quad_perm:[1,0,3,2] row_mask:0xf bank_mask:0xf
	v_mul_f32_e32 v37, v37, v35
	v_mul_f32_e32 v12, v12, v35
	s_nop 1
	v_add_f32_dpp v21, v21, v21 quad_perm:[2,3,0,1] row_mask:0xf bank_mask:0xf
	s_nop 1
	v_add_f32_dpp v21, v21, v21 row_half_mirror row_mask:0xf bank_mask:0xf
	s_nop 1
	v_add_f32_dpp v21, v21, v21 row_mirror row_mask:0xf bank_mask:0xf
	v_mov_b32_e32 v22, v21
	v_mov_b32_e32 v23, v21
	s_nop 1
	v_permlane16_swap_b32_e32 v22, v23
	v_add_f32_e32 v21, v22, v23
	v_fmamk_f32 v21, v21, 0x3c000000, v100
	v_cmp_gt_f32_e32 vcc, s34, v21
	v_mul_f32_e32 v22, 0x4f800000, v21
	s_nop 0
	v_cndmask_b32_e32 v21, v21, v22, vcc
	v_sqrt_f32_e32 v22, v21
	s_nop 0
	v_add_u32_e32 v23, -1, v22
	v_fma_f32 v24, -v23, v22, v21
	v_cmp_ge_f32_e64 s[4:5], 0, v24
	v_add_u32_e32 v24, 1, v22
	s_nop 0
	v_cndmask_b32_e64 v23, v22, v23, s[4:5]
	v_fma_f32 v22, -v24, v22, v21
	v_cmp_lt_f32_e64 s[4:5], 0, v22
	s_nop 1
	v_cndmask_b32_e64 v22, v23, v24, s[4:5]
	v_mul_f32_e32 v23, 0x37800000, v22
	v_cndmask_b32_e32 v22, v22, v23, vcc
	v_cmp_class_f32_e32 vcc, v21, v101
	s_nop 1
	v_cndmask_b32_e32 v21, v22, v21, vcc
	s_nop 0
	v_div_scale_f32 v24, vcc, 1.0, v21, 1.0
	v_rcp_f32_e32 v31, v21
	v_mul_f32_e32 v21, v113, v113
	v_fmac_f32_e32 v21, v129, v129
	v_fmac_f32_e32 v21, v34, v34
	v_fmac_f32_e32 v21, v10, v10
	s_nop 1
	v_add_f32_dpp v21, v21, v21 quad_perm:[1,0,3,2] row_mask:0xf bank_mask:0xf
	v_mul_f32_e32 v36, v36, v31
	v_mul_f32_e32 v11, v11, v31
	s_nop 1
	v_add_f32_dpp v21, v21, v21 quad_perm:[2,3,0,1] row_mask:0xf bank_mask:0xf
	s_nop 1
	v_add_f32_dpp v21, v21, v21 row_half_mirror row_mask:0xf bank_mask:0xf
	s_nop 1
	v_add_f32_dpp v21, v21, v21 row_mirror row_mask:0xf bank_mask:0xf
	v_mov_b32_e32 v22, v21
	v_mov_b32_e32 v23, v21
	s_nop 1
	v_permlane16_swap_b32_e32 v22, v23
	v_add_f32_e32 v21, v22, v23
	v_fmamk_f32 v21, v21, 0x3c000000, v100
	v_cmp_gt_f32_e32 vcc, s34, v21
	v_mul_f32_e32 v22, 0x4f800000, v21
	s_nop 0
	v_cndmask_b32_e32 v21, v21, v22, vcc
	v_sqrt_f32_e32 v22, v21
	s_nop 0
; DI void gla_stage3(const Ctx& c0, int layer, int unit, int cb, LAS unsigned char* lds) {
;     ...
;     float rs[16];
; #pragma unroll
;     for (int rg = 0; rg < 16; ++rg) { float ss = o[0][rg] * o[0][rg] + o[1][rg] * o[1][rg] + o[2][rg] * o[2][rg] + o[3][rg] * o[3][rg];
;         ss += __shfl_xor(ss, 1); ss += __shfl_xor(ss, 2); ss += __shfl_xor(ss, 4); ss += __shfl_xor(ss, 8); ss += __shfl_xor(ss, 16);
;         rs[rg] = 1.f / sqrtf(ss * (1.f / 128.f) + EPS); }
	v_add_u32_e32 v23, -1, v22
	v_fma_f32 v24, -v23, v22, v21
	v_cmp_ge_f32_e64 s[4:5], 0, v24
	v_add_u32_e32 v24, 1, v22
	s_nop 0
	v_cndmask_b32_e64 v23, v22, v23, s[4:5]
	v_fma_f32 v22, -v24, v22, v21
	v_cmp_lt_f32_e64 s[4:5], 0, v22
	s_nop 1
	v_cndmask_b32_e64 v22, v23, v24, s[4:5]
	v_mul_f32_e32 v23, 0x37800000, v22
	v_cndmask_b32_e32 v22, v22, v23, vcc
	v_cmp_class_f32_e32 vcc, v21, v101
	s_nop 1
	v_cndmask_b32_e32 v21, v22, v21, vcc
	s_nop 0
	v_div_scale_f32 v24, vcc, 1.0, v21, 1.0
	v_rcp_f32_e32 v27, v21
	v_mul_f32_e32 v21, v112, v112
	v_fmac_f32_e32 v21, v128, v128
	v_fmac_f32_e32 v21, v33, v33
	v_fmac_f32_e32 v21, v9, v9
	s_nop 1
	v_add_f32_dpp v21, v21, v21 quad_perm:[1,0,3,2] row_mask:0xf bank_mask:0xf
	v_mul_f32_e32 v34, v34, v27
	v_mul_f32_e32 v10, v10, v27
	s_nop 1
	v_add_f32_dpp v21, v21, v21 quad_perm:[2,3,0,1] row_mask:0xf bank_mask:0xf
	s_nop 1
	v_add_f32_dpp v21, v21, v21 row_half_mirror row_mask:0xf bank_mask:0xf
	s_nop 1
	v_add_f32_dpp v21, v21, v21 row_mirror row_mask:0xf bank_mask:0xf
	v_mov_b32_e32 v22, v21
	v_mov_b32_e32 v23, v21
	s_nop 1
	v_permlane16_swap_b32_e32 v22, v23
	v_add_f32_e32 v21, v22, v23
	v_fmamk_f32 v21, v21, 0x3c000000, v100
	v_cmp_gt_f32_e32 vcc, s34, v21
	v_mul_f32_e32 v22, 0x4f800000, v21
	s_nop 0
	v_cndmask_b32_e32 v21, v21, v22, vcc
	v_sqrt_f32_e32 v22, v21
	s_nop 0
	v_add_u32_e32 v23, -1, v22
	v_fma_f32 v24, -v23, v22, v21
	v_cmp_ge_f32_e64 s[4:5], 0, v24
	v_add_u32_e32 v24, 1, v22
	s_nop 0
	v_cndmask_b32_e64 v23, v22, v23, s[4:5]
	v_fma_f32 v22, -v24, v22, v21
	v_cmp_lt_f32_e64 s[4:5], 0, v22
	s_nop 1
	v_cndmask_b32_e64 v22, v23, v24, s[4:5]
	v_mul_f32_e32 v23, 0x37800000, v22
	v_cndmask_b32_e32 v22, v22, v23, vcc
	v_cmp_class_f32_e32 vcc, v21, v101
	s_nop 1
	v_cndmask_b32_e32 v21, v22, v21, vcc
	s_nop 0
	v_div_scale_f32 v24, vcc, 1.0, v21, 1.0
	v_rcp_f32_e32 v25, v21
	v_mul_f32_e32 v21, v111, v111
	v_fmac_f32_e32 v21, v127, v127
	v_fmac_f32_e32 v21, v32, v32
	v_fmac_f32_e32 v21, v8, v8
	s_nop 1
	v_add_f32_dpp v21, v21, v21 quad_perm:[1,0,3,2] row_mask:0xf bank_mask:0xf
	v_mul_f32_e32 v33, v33, v25
	v_mul_f32_e32 v9, v9, v25
	s_nop 1
	v_add_f32_dpp v21, v21, v21 quad_perm:[2,3,0,1] row_mask:0xf bank_mask:0xf
	s_nop 1
	v_add_f32_dpp v21, v21, v21 row_half_mirror row_mask:0xf bank_mask:0xf
	s_nop 1
	v_add_f32_dpp v21, v21, v21 row_mirror row_mask:0xf bank_mask:0xf
	v_mov_b32_e32 v22, v21
	v_mov_b32_e32 v23, v21
	s_nop 1
	v_permlane16_swap_b32_e32 v22, v23
	v_add_f32_e32 v21, v22, v23
	v_fmamk_f32 v21, v21, 0x3c000000, v100
	v_cmp_gt_f32_e32 vcc, s34, v21
	v_mul_f32_e32 v22, 0x4f800000, v21
	s_nop 0
	v_cndmask_b32_e32 v21, v21, v22, vcc
	v_sqrt_f32_e32 v22, v21
	s_nop 0
	v_add_u32_e32 v23, -1, v22
	v_fma_f32 v24, -v23, v22, v21
	v_cmp_ge_f32_e64 s[4:5], 0, v24
	v_add_u32_e32 v24, 1, v22
	s_nop 0
	v_cndmask_b32_e64 v23, v22, v23, s[4:5]
	v_fma_f32 v22, -v24, v22, v21
	v_cmp_lt_f32_e64 s[4:5], 0, v22
	s_nop 1
	v_cndmask_b32_e64 v22, v23, v24, s[4:5]
	v_mul_f32_e32 v23, 0x37800000, v22
	v_cndmask_b32_e32 v22, v22, v23, vcc
	v_cmp_class_f32_e32 vcc, v21, v101
	s_nop 1
	v_cndmask_b32_e32 v21, v22, v21, vcc
	s_nop 0
	v_div_scale_f32 v24, vcc, 1.0, v21, 1.0
	v_rcp_f32_e32 v24, v21
	v_mul_f32_e32 v21, v110, v110
	v_fmac_f32_e32 v21, v126, v126
	v_fmac_f32_e32 v21, v30, v30
	v_fmac_f32_e32 v21, v7, v7
	s_nop 1
	v_add_f32_dpp v21, v21, v21 quad_perm:[1,0,3,2] row_mask:0xf bank_mask:0xf
	v_mul_f32_e32 v32, v32, v24
	v_mul_f32_e32 v8, v8, v24
	s_nop 1
	v_add_f32_dpp v21, v21, v21 quad_perm:[2,3,0,1] row_mask:0xf bank_mask:0xf
	s_nop 1
	v_add_f32_dpp v21, v21, v21 row_half_mirror row_mask:0xf bank_mask:0xf
	s_nop 1
	v_add_f32_dpp v21, v21, v21 row_mirror row_mask:0xf bank_mask:0xf
	v_mov_b32_e32 v22, v21
	v_mov_b32_e32 v23, v21
	s_nop 1
	v_permlane16_swap_b32_e32 v22, v23
	v_add_f32_e32 v21, v22, v23
	v_fmamk_f32 v21, v21, 0x3c000000, v100
	v_cmp_gt_f32_e32 vcc, s34, v21
	v_mul_f32_e32 v22, 0x4f800000, v21
	s_nop 0
	v_cndmask_b32_e32 v21, v21, v22, vcc
	v_sqrt_f32_e32 v22, v21
	s_nop 0
	v_add_u32_e32 v23, -1, v22
	v_fma_f32 v49, -v23, v22, v21
	v_cmp_ge_f32_e64 s[4:5], 0, v49
	v_add_u32_e32 v49, 1, v22
	s_nop 0
	v_cndmask_b32_e64 v23, v22, v23, s[4:5]
	v_fma_f32 v22, -v49, v22, v21
	v_cmp_lt_f32_e64 s[4:5], 0, v22
	s_nop 1
	v_cndmask_b32_e64 v22, v23, v49, s[4:5]
	v_mul_f32_e32 v23, 0x37800000, v22
	v_cndmask_b32_e32 v22, v22, v23, vcc
	v_cmp_class_f32_e32 vcc, v21, v101
	s_nop 1
	v_cndmask_b32_e32 v21, v22, v21, vcc
	s_nop 0
	v_div_scale_f32 v49, vcc, 1.0, v21, 1.0
	v_rcp_f32_e32 v23, v21
	v_mul_f32_e32 v21, v109, v109
	v_fmac_f32_e32 v21, v125, v125
	v_fmac_f32_e32 v21, v29, v29
	v_fmac_f32_e32 v21, v6, v6
	s_nop 1
	v_add_f32_dpp v21, v21, v21 quad_perm:[1,0,3,2] row_mask:0xf bank_mask:0xf
	v_mul_f32_e32 v30, v30, v23
	v_mul_f32_e32 v7, v7, v23
	s_nop 1
	v_add_f32_dpp v21, v21, v21 quad_perm:[2,3,0,1] row_mask:0xf bank_mask:0xf
	s_nop 1
	v_add_f32_dpp v21, v21, v21 row_half_mirror row_mask:0xf bank_mask:0xf
	s_nop 1
	v_add_f32_dpp v21, v21, v21 row_mirror row_mask:0xf bank_mask:0xf
	v_mov_b32_e32 v22, v21
	v_mov_b32_e32 v49, v21
	s_nop 1
	v_permlane16_swap_b32_e32 v22, v49
	v_add_f32_e32 v21, v22, v49
	v_fmamk_f32 v21, v21, 0x3c000000, v100
	v_cmp_gt_f32_e32 vcc, s34, v21
	v_mul_f32_e32 v22, 0x4f800000, v21
	s_nop 0
	v_cndmask_b32_e32 v21, v21, v22, vcc
	v_sqrt_f32_e32 v22, v21
	s_nop 0
	v_add_u32_e32 v49, -1, v22
	v_fma_f32 v50, -v49, v22, v21
	v_cmp_ge_f32_e64 s[4:5], 0, v50
	v_add_u32_e32 v50, 1, v22
	s_nop 0
	v_cndmask_b32_e64 v49, v22, v49, s[4:5]
	v_fma_f32 v22, -v50, v22, v21
	v_cmp_lt_f32_e64 s[4:5], 0, v22
	s_nop 1
	v_cndmask_b32_e64 v22, v49, v50, s[4:5]
	v_mul_f32_e32 v49, 0x37800000, v22
; #define LAS __attribute__((address_space(3)))
; #define LDS_WAIT() asm volatile("s_waitcnt lgkmcnt(0)" ::: "memory")
; DI unsigned cvtpk(float lo, float hi) { f32x2 v = {lo, hi}; bf16x2_t b = __builtin_convertvector(v, bf16x2_t); return __builtin_bit_cast(unsigned, b); }
; DI float bf2f(bf16 b) { return __uint_as_float(((unsigned)b) << 16); }
; DI float siluf_(float x) { return x / (1.f + __expf(-x)); }
; DI void gla_stage3(const Ctx& c0, int layer, int unit, int cb, LAS unsigned char* lds) {
;     ...
;     float rs[16];
; #pragma unroll
;     for (int rg = 0; rg < 16; ++rg) { float ss = o[0][rg] * o[0][rg] + o[1][rg] * o[1][rg] + o[2][rg] * o[2][rg] + o[3][rg] * o[3][rg];
;         ss += __shfl_xor(ss, 1); ss += __shfl_xor(ss, 2); ss += __shfl_xor(ss, 4); ss += __shfl_xor(ss, 8); ss += __shfl_xor(ss, 16);
;         rs[rg] = 1.f / sqrtf(ss * (1.f / 128.f) + EPS); }
;     LDS_WAIT();
;     g3_tile_in((const bf16*)(c.ws + O_GR) + row0 * 512 + h * 128, R, lane);
; #pragma unroll
;     for (int vb = 0; vb < 4; ++vb) { const float g = gn[32 * vb + r];
; #pragma unroll
;         for (int rg = 0; rg < 16; ++rg) { LAS bf16* e = (LAS bf16*)(R + (4 * hi) * G3_PITCH + r * 2 + ((rg & 3) + 8 * (rg >> 2)) * G3_PITCH + 64 * vb);
;             const float z = bf2f(*e);
;             *e = (bf16)(cvtpk(o[vb][rg] * rs[rg] * g * siluf_(z), 0.f) & 0xffffu); }
	v_cndmask_b32_e32 v22, v22, v49, vcc
	v_cmp_class_f32_e32 vcc, v21, v101
	s_nop 1
	v_cndmask_b32_e32 v21, v22, v21, vcc
	s_nop 0
	v_div_scale_f32 v50, vcc, 1.0, v21, 1.0
	v_rcp_f32_e32 v22, v21
	v_mul_f32_e32 v21, v108, v108
	v_fmac_f32_e32 v21, v124, v124
	v_fmac_f32_e32 v21, v28, v28
	v_fmac_f32_e32 v21, v5, v5
	s_nop 1
	v_add_f32_dpp v21, v21, v21 quad_perm:[1,0,3,2] row_mask:0xf bank_mask:0xf
	v_mul_f32_e32 v29, v29, v22
	v_mul_f32_e32 v6, v6, v22
	s_nop 1
	v_add_f32_dpp v21, v21, v21 quad_perm:[2,3,0,1] row_mask:0xf bank_mask:0xf
	s_nop 1
	v_add_f32_dpp v21, v21, v21 row_half_mirror row_mask:0xf bank_mask:0xf
	s_nop 1
	v_add_f32_dpp v21, v21, v21 row_mirror row_mask:0xf bank_mask:0xf
	v_mov_b32_e32 v49, v21
	v_mov_b32_e32 v50, v21
	s_nop 1
	v_permlane16_swap_b32_e32 v49, v50
	v_add_f32_e32 v21, v49, v50
	v_fmamk_f32 v21, v21, 0x3c000000, v100
	v_cmp_gt_f32_e32 vcc, s34, v21
	v_mul_f32_e32 v49, 0x4f800000, v21
	s_nop 0
	v_cndmask_b32_e32 v21, v21, v49, vcc
	v_sqrt_f32_e32 v49, v21
	s_nop 0
	v_add_u32_e32 v50, -1, v49
	v_fma_f32 v51, -v50, v49, v21
	v_cmp_ge_f32_e64 s[4:5], 0, v51
	v_add_u32_e32 v51, 1, v49
	s_nop 0
	v_cndmask_b32_e64 v50, v49, v50, s[4:5]
	v_fma_f32 v49, -v51, v49, v21
	v_cmp_lt_f32_e64 s[4:5], 0, v49
	s_nop 1
	v_cndmask_b32_e64 v49, v50, v51, s[4:5]
	v_mul_f32_e32 v50, 0x37800000, v49
	v_cndmask_b32_e32 v49, v49, v50, vcc
	v_cmp_class_f32_e32 vcc, v21, v101
	s_nop 1
	v_cndmask_b32_e32 v21, v49, v21, vcc
	s_nop 0
	v_div_scale_f32 v51, vcc, 1.0, v21, 1.0
	v_rcp_f32_e32 v21, v21
	v_mul_f32_e32 v49, v107, v107
	v_fmac_f32_e32 v49, v123, v123
	v_fmac_f32_e32 v49, v26, v26
	v_fmac_f32_e32 v49, v4, v4
	ds_bpermute_b32 v2, v2, v49
	v_mul_f32_e32 v28, v28, v21
	v_mul_f32_e32 v5, v5, v21
	s_waitcnt lgkmcnt(0)
	v_add_f32_e32 v2, v49, v2
	ds_bpermute_b32 v3, v3, v2
	s_waitcnt lgkmcnt(0)
	v_add_f32_e32 v2, v2, v3
	ds_bpermute_b32 v3, v20, v2
	s_waitcnt lgkmcnt(0)
	v_add_f32_e32 v2, v2, v3
	ds_bpermute_b32 v3, v47, v2
	s_waitcnt lgkmcnt(0)
	v_add_f32_e32 v2, v2, v3
	ds_bpermute_b32 v3, v48, v2
	s_waitcnt lgkmcnt(0)
	v_add_f32_e32 v2, v2, v3
	v_fmamk_f32 v2, v2, 0x3c000000, v100
	v_cmp_gt_f32_e32 vcc, s34, v2
	v_mul_f32_e32 v3, 0x4f800000, v2
	s_nop 0
	v_cndmask_b32_e32 v2, v2, v3, vcc
	v_sqrt_f32_e32 v3, v2
	s_nop 0
	v_add_u32_e32 v20, -1, v3
	v_fma_f32 v47, -v20, v3, v2
	v_cmp_ge_f32_e64 s[4:5], 0, v47
	v_add_u32_e32 v47, 1, v3
	s_nop 0
	v_cndmask_b32_e64 v20, v3, v20, s[4:5]
	v_fma_f32 v3, -v47, v3, v2
	v_cmp_lt_f32_e64 s[4:5], 0, v3
	s_nop 1
	v_cndmask_b32_e64 v3, v20, v47, s[4:5]
	v_mul_f32_e32 v20, 0x37800000, v3
	v_cndmask_b32_e32 v3, v3, v20, vcc
	v_cmp_class_f32_e32 vcc, v2, v101
	s_nop 1
	v_cndmask_b32_e32 v2, v3, v2, vcc
	s_nop 0
	v_rcp_f32_e32 v20, v2
	v_mul_f32_e32 v47, v138, v46
	v_mul_f32_e32 v26, v26, v20
	v_mul_f32_e32 v4, v4, v20
	s_waitcnt vmcnt(2) lgkmcnt(0)
	ds_write_b128 v92, v[164:167]
	s_waitcnt vmcnt(0) lgkmcnt(0)
	ds_write_b128 v92, v[170:173] offset:1088
	s_waitcnt vmcnt(13) lgkmcnt(0)
	ds_write_b128 v92, v[174:177] offset:2176
	s_waitcnt vmcnt(8) lgkmcnt(0)
	ds_write_b128 v92, v[178:181] offset:3264
	s_waitcnt vmcnt(9) lgkmcnt(0)
	ds_write_b128 v92, v[196:199] offset:4352
	s_waitcnt vmcnt(10) lgkmcnt(0)
	ds_write_b128 v92, v[200:203] offset:5440
	v_lshl_add_u64 v[2:3], v[168:169], 0, v[80:81]
	s_waitcnt vmcnt(5) lgkmcnt(0)
	ds_write_b128 v92, v[204:207] offset:6528
	global_load_dwordx4 v[48:51], v[2:3], off
	s_waitcnt vmcnt(0) lgkmcnt(0)
	ds_write_b128 v92, v[48:51] offset:7616
	s_waitcnt lgkmcnt(0)
	ds_read_u16 v3, v1
	s_waitcnt lgkmcnt(0)
	v_lshlrev_b32_e32 v3, 16, v3
	v_mul_f32_e32 v48, 0xbfb8aa3b, v3
	v_exp_f32_e32 v48, v48
	s_waitcnt vmcnt(0)
	v_mul_f32_e32 v47, v47, v232
	v_add_f32_e32 v48, 1.0, v48
	v_rcp_f32_e32 v49, v48
	s_nop 0
	v_mul_f32_e32 v3, v3, v49
	v_mul_f32_e32 v3, v47, v3
	v_cvt_pk_bf16_f32 v3, v3, v3
	ds_write_b16 v1, v3
	ds_read_u16 v3, v1 offset:272
	s_waitcnt lgkmcnt(0)
	v_lshlrev_b32_e32 v3, 16, v3
	v_mul_f32_e32 v48, 0xbfb8aa3b, v3
	v_exp_f32_e32 v48, v48
	v_mul_f32_e32 v47, v137, v45
	v_add_f32_e32 v48, 1.0, v48
	v_rcp_f32_e32 v49, v48
	v_mul_f32_e32 v47, v47, v232
	v_mul_f32_e32 v3, v3, v49
	v_mul_f32_e32 v3, v47, v3
	v_cvt_pk_bf16_f32 v3, v3, v3
	ds_write_b16 v1, v3 offset:272
	ds_read_u16 v3, v1 offset:544
	s_waitcnt lgkmcnt(0)
	v_lshlrev_b32_e32 v3, 16, v3
	v_mul_f32_e32 v48, 0xbfb8aa3b, v3
	v_exp_f32_e32 v48, v48
	v_mul_f32_e32 v47, v136, v44
	v_add_f32_e32 v48, 1.0, v48
	v_rcp_f32_e32 v49, v48
	v_mul_f32_e32 v47, v47, v232
	v_mul_f32_e32 v3, v3, v49
	v_mul_f32_e32 v3, v47, v3
	v_cvt_pk_bf16_f32 v3, v3, v3
	ds_write_b16 v1, v3 offset:544
	ds_read_u16 v3, v1 offset:816
	s_waitcnt lgkmcnt(0)
	v_lshlrev_b32_e32 v3, 16, v3
	v_mul_f32_e32 v48, 0xbfb8aa3b, v3
	v_exp_f32_e32 v48, v48
	v_mul_f32_e32 v47, v135, v43
	v_add_f32_e32 v48, 1.0, v48
	v_rcp_f32_e32 v49, v48
	v_mul_f32_e32 v47, v47, v232
	v_mul_f32_e32 v3, v3, v49
	v_mul_f32_e32 v3, v47, v3
	v_cvt_pk_bf16_f32 v3, v3, v3
	ds_write_b16 v1, v3 offset:816
	ds_read_u16 v3, v1 offset:2176
	s_waitcnt lgkmcnt(0)
	v_lshlrev_b32_e32 v3, 16, v3
	v_mul_f32_e32 v48, 0xbfb8aa3b, v3
	v_exp_f32_e32 v48, v48
	v_mul_f32_e32 v47, v134, v42
	v_add_f32_e32 v48, 1.0, v48
	v_rcp_f32_e32 v49, v48
	v_mul_f32_e32 v47, v47, v232
	v_mul_f32_e32 v3, v3, v49
	v_mul_f32_e32 v3, v47, v3
	v_cvt_pk_bf16_f32 v3, v3, v3
	ds_write_b16 v1, v3 offset:2176
	ds_read_u16 v3, v1 offset:2448
	s_waitcnt lgkmcnt(0)
	v_lshlrev_b32_e32 v3, 16, v3
	v_mul_f32_e32 v48, 0xbfb8aa3b, v3
	v_exp_f32_e32 v48, v48
	v_mul_f32_e32 v47, v133, v41
	v_add_f32_e32 v48, 1.0, v48
	v_rcp_f32_e32 v49, v48
	v_mul_f32_e32 v47, v47, v232
	v_mul_f32_e32 v3, v3, v49
	v_mul_f32_e32 v3, v47, v3
	v_cvt_pk_bf16_f32 v3, v3, v3
	ds_write_b16 v1, v3 offset:2448
	ds_read_u16 v3, v1 offset:2720
	s_waitcnt lgkmcnt(0)
; #define LAS __attribute__((address_space(3)))
; DI unsigned cvtpk(float lo, float hi) { f32x2 v = {lo, hi}; bf16x2_t b = __builtin_convertvector(v, bf16x2_t); return __builtin_bit_cast(unsigned, b); }
; DI float bf2f(bf16 b) { return __uint_as_float(((unsigned)b) << 16); }
; DI float siluf_(float x) { return x / (1.f + __expf(-x)); }
; DI void gla_stage3(const Ctx& c0, int layer, int unit, int cb, LAS unsigned char* lds) {
;     ...
;     for (int vb = 0; vb < 4; ++vb) { const float g = gn[32 * vb + r];
; #pragma unroll
;         for (int rg = 0; rg < 16; ++rg) { LAS bf16* e = (LAS bf16*)(R + (4 * hi) * G3_PITCH + r * 2 + ((rg & 3) + 8 * (rg >> 2)) * G3_PITCH + 64 * vb);
;             const float z = bf2f(*e);
;             *e = (bf16)(cvtpk(o[vb][rg] * rs[rg] * g * siluf_(z), 0.f) & 0xffffu); }
	v_lshlrev_b32_e32 v3, 16, v3
	v_mul_f32_e32 v48, 0xbfb8aa3b, v3
	v_exp_f32_e32 v48, v48
	v_mul_f32_e32 v47, v132, v40
	v_add_f32_e32 v48, 1.0, v48
	v_rcp_f32_e32 v49, v48
	v_mul_f32_e32 v47, v47, v232
	v_mul_f32_e32 v3, v3, v49
	v_mul_f32_e32 v3, v47, v3
	v_cvt_pk_bf16_f32 v3, v3, v3
	ds_write_b16 v1, v3 offset:2720
	ds_read_u16 v3, v1 offset:2992
	s_waitcnt lgkmcnt(0)
	v_lshlrev_b32_e32 v3, 16, v3
	v_mul_f32_e32 v48, 0xbfb8aa3b, v3
	v_exp_f32_e32 v48, v48
	v_mul_f32_e32 v47, v131, v35
	v_add_f32_e32 v48, 1.0, v48
	v_rcp_f32_e32 v49, v48
	v_mul_f32_e32 v47, v47, v232
	v_mul_f32_e32 v3, v3, v49
	v_mul_f32_e32 v3, v47, v3
	v_cvt_pk_bf16_f32 v3, v3, v3
	ds_write_b16 v1, v3 offset:2992
	ds_read_u16 v3, v1 offset:4352
	s_waitcnt lgkmcnt(0)
	v_lshlrev_b32_e32 v3, 16, v3
	v_mul_f32_e32 v48, 0xbfb8aa3b, v3
	v_exp_f32_e32 v48, v48
	v_mul_f32_e32 v47, v130, v31
	v_add_f32_e32 v48, 1.0, v48
	v_rcp_f32_e32 v49, v48
	v_mul_f32_e32 v47, v47, v232
	v_mul_f32_e32 v3, v3, v49
	v_mul_f32_e32 v3, v47, v3
	v_cvt_pk_bf16_f32 v3, v3, v3
	ds_write_b16 v1, v3 offset:4352
	ds_read_u16 v3, v1 offset:4624
	s_waitcnt lgkmcnt(0)
	v_lshlrev_b32_e32 v3, 16, v3
	v_mul_f32_e32 v48, 0xbfb8aa3b, v3
	v_exp_f32_e32 v48, v48
	v_mul_f32_e32 v47, v129, v27
	v_add_f32_e32 v48, 1.0, v48
	v_rcp_f32_e32 v49, v48
	v_mul_f32_e32 v47, v47, v232
	v_mul_f32_e32 v3, v3, v49
	v_mul_f32_e32 v3, v47, v3
	v_cvt_pk_bf16_f32 v3, v3, v3
	ds_write_b16 v1, v3 offset:4624
	ds_read_u16 v3, v1 offset:4896
	s_waitcnt lgkmcnt(0)
	v_lshlrev_b32_e32 v3, 16, v3
	v_mul_f32_e32 v48, 0xbfb8aa3b, v3
	v_exp_f32_e32 v48, v48
	v_mul_f32_e32 v47, v128, v25
	v_add_f32_e32 v48, 1.0, v48
	v_rcp_f32_e32 v49, v48
	v_mul_f32_e32 v47, v47, v232
	v_mul_f32_e32 v3, v3, v49
	v_mul_f32_e32 v3, v47, v3
	v_cvt_pk_bf16_f32 v3, v3, v3
	ds_write_b16 v1, v3 offset:4896
	ds_read_u16 v3, v1 offset:5168
	s_waitcnt lgkmcnt(0)
	v_lshlrev_b32_e32 v3, 16, v3
	v_mul_f32_e32 v48, 0xbfb8aa3b, v3
	v_exp_f32_e32 v48, v48
	v_mul_f32_e32 v47, v127, v24
	v_add_f32_e32 v48, 1.0, v48
	v_rcp_f32_e32 v49, v48
	v_mul_f32_e32 v47, v47, v232
	v_mul_f32_e32 v3, v3, v49
	v_mul_f32_e32 v3, v47, v3
	v_cvt_pk_bf16_f32 v3, v3, v3
	ds_write_b16 v1, v3 offset:5168
	ds_read_u16 v3, v1 offset:6528
	s_waitcnt lgkmcnt(0)
	v_lshlrev_b32_e32 v3, 16, v3
	v_mul_f32_e32 v48, 0xbfb8aa3b, v3
	v_exp_f32_e32 v48, v48
	v_mul_f32_e32 v47, v126, v23
	v_add_f32_e32 v48, 1.0, v48
	v_rcp_f32_e32 v49, v48
	v_mul_f32_e32 v47, v47, v232
	v_mul_f32_e32 v3, v3, v49
	v_mul_f32_e32 v3, v47, v3
	v_cvt_pk_bf16_f32 v3, v3, v3
	ds_write_b16 v1, v3 offset:6528
	ds_read_u16 v3, v1 offset:6800
	s_waitcnt lgkmcnt(0)
	v_lshlrev_b32_e32 v3, 16, v3
	v_mul_f32_e32 v48, 0xbfb8aa3b, v3
	v_exp_f32_e32 v48, v48
	v_mul_f32_e32 v47, v125, v22
	v_add_f32_e32 v48, 1.0, v48
	v_rcp_f32_e32 v49, v48
	v_mul_f32_e32 v47, v47, v232
	v_mul_f32_e32 v3, v3, v49
	v_mul_f32_e32 v3, v47, v3
	v_cvt_pk_bf16_f32 v3, v3, v3
	ds_write_b16 v1, v3 offset:6800
	ds_read_u16 v3, v1 offset:7072
	s_waitcnt lgkmcnt(0)
	v_lshlrev_b32_e32 v3, 16, v3
	v_mul_f32_e32 v48, 0xbfb8aa3b, v3
	v_exp_f32_e32 v48, v48
	v_mul_f32_e32 v47, v124, v21
	v_add_f32_e32 v48, 1.0, v48
	v_rcp_f32_e32 v49, v48
	v_mul_f32_e32 v47, v47, v232
	v_mul_f32_e32 v3, v3, v49
	v_mul_f32_e32 v3, v47, v3
	v_cvt_pk_bf16_f32 v3, v3, v3
	ds_write_b16 v1, v3 offset:7072
	ds_read_u16 v3, v1 offset:7344
	v_mul_f32_e32 v47, v123, v20
	v_mul_f32_e32 v2, v47, v232
	s_waitcnt lgkmcnt(0)
	v_lshlrev_b32_e32 v3, 16, v3
	v_mul_f32_e32 v47, 0xbfb8aa3b, v3
	v_exp_f32_e32 v47, v47
	s_nop 0
	v_add_f32_e32 v47, 1.0, v47
	v_div_scale_f32 v48, s[0:1], v47, v47, v3
	s_nop 0
	v_rcp_f32_e32 v48, v47
	s_nop 0
	v_mul_f32_e32 v3, v3, v48
	v_mul_f32_e32 v2, v2, v3
	v_cvt_pk_bf16_f32 v2, v2, s0
	ds_write_b16 v1, v2 offset:7344
	ds_read_u16 v3, v1 offset:64
	v_mul_f32_e32 v47, v122, v46
	s_waitcnt lgkmcnt(0)
	v_lshlrev_b32_e32 v3, 16, v3
	v_mul_f32_e32 v48, 0xbfb8aa3b, v3
	v_exp_f32_e32 v48, v48
	s_waitcnt vmcnt(0)
	v_mul_f32_e32 v47, v47, v234
	v_add_f32_e32 v48, 1.0, v48
	v_rcp_f32_e32 v49, v48
	s_nop 0
	v_mul_f32_e32 v3, v3, v49
	v_mul_f32_e32 v3, v47, v3
	v_cvt_pk_bf16_f32 v3, v3, v3
	ds_write_b16 v1, v3 offset:64
	ds_read_u16 v3, v1 offset:336
	s_waitcnt lgkmcnt(0)
	v_lshlrev_b32_e32 v3, 16, v3
	v_mul_f32_e32 v48, 0xbfb8aa3b, v3
	v_exp_f32_e32 v48, v48
	v_mul_f32_e32 v47, v121, v45
	v_add_f32_e32 v48, 1.0, v48
	v_rcp_f32_e32 v49, v48
	v_mul_f32_e32 v47, v47, v234
	v_mul_f32_e32 v3, v3, v49
	v_mul_f32_e32 v3, v47, v3
	v_cvt_pk_bf16_f32 v3, v3, v3
	ds_write_b16 v1, v3 offset:336
	ds_read_u16 v3, v1 offset:608
	s_waitcnt lgkmcnt(0)
	v_lshlrev_b32_e32 v3, 16, v3
	v_mul_f32_e32 v48, 0xbfb8aa3b, v3
	v_exp_f32_e32 v48, v48
	v_mul_f32_e32 v47, v120, v44
	v_add_f32_e32 v48, 1.0, v48
	v_rcp_f32_e32 v49, v48
	v_mul_f32_e32 v47, v47, v234
	v_mul_f32_e32 v3, v3, v49
	v_mul_f32_e32 v3, v47, v3
	v_cvt_pk_bf16_f32 v3, v3, v3
	ds_write_b16 v1, v3 offset:608
	ds_read_u16 v3, v1 offset:880
	s_waitcnt lgkmcnt(0)
	v_lshlrev_b32_e32 v3, 16, v3
	v_mul_f32_e32 v48, 0xbfb8aa3b, v3
	v_exp_f32_e32 v48, v48
	v_mul_f32_e32 v47, v119, v43
	v_add_f32_e32 v48, 1.0, v48
	v_rcp_f32_e32 v49, v48
	v_mul_f32_e32 v47, v47, v234
	v_mul_f32_e32 v3, v3, v49
	v_mul_f32_e32 v3, v47, v3
	v_cvt_pk_bf16_f32 v3, v3, v3
	ds_write_b16 v1, v3 offset:880
	ds_read_u16 v3, v1 offset:2240
	s_waitcnt lgkmcnt(0)
	v_lshlrev_b32_e32 v3, 16, v3
	v_mul_f32_e32 v48, 0xbfb8aa3b, v3
	v_exp_f32_e32 v48, v48
	v_mul_f32_e32 v47, v118, v42
	v_add_f32_e32 v48, 1.0, v48
	v_rcp_f32_e32 v49, v48
	v_mul_f32_e32 v47, v47, v234
	v_mul_f32_e32 v3, v3, v49
	v_mul_f32_e32 v3, v47, v3
	v_cvt_pk_bf16_f32 v3, v3, v3
	ds_write_b16 v1, v3 offset:2240
	ds_read_u16 v3, v1 offset:2512
	s_waitcnt lgkmcnt(0)
; #define LAS __attribute__((address_space(3)))
; DI unsigned cvtpk(float lo, float hi) { f32x2 v = {lo, hi}; bf16x2_t b = __builtin_convertvector(v, bf16x2_t); return __builtin_bit_cast(unsigned, b); }
; DI float bf2f(bf16 b) { return __uint_as_float(((unsigned)b) << 16); }
; DI float siluf_(float x) { return x / (1.f + __expf(-x)); }
; DI void gla_stage3(const Ctx& c0, int layer, int unit, int cb, LAS unsigned char* lds) {
;     ...
;     for (int vb = 0; vb < 4; ++vb) { const float g = gn[32 * vb + r];
; #pragma unroll
;         for (int rg = 0; rg < 16; ++rg) { LAS bf16* e = (LAS bf16*)(R + (4 * hi) * G3_PITCH + r * 2 + ((rg & 3) + 8 * (rg >> 2)) * G3_PITCH + 64 * vb);
;             const float z = bf2f(*e);
;             *e = (bf16)(cvtpk(o[vb][rg] * rs[rg] * g * siluf_(z), 0.f) & 0xffffu); }
	v_lshlrev_b32_e32 v3, 16, v3
	v_mul_f32_e32 v48, 0xbfb8aa3b, v3
	v_exp_f32_e32 v48, v48
	v_mul_f32_e32 v47, v117, v41
	v_add_f32_e32 v48, 1.0, v48
	v_rcp_f32_e32 v49, v48
	v_mul_f32_e32 v47, v47, v234
	v_mul_f32_e32 v3, v3, v49
	v_mul_f32_e32 v3, v47, v3
	v_cvt_pk_bf16_f32 v3, v3, v3
	ds_write_b16 v1, v3 offset:2512
	ds_read_u16 v3, v1 offset:2784
	s_waitcnt lgkmcnt(0)
	v_lshlrev_b32_e32 v3, 16, v3
	v_mul_f32_e32 v48, 0xbfb8aa3b, v3
	v_exp_f32_e32 v48, v48
	v_mul_f32_e32 v47, v116, v40
	v_add_f32_e32 v48, 1.0, v48
	v_rcp_f32_e32 v49, v48
	v_mul_f32_e32 v47, v47, v234
	v_mul_f32_e32 v3, v3, v49
	v_mul_f32_e32 v3, v47, v3
	v_cvt_pk_bf16_f32 v3, v3, v3
	ds_write_b16 v1, v3 offset:2784
	ds_read_u16 v3, v1 offset:3056
	s_waitcnt lgkmcnt(0)
	v_lshlrev_b32_e32 v3, 16, v3
	v_mul_f32_e32 v48, 0xbfb8aa3b, v3
	v_exp_f32_e32 v48, v48
	v_mul_f32_e32 v47, v115, v35
	v_add_f32_e32 v48, 1.0, v48
	v_rcp_f32_e32 v49, v48
	v_mul_f32_e32 v47, v47, v234
	v_mul_f32_e32 v3, v3, v49
	v_mul_f32_e32 v3, v47, v3
	v_cvt_pk_bf16_f32 v3, v3, v3
	ds_write_b16 v1, v3 offset:3056
	ds_read_u16 v3, v1 offset:4416
	s_waitcnt lgkmcnt(0)
	v_lshlrev_b32_e32 v3, 16, v3
	v_mul_f32_e32 v48, 0xbfb8aa3b, v3
	v_exp_f32_e32 v48, v48
	v_mul_f32_e32 v47, v114, v31
	v_add_f32_e32 v48, 1.0, v48
	v_rcp_f32_e32 v49, v48
	v_mul_f32_e32 v47, v47, v234
	v_mul_f32_e32 v3, v3, v49
	v_mul_f32_e32 v3, v47, v3
	v_cvt_pk_bf16_f32 v3, v3, v3
	ds_write_b16 v1, v3 offset:4416
	ds_read_u16 v3, v1 offset:4688
	s_waitcnt lgkmcnt(0)
	v_lshlrev_b32_e32 v3, 16, v3
	v_mul_f32_e32 v48, 0xbfb8aa3b, v3
	v_exp_f32_e32 v48, v48
	v_mul_f32_e32 v47, v113, v27
	v_add_f32_e32 v48, 1.0, v48
	v_rcp_f32_e32 v49, v48
	v_mul_f32_e32 v47, v47, v234
	v_mul_f32_e32 v3, v3, v49
	v_mul_f32_e32 v3, v47, v3
	v_cvt_pk_bf16_f32 v3, v3, v3
	ds_write_b16 v1, v3 offset:4688
	ds_read_u16 v3, v1 offset:4960
	s_waitcnt lgkmcnt(0)
	v_lshlrev_b32_e32 v3, 16, v3
	v_mul_f32_e32 v48, 0xbfb8aa3b, v3
	v_exp_f32_e32 v48, v48
	v_mul_f32_e32 v47, v112, v25
	v_add_f32_e32 v48, 1.0, v48
	v_rcp_f32_e32 v49, v48
	v_mul_f32_e32 v47, v47, v234
	v_mul_f32_e32 v3, v3, v49
	v_mul_f32_e32 v3, v47, v3
	v_cvt_pk_bf16_f32 v3, v3, v3
	ds_write_b16 v1, v3 offset:4960
	ds_read_u16 v3, v1 offset:5232
	s_waitcnt lgkmcnt(0)
	v_lshlrev_b32_e32 v3, 16, v3
	v_mul_f32_e32 v48, 0xbfb8aa3b, v3
	v_exp_f32_e32 v48, v48
	v_mul_f32_e32 v47, v111, v24
	v_add_f32_e32 v48, 1.0, v48
	v_rcp_f32_e32 v49, v48
	v_mul_f32_e32 v47, v47, v234
	v_mul_f32_e32 v3, v3, v49
	v_mul_f32_e32 v3, v47, v3
	v_cvt_pk_bf16_f32 v3, v3, v3
	ds_write_b16 v1, v3 offset:5232
	ds_read_u16 v3, v1 offset:6592
	s_waitcnt lgkmcnt(0)
	v_lshlrev_b32_e32 v3, 16, v3
	v_mul_f32_e32 v48, 0xbfb8aa3b, v3
	v_exp_f32_e32 v48, v48
	v_mul_f32_e32 v47, v110, v23
	v_add_f32_e32 v48, 1.0, v48
	v_rcp_f32_e32 v49, v48
	v_mul_f32_e32 v47, v47, v234
	v_mul_f32_e32 v3, v3, v49
	v_mul_f32_e32 v3, v47, v3
	v_cvt_pk_bf16_f32 v3, v3, v3
	ds_write_b16 v1, v3 offset:6592
	ds_read_u16 v3, v1 offset:6864
	s_waitcnt lgkmcnt(0)
	v_lshlrev_b32_e32 v3, 16, v3
	v_mul_f32_e32 v48, 0xbfb8aa3b, v3
	v_exp_f32_e32 v48, v48
	v_mul_f32_e32 v47, v109, v22
	v_add_f32_e32 v48, 1.0, v48
	v_rcp_f32_e32 v49, v48
	v_mul_f32_e32 v47, v47, v234
	v_mul_f32_e32 v3, v3, v49
	v_mul_f32_e32 v3, v47, v3
	v_cvt_pk_bf16_f32 v3, v3, v3
	ds_write_b16 v1, v3 offset:6864
	ds_read_u16 v3, v1 offset:7136
	s_waitcnt lgkmcnt(0)
	v_lshlrev_b32_e32 v3, 16, v3
	v_mul_f32_e32 v48, 0xbfb8aa3b, v3
	v_exp_f32_e32 v48, v48
	v_mul_f32_e32 v47, v108, v21
	v_add_f32_e32 v48, 1.0, v48
	v_rcp_f32_e32 v49, v48
	v_mul_f32_e32 v47, v47, v234
	v_mul_f32_e32 v3, v3, v49
	v_mul_f32_e32 v3, v47, v3
	v_cvt_pk_bf16_f32 v3, v3, v3
	ds_write_b16 v1, v3 offset:7136
	ds_read_u16 v3, v1 offset:7408
	v_mul_f32_e32 v47, v107, v20
	v_mul_f32_e32 v2, v47, v234
	s_waitcnt lgkmcnt(0)
	v_lshlrev_b32_e32 v3, 16, v3
	v_mul_f32_e32 v47, 0xbfb8aa3b, v3
	v_exp_f32_e32 v47, v47
	s_nop 0
	v_add_f32_e32 v47, 1.0, v47
	v_div_scale_f32 v48, s[0:1], v47, v47, v3
	s_nop 0
	v_rcp_f32_e32 v48, v47
	s_nop 0
	v_mul_f32_e32 v3, v3, v48
	v_mul_f32_e32 v2, v2, v3
	v_cvt_pk_bf16_f32 v2, v2, s0
	ds_write_b16 v1, v2 offset:7408
	ds_read_u16 v3, v1 offset:128
	v_mul_f32_e32 v47, v106, v46
	s_waitcnt lgkmcnt(0)
	v_lshlrev_b32_e32 v3, 16, v3
	v_mul_f32_e32 v48, 0xbfb8aa3b, v3
	v_exp_f32_e32 v48, v48
	s_waitcnt vmcnt(0)
	v_mul_f32_e32 v47, v47, v236
	v_add_f32_e32 v48, 1.0, v48
	v_div_scale_f32 v49, s[0:1], v48, v48, v3
	v_mul_f32_e32 v39, v39, v236
	v_mul_f32_e32 v38, v38, v236
	v_mul_f32_e32 v37, v37, v236
	v_rcp_f32_e32 v49, v48
	s_nop 0
	v_mul_f32_e32 v3, v3, v49
	v_mul_f32_e32 v3, v47, v3
	v_cvt_pk_bf16_f32 v3, v3, s0
	ds_write_b16 v1, v3 offset:128
	ds_read_u16 v3, v1 offset:400
	v_mul_f32_e32 v47, v105, v45
	v_mul_f32_e32 v47, v47, v236
	v_mul_f32_e32 v36, v36, v236
	v_mul_f32_e32 v34, v34, v236
	s_waitcnt lgkmcnt(0)
	v_lshlrev_b32_e32 v3, 16, v3
	v_mul_f32_e32 v48, 0xbfb8aa3b, v3
	v_exp_f32_e32 v48, v48
	v_mul_f32_e32 v33, v33, v236
	v_mul_f32_e32 v32, v32, v236
	v_mul_f32_e32 v30, v30, v236
	v_add_f32_e32 v48, 1.0, v48
	v_div_scale_f32 v49, s[0:1], v48, v48, v3
	v_mul_f32_e32 v29, v29, v236
	v_mul_f32_e32 v28, v28, v236
	v_rcp_f32_e32 v49, v48
	s_nop 0
	v_mul_f32_e32 v3, v3, v49
	v_mul_f32_e32 v3, v47, v3
	v_cvt_pk_bf16_f32 v3, v3, s0
	ds_write_b16 v1, v3 offset:400
	ds_read_u16 v3, v1 offset:672
	s_waitcnt lgkmcnt(0)
	v_lshlrev_b32_e32 v3, 16, v3
	v_mul_f32_e32 v48, 0xbfb8aa3b, v3
	v_exp_f32_e32 v48, v48
	v_mul_f32_e32 v47, v104, v44
	v_add_f32_e32 v48, 1.0, v48
	v_rcp_f32_e32 v49, v48
	v_mul_f32_e32 v47, v47, v236
	v_mul_f32_e32 v3, v3, v49
	v_mul_f32_e32 v3, v47, v3
	v_cvt_pk_bf16_f32 v3, v3, v3
	ds_write_b16 v1, v3 offset:672
	ds_read_u16 v3, v1 offset:944
	s_waitcnt lgkmcnt(0)
; #define LAS __attribute__((address_space(3)))
; DI unsigned cvtpk(float lo, float hi) { f32x2 v = {lo, hi}; bf16x2_t b = __builtin_convertvector(v, bf16x2_t); return __builtin_bit_cast(unsigned, b); }
; DI float bf2f(bf16 b) { return __uint_as_float(((unsigned)b) << 16); }
; DI float siluf_(float x) { return x / (1.f + __expf(-x)); }
; DI void gla_stage3(const Ctx& c0, int layer, int unit, int cb, LAS unsigned char* lds) {
;     ...
;     for (int vb = 0; vb < 4; ++vb) { const float g = gn[32 * vb + r];
; #pragma unroll
;         for (int rg = 0; rg < 16; ++rg) { LAS bf16* e = (LAS bf16*)(R + (4 * hi) * G3_PITCH + r * 2 + ((rg & 3) + 8 * (rg >> 2)) * G3_PITCH + 64 * vb);
;             const float z = bf2f(*e);
;             *e = (bf16)(cvtpk(o[vb][rg] * rs[rg] * g * siluf_(z), 0.f) & 0xffffu); }
	v_lshlrev_b32_e32 v3, 16, v3
	v_mul_f32_e32 v48, 0xbfb8aa3b, v3
	v_exp_f32_e32 v48, v48
	v_mul_f32_e32 v47, v103, v43
	v_add_f32_e32 v48, 1.0, v48
	v_rcp_f32_e32 v49, v48
	v_mul_f32_e32 v47, v47, v236
	v_mul_f32_e32 v3, v3, v49
	v_mul_f32_e32 v3, v47, v3
	v_cvt_pk_bf16_f32 v3, v3, v3
	ds_write_b16 v1, v3 offset:944
	ds_read_u16 v3, v1 offset:2304
	v_mul_f32_e32 v47, v102, v42
	v_mul_f32_e32 v47, v47, v236
	v_mul_f32_e32 v2, v26, v236
	s_waitcnt lgkmcnt(0)
	v_lshlrev_b32_e32 v3, 16, v3
	v_mul_f32_e32 v48, 0xbfb8aa3b, v3
	v_exp_f32_e32 v48, v48
	s_nop 0
	v_add_f32_e32 v48, 1.0, v48
	v_rcp_f32_e32 v49, v48
	s_nop 0
	v_mul_f32_e32 v3, v3, v49
	v_mul_f32_e32 v3, v47, v3
	v_cvt_pk_bf16_f32 v3, v3, v3
	ds_write_b16 v1, v3 offset:2304
	ds_read_u16 v3, v1 offset:2576
	s_waitcnt lgkmcnt(0)
	v_lshlrev_b32_e32 v3, 16, v3
	v_mul_f32_e32 v47, 0xbfb8aa3b, v3
	v_exp_f32_e32 v47, v47
	s_nop 0
	v_add_f32_e32 v47, 1.0, v47
	v_rcp_f32_e32 v48, v47
	s_nop 0
	v_mul_f32_e32 v3, v3, v48
	v_mul_f32_e32 v3, v39, v3
	v_cvt_pk_bf16_f32 v3, v3, v3
	ds_write_b16 v1, v3 offset:2576
	ds_read_u16 v3, v1 offset:2848
	s_waitcnt lgkmcnt(0)
	v_lshlrev_b32_e32 v3, 16, v3
	v_mul_f32_e32 v39, 0xbfb8aa3b, v3
	v_exp_f32_e32 v39, v39
	s_nop 0
	v_add_f32_e32 v39, 1.0, v39
	v_rcp_f32_e32 v47, v39
	s_nop 0
	v_mul_f32_e32 v3, v3, v47
	v_mul_f32_e32 v3, v38, v3
	v_cvt_pk_bf16_f32 v3, v3, v3
	ds_write_b16 v1, v3 offset:2848
	ds_read_u16 v3, v1 offset:3120
	s_waitcnt lgkmcnt(0)
	v_lshlrev_b32_e32 v3, 16, v3
	v_mul_f32_e32 v38, 0xbfb8aa3b, v3
	v_exp_f32_e32 v38, v38
	s_nop 0
	v_add_f32_e32 v38, 1.0, v38
	v_rcp_f32_e32 v39, v38
	s_nop 0
	v_mul_f32_e32 v3, v3, v39
	v_mul_f32_e32 v3, v37, v3
	v_cvt_pk_bf16_f32 v3, v3, v3
	ds_write_b16 v1, v3 offset:3120
	ds_read_u16 v3, v1 offset:4480
	s_waitcnt lgkmcnt(0)
	v_lshlrev_b32_e32 v3, 16, v3
	v_mul_f32_e32 v37, 0xbfb8aa3b, v3
	v_exp_f32_e32 v37, v37
	s_nop 0
	v_add_f32_e32 v37, 1.0, v37
	v_rcp_f32_e32 v38, v37
	s_nop 0
	v_mul_f32_e32 v3, v3, v38
	v_mul_f32_e32 v3, v36, v3
	v_cvt_pk_bf16_f32 v3, v3, v3
	ds_write_b16 v1, v3 offset:4480
	ds_read_u16 v3, v1 offset:4752
	s_waitcnt lgkmcnt(0)
	v_lshlrev_b32_e32 v3, 16, v3
	v_mul_f32_e32 v36, 0xbfb8aa3b, v3
	v_exp_f32_e32 v36, v36
	s_nop 0
	v_add_f32_e32 v36, 1.0, v36
	v_rcp_f32_e32 v37, v36
	s_nop 0
	v_mul_f32_e32 v3, v3, v37
	v_mul_f32_e32 v3, v34, v3
	v_cvt_pk_bf16_f32 v3, v3, v3
	ds_write_b16 v1, v3 offset:4752
	ds_read_u16 v3, v1 offset:5024
	s_waitcnt lgkmcnt(0)
	v_lshlrev_b32_e32 v3, 16, v3
	v_mul_f32_e32 v34, 0xbfb8aa3b, v3
	v_exp_f32_e32 v34, v34
	s_nop 0
	v_add_f32_e32 v34, 1.0, v34
	v_rcp_f32_e32 v36, v34
	s_nop 0
	v_mul_f32_e32 v3, v3, v36
	v_mul_f32_e32 v3, v33, v3
	v_cvt_pk_bf16_f32 v3, v3, v3
	ds_write_b16 v1, v3 offset:5024
	ds_read_u16 v3, v1 offset:5296
	s_waitcnt lgkmcnt(0)
	v_lshlrev_b32_e32 v3, 16, v3
	v_mul_f32_e32 v33, 0xbfb8aa3b, v3
	v_exp_f32_e32 v33, v33
	s_nop 0
	v_add_f32_e32 v33, 1.0, v33
	v_rcp_f32_e32 v34, v33
	s_nop 0
	v_mul_f32_e32 v3, v3, v34
	v_mul_f32_e32 v3, v32, v3
	v_cvt_pk_bf16_f32 v3, v3, v3
	ds_write_b16 v1, v3 offset:5296
	ds_read_u16 v3, v1 offset:6656
	s_waitcnt lgkmcnt(0)
	v_lshlrev_b32_e32 v3, 16, v3
	v_mul_f32_e32 v32, 0xbfb8aa3b, v3
	v_exp_f32_e32 v32, v32
	s_nop 0
	v_add_f32_e32 v32, 1.0, v32
	v_rcp_f32_e32 v33, v32
	s_nop 0
	v_mul_f32_e32 v3, v3, v33
	v_mul_f32_e32 v3, v30, v3
	v_cvt_pk_bf16_f32 v3, v3, v3
	ds_write_b16 v1, v3 offset:6656
	ds_read_u16 v3, v1 offset:6928
	s_waitcnt lgkmcnt(0)
	v_lshlrev_b32_e32 v3, 16, v3
	v_mul_f32_e32 v30, 0xbfb8aa3b, v3
	v_exp_f32_e32 v30, v30
	s_nop 0
	v_add_f32_e32 v30, 1.0, v30
	v_rcp_f32_e32 v32, v30
	s_nop 0
	v_mul_f32_e32 v3, v3, v32
	v_mul_f32_e32 v3, v29, v3
	v_cvt_pk_bf16_f32 v3, v3, v3
	ds_write_b16 v1, v3 offset:6928
	ds_read_u16 v3, v1 offset:7200
	s_waitcnt lgkmcnt(0)
	v_lshlrev_b32_e32 v3, 16, v3
	v_mul_f32_e32 v29, 0xbfb8aa3b, v3
	v_exp_f32_e32 v29, v29
	s_nop 0
	v_add_f32_e32 v29, 1.0, v29
	v_rcp_f32_e32 v30, v29
	s_nop 0
	v_mul_f32_e32 v3, v3, v30
	v_mul_f32_e32 v3, v28, v3
	v_cvt_pk_bf16_f32 v3, v3, v3
	ds_write_b16 v1, v3 offset:7200
	ds_read_u16 v3, v1 offset:7472
	s_waitcnt lgkmcnt(0)
	v_lshlrev_b32_e32 v3, 16, v3
	v_mul_f32_e32 v26, 0xbfb8aa3b, v3
	v_exp_f32_e32 v26, v26
	s_nop 0
	v_add_f32_e32 v26, 1.0, v26
	v_div_scale_f32 v28, s[0:1], v26, v26, v3
	s_nop 0
	v_rcp_f32_e32 v28, v26
	s_nop 0
	v_mul_f32_e32 v3, v3, v28
	v_mul_f32_e32 v2, v2, v3
	v_cvt_pk_bf16_f32 v2, v2, s0
	ds_write_b16 v1, v2 offset:7472
	ds_read_u16 v3, v1 offset:192
	s_waitcnt lgkmcnt(0)
	v_lshlrev_b32_e32 v3, 16, v3
	v_mul_f32_e32 v26, 0xbfb8aa3b, v3
	v_exp_f32_e32 v26, v26
	s_waitcnt vmcnt(31)
	v_mul_f32_e32 v19, v19, v238
	v_add_f32_e32 v26, 1.0, v26
	v_div_scale_f32 v28, s[0:1], v26, v26, v3
	v_mul_f32_e32 v18, v18, v238
	v_mul_f32_e32 v17, v17, v238
	v_mul_f32_e32 v16, v16, v238
	v_rcp_f32_e32 v28, v26
	s_nop 0
	v_mul_f32_e32 v3, v3, v28
	v_mul_f32_e32 v3, v19, v3
	v_cvt_pk_bf16_f32 v3, v3, s0
	ds_write_b16 v1, v3 offset:192
	ds_read_u16 v3, v1 offset:464
	v_mul_f32_e32 v15, v15, v238
	v_mul_f32_e32 v14, v14, v238
	v_mul_f32_e32 v13, v13, v238
	v_mul_f32_e32 v12, v12, v238
	s_waitcnt lgkmcnt(0)
	v_lshlrev_b32_e32 v3, 16, v3
	v_mul_f32_e32 v19, 0xbfb8aa3b, v3
	v_exp_f32_e32 v19, v19
	v_mul_f32_e32 v11, v11, v238
	v_mul_f32_e32 v10, v10, v238
	v_mul_f32_e32 v9, v9, v238
	v_add_f32_e32 v19, 1.0, v19
	v_div_scale_f32 v26, s[0:1], v19, v19, v3
	v_mul_f32_e32 v8, v8, v238
	v_mul_f32_e32 v7, v7, v238
	v_mul_f32_e32 v6, v6, v238
	v_rcp_f32_e32 v26, v19
	s_nop 0
	v_mul_f32_e32 v3, v3, v26
	v_mul_f32_e32 v3, v18, v3
	v_cvt_pk_bf16_f32 v3, v3, s0
	ds_write_b16 v1, v3 offset:464
	ds_read_u16 v3, v1 offset:736
	v_mul_f32_e32 v5, v5, v238
	v_mul_f32_e32 v2, v4, v238
	s_waitcnt lgkmcnt(0)
; #define LAS __attribute__((address_space(3)))
; #define LDS_WAIT() asm volatile("s_waitcnt lgkmcnt(0)" ::: "memory")
; DI unsigned cvtpk(float lo, float hi) { f32x2 v = {lo, hi}; bf16x2_t b = __builtin_convertvector(v, bf16x2_t); return __builtin_bit_cast(unsigned, b); }
; DI float bf2f(bf16 b) { return __uint_as_float(((unsigned)b) << 16); }
; DI float siluf_(float x) { return x / (1.f + __expf(-x)); }
; DI void g3_tile_out(bf16* g, const LAS unsigned char* R, int lane) {
;     LDS_WAIT();
; #pragma unroll
;     for (int it = 0; it < 8; ++it) { const int row = 4 * it + (lane >> 4), ch = lane & 15;
;         *(u32x4*)(g + (size_t)row * 512 + ch * 8) = *(const LAS u32x4*)(R + row * G3_PITCH + ch * 16); }
;     LDS_WAIT();
; }
; DI void gla_stage3(const Ctx& c0, int layer, int unit, int cb, LAS unsigned char* lds) {
;     ...
;     for (int vb = 0; vb < 4; ++vb) { const float g = gn[32 * vb + r];
; #pragma unroll
;         for (int rg = 0; rg < 16; ++rg) { LAS bf16* e = (LAS bf16*)(R + (4 * hi) * G3_PITCH + r * 2 + ((rg & 3) + 8 * (rg >> 2)) * G3_PITCH + 64 * vb);
;             const float z = bf2f(*e);
;             *e = (bf16)(cvtpk(o[vb][rg] * rs[rg] * g * siluf_(z), 0.f) & 0xffffu); }
;         asm volatile("" ::: "memory"); }
;     g3_tile_out((bf16*)(c.ws + O_OGLA) + row0 * 512 + h * 128, R, lane);
	v_lshlrev_b32_e32 v3, 16, v3
	v_mul_f32_e32 v18, 0xbfb8aa3b, v3
	v_exp_f32_e32 v18, v18
	s_nop 0
	v_add_f32_e32 v18, 1.0, v18
	v_rcp_f32_e32 v19, v18
	s_nop 0
	v_mul_f32_e32 v3, v3, v19
	v_mul_f32_e32 v3, v17, v3
	v_cvt_pk_bf16_f32 v3, v3, v3
	ds_write_b16 v1, v3 offset:736
	ds_read_u16 v3, v1 offset:1008
	s_waitcnt lgkmcnt(0)
	v_lshlrev_b32_e32 v3, 16, v3
	v_mul_f32_e32 v17, 0xbfb8aa3b, v3
	v_exp_f32_e32 v17, v17
	s_nop 0
	v_add_f32_e32 v17, 1.0, v17
	v_rcp_f32_e32 v18, v17
	s_nop 0
	v_mul_f32_e32 v3, v3, v18
	v_mul_f32_e32 v3, v16, v3
	v_cvt_pk_bf16_f32 v3, v3, v3
	ds_write_b16 v1, v3 offset:1008
	ds_read_u16 v3, v1 offset:2368
	s_waitcnt lgkmcnt(0)
	v_lshlrev_b32_e32 v3, 16, v3
	v_mul_f32_e32 v16, 0xbfb8aa3b, v3
	v_exp_f32_e32 v16, v16
	s_nop 0
	v_add_f32_e32 v16, 1.0, v16
	v_rcp_f32_e32 v17, v16
	s_nop 0
	v_mul_f32_e32 v3, v3, v17
	v_mul_f32_e32 v3, v15, v3
	v_cvt_pk_bf16_f32 v3, v3, v3
	ds_write_b16 v1, v3 offset:2368
	ds_read_u16 v3, v1 offset:2640
	s_waitcnt lgkmcnt(0)
	v_lshlrev_b32_e32 v3, 16, v3
	v_mul_f32_e32 v15, 0xbfb8aa3b, v3
	v_exp_f32_e32 v15, v15
	s_nop 0
	v_add_f32_e32 v15, 1.0, v15
	v_rcp_f32_e32 v16, v15
	s_nop 0
	v_mul_f32_e32 v3, v3, v16
	v_mul_f32_e32 v3, v14, v3
	v_cvt_pk_bf16_f32 v3, v3, v3
	ds_write_b16 v1, v3 offset:2640
	ds_read_u16 v3, v1 offset:2912
	s_waitcnt lgkmcnt(0)
	v_lshlrev_b32_e32 v3, 16, v3
	v_mul_f32_e32 v14, 0xbfb8aa3b, v3
	v_exp_f32_e32 v14, v14
	s_nop 0
	v_add_f32_e32 v14, 1.0, v14
	v_rcp_f32_e32 v15, v14
	s_nop 0
	v_mul_f32_e32 v3, v3, v15
	v_mul_f32_e32 v3, v13, v3
	v_cvt_pk_bf16_f32 v3, v3, v3
	ds_write_b16 v1, v3 offset:2912
	ds_read_u16 v3, v1 offset:3184
	s_waitcnt lgkmcnt(0)
	v_lshlrev_b32_e32 v3, 16, v3
	v_mul_f32_e32 v13, 0xbfb8aa3b, v3
	v_exp_f32_e32 v13, v13
	s_nop 0
	v_add_f32_e32 v13, 1.0, v13
	v_rcp_f32_e32 v14, v13
	s_nop 0
	v_mul_f32_e32 v3, v3, v14
	v_mul_f32_e32 v3, v12, v3
	v_cvt_pk_bf16_f32 v3, v3, v3
	ds_write_b16 v1, v3 offset:3184
	ds_read_u16 v3, v1 offset:4544
	s_waitcnt lgkmcnt(0)
	v_lshlrev_b32_e32 v3, 16, v3
	v_mul_f32_e32 v12, 0xbfb8aa3b, v3
	v_exp_f32_e32 v12, v12
	s_nop 0
	v_add_f32_e32 v12, 1.0, v12
	v_rcp_f32_e32 v13, v12
	s_nop 0
	v_mul_f32_e32 v3, v3, v13
	v_mul_f32_e32 v3, v11, v3
	v_cvt_pk_bf16_f32 v3, v3, v3
	ds_write_b16 v1, v3 offset:4544
	ds_read_u16 v3, v1 offset:4816
	s_waitcnt lgkmcnt(0)
	v_lshlrev_b32_e32 v3, 16, v3
	v_mul_f32_e32 v11, 0xbfb8aa3b, v3
	v_exp_f32_e32 v11, v11
	s_nop 0
	v_add_f32_e32 v11, 1.0, v11
	v_rcp_f32_e32 v12, v11
	s_nop 0
	v_mul_f32_e32 v3, v3, v12
	v_mul_f32_e32 v3, v10, v3
	v_cvt_pk_bf16_f32 v3, v3, v3
	ds_write_b16 v1, v3 offset:4816
	ds_read_u16 v3, v1 offset:5088
	s_waitcnt lgkmcnt(0)
	v_lshlrev_b32_e32 v3, 16, v3
	v_mul_f32_e32 v10, 0xbfb8aa3b, v3
	v_exp_f32_e32 v10, v10
	s_nop 0
	v_add_f32_e32 v10, 1.0, v10
	v_rcp_f32_e32 v11, v10
	s_nop 0
	v_mul_f32_e32 v3, v3, v11
	v_mul_f32_e32 v3, v9, v3
	v_cvt_pk_bf16_f32 v3, v3, v3
	ds_write_b16 v1, v3 offset:5088
	ds_read_u16 v3, v1 offset:5360
	s_waitcnt lgkmcnt(0)
	v_lshlrev_b32_e32 v3, 16, v3
	v_mul_f32_e32 v9, 0xbfb8aa3b, v3
	v_exp_f32_e32 v9, v9
	s_nop 0
	v_add_f32_e32 v9, 1.0, v9
	v_rcp_f32_e32 v10, v9
	s_nop 0
	v_mul_f32_e32 v3, v3, v10
	v_mul_f32_e32 v3, v8, v3
	v_cvt_pk_bf16_f32 v3, v3, v3
	ds_write_b16 v1, v3 offset:5360
	ds_read_u16 v3, v1 offset:6720
	s_waitcnt lgkmcnt(0)
	v_lshlrev_b32_e32 v3, 16, v3
	v_mul_f32_e32 v8, 0xbfb8aa3b, v3
	v_exp_f32_e32 v8, v8
	s_nop 0
	v_add_f32_e32 v8, 1.0, v8
	v_rcp_f32_e32 v9, v8
	s_nop 0
	v_mul_f32_e32 v3, v3, v9
	v_mul_f32_e32 v3, v7, v3
	v_cvt_pk_bf16_f32 v3, v3, v3
	ds_write_b16 v1, v3 offset:6720
	ds_read_u16 v3, v1 offset:6992
	s_waitcnt lgkmcnt(0)
	v_lshlrev_b32_e32 v3, 16, v3
	v_mul_f32_e32 v7, 0xbfb8aa3b, v3
	v_exp_f32_e32 v7, v7
	s_nop 0
	v_add_f32_e32 v7, 1.0, v7
	v_rcp_f32_e32 v8, v7
	s_nop 0
	v_mul_f32_e32 v3, v3, v8
	v_mul_f32_e32 v3, v6, v3
	v_cvt_pk_bf16_f32 v3, v3, v3
	ds_write_b16 v1, v3 offset:6992
	ds_read_u16 v3, v1 offset:7264
	s_waitcnt lgkmcnt(0)
	v_lshlrev_b32_e32 v3, 16, v3
	v_mul_f32_e32 v6, 0xbfb8aa3b, v3
	v_exp_f32_e32 v6, v6
	s_nop 0
	v_add_f32_e32 v6, 1.0, v6
	v_rcp_f32_e32 v7, v6
	s_nop 0
	v_mul_f32_e32 v3, v3, v7
	v_mul_f32_e32 v3, v5, v3
	v_cvt_pk_bf16_f32 v3, v3, v3
	ds_write_b16 v1, v3 offset:7264
	ds_read_u16 v3, v1 offset:7536
	s_waitcnt lgkmcnt(0)
	v_lshlrev_b32_e32 v3, 16, v3
	v_mul_f32_e32 v4, 0xbfb8aa3b, v3
	v_exp_f32_e32 v4, v4
	s_nop 0
	v_add_f32_e32 v4, 1.0, v4
	v_div_scale_f32 v5, s[0:1], v4, v4, v3
	s_nop 0
	v_rcp_f32_e32 v5, v4
	s_nop 0
	v_mul_f32_e32 v3, v3, v5
	v_mul_f32_e32 v2, v2, v3
	v_cvt_pk_bf16_f32 v2, v2, s0
	ds_write_b16 v1, v2 offset:7536
	s_waitcnt lgkmcnt(0)
	ds_read_b128 v[2:5], v92
	v_lshl_add_u64 v[6:7], v[90:91], 0, s[22:23]
	v_lshl_add_u64 v[8:9], v[6:7], 0, v[66:67]
	s_waitcnt lgkmcnt(0)
	global_store_dwordx4 v[8:9], v[2:5], off
	ds_read_b128 v[2:5], v92 offset:1088
	v_lshl_add_u64 v[8:9], v[6:7], 0, v[68:69]
	s_waitcnt lgkmcnt(0)
	global_store_dwordx4 v[8:9], v[2:5], off
	ds_read_b128 v[2:5], v92 offset:2176
	v_lshl_add_u64 v[8:9], v[6:7], 0, v[70:71]
	s_waitcnt lgkmcnt(0)
	global_store_dwordx4 v[8:9], v[2:5], off
	ds_read_b128 v[2:5], v92 offset:3264
	v_lshl_add_u64 v[8:9], v[6:7], 0, v[72:73]
	s_waitcnt lgkmcnt(0)
	global_store_dwordx4 v[8:9], v[2:5], off
	ds_read_b128 v[2:5], v92 offset:4352
	v_lshl_add_u64 v[8:9], v[6:7], 0, v[74:75]
	s_waitcnt lgkmcnt(0)
	global_store_dwordx4 v[8:9], v[2:5], off
	ds_read_b128 v[2:5], v92 offset:5440
	v_lshl_add_u64 v[8:9], v[6:7], 0, v[76:77]
	s_waitcnt lgkmcnt(0)
	global_store_dwordx4 v[8:9], v[2:5], off
	ds_read_b128 v[2:5], v92 offset:6528
	v_lshl_add_u64 v[8:9], v[6:7], 0, v[78:79]
	v_lshl_add_u64 v[6:7], v[6:7], 0, v[80:81]
	s_waitcnt lgkmcnt(0)
	global_store_dwordx4 v[8:9], v[2:5], off
	ds_read_b128 v[2:5], v92 offset:7616
	s_waitcnt lgkmcnt(0)
	global_store_dwordx4 v[6:7], v[2:5], off
	s_waitcnt lgkmcnt(0)
	s_cbranch_scc1 .LBB0_604

; #define LAS __attribute__((address_space(3)))
; #define MFMA32(a, b, c) __builtin_amdgcn_mfma_f32_32x32x16_bf16((a), (b), (c), 0, 0, 0)
; DI Ctx launder(const Ctx& c0) { Ctx c = c0; asm volatile("" : "+s"(c.ws), "+s"(c.out), "+v"(c.tid)); return c; }
; DI void gla_stage3(const Ctx& c0, int layer, int unit, int cb, LAS unsigned char* lds) {
;     const Ctx c = launder(c0);
;     const int lane = c.lane, r = lane & 31, hi = lane >> 5;
;     const int bh = unit >> 6, n = unit & 63, b = bh >> 2, h = bh & 3;
;     const size_t row0 = (size_t)b * SEQ + n * 64 + 32 * cb;
;     LAS unsigned char* R = lds + c.wid * G3_BYTES;
;     const LAS unsigned char* Re = R + (4 * hi) * G3_PITCH + r * 2;
;     const bf16* qgp = (const bf16*)(c.ws + O_QG) + (row0 + r) * 256 + h * 64 + 8 * hi;
;     const float* sp = (const float*)(c.ws + O_UPD) + (size_t)unit * 8192;
;     const float* gn = c.a->in[I_GNORM] + (size_t)layer * 128;
;     bf16x8 qf[4];
; #pragma unroll
;     for (int s = 0; s < 4; ++s) qf[s] = *(const bf16x8*)(qgp + 16 * s);
;     f32x16 o[4];
; #pragma unroll
;     for (int vb = 0; vb < 4; ++vb) {
;         o[vb] = f32x16{};
; #pragma unroll
;         for (int s = 0; s < 4; ++s) { const float* s0 = sp + (size_t)(16 * s + 8 * hi) * 128 + 32 * vb + r;
;             const bf16x8 bfv = pack8(s0[0], s0[128], s0[256], s0[384], s0[512], s0[640], s0[768], s0[896]);
;             o[vb] = MFMA32(qf[s], bfv, o[vb]); }
;         asm volatile("" ::: "memory");
;     }
.LBB0_1216:
	s_mov_b64 s[0:1], s[74:75]
	s_mov_b64 s[2:3], s[72:73]
	s_ashr_i32 s2, s34, 8
	s_ashr_i32 s3, s2, 31
	s_lshl_b64 s[2:3], s[2:3], 12
	s_and_b32 s9, s4, 0xfc0
	s_or_b32 s2, s2, s9
	s_or_b64 s[2:3], s[2:3], s[10:11]
	v_mov_b32_e32 v3, s3
	v_or_b32_e32 v2, s2, v152
	s_bfe_u32 s8, s34, 0x20006
	v_lshlrev_b64 v[2:3], 9, v[2:3]
	v_lshl_add_u64 v[2:3], s[0:1], 0, v[2:3]
	s_lshl_b32 s12, s8, 7
	v_lshl_add_u64 v[2:3], v[2:3], 0, s[12:13]
	v_lshl_add_u64 v[2:3], v[2:3], 0, v[86:87]
	v_lshl_add_u64 v[4:5], v[2:3], 0, s[18:19]
	v_add_co_u32_e32 v2, vcc, s6, v2
	v_lshl_add_u64 v[90:91], s[0:1], 0, v[84:85]
	s_nop 0
	v_addc_co_u32_e32 v3, vcc, 0, v3, vcc
	global_load_dwordx4 v[50:53], v[2:3], off
	global_load_dwordx4 v[110:113], v[4:5], off offset:96
	global_load_dwordx4 v[106:109], v[4:5], off offset:64
	global_load_dwordx4 v[102:105], v[4:5], off offset:32
	v_add_co_u32_e32 v2, vcc, s7, v90
	s_lshl_b64 s[2:3], s[2:3], 10
	s_nop 0
	v_addc_co_u32_e32 v3, vcc, -1, v91, vcc
	v_add_co_u32_e32 v58, vcc, s28, v90
	global_load_dword v2, v[2:3], off
	s_nop 0
	v_addc_co_u32_e32 v59, vcc, -1, v91, vcc
	global_load_dword v3, v[58:59], off offset:384
	global_load_dword v4, v[58:59], off offset:896
	global_load_dword v5, v[58:59], off offset:1408
	global_load_dword v6, v[58:59], off offset:1920
	global_load_dword v7, v[58:59], off offset:2432
	global_load_dword v8, v[58:59], off offset:2944
	global_load_dword v9, v[58:59], off offset:3456
	v_add_co_u32_e32 v18, vcc, s15, v90
	s_lshl_b32 s8, s8, 8
	s_nop 0
	v_addc_co_u32_e32 v19, vcc, -1, v91, vcc
	v_add_co_u32_e32 v114, vcc, s29, v90
	global_load_dword v18, v[18:19], off
	s_nop 0
	v_addc_co_u32_e32 v115, vcc, -1, v91, vcc
	global_load_dword v19, v[114:115], off offset:384
	global_load_dword v20, v[114:115], off offset:896
	global_load_dword v21, v[114:115], off offset:1408
	global_load_dword v22, v[114:115], off offset:1920
	global_load_dword v23, v[114:115], off offset:2432
	global_load_dword v24, v[114:115], off offset:2944
	global_load_dword v25, v[114:115], off offset:3456
	s_add_u32 s0, s0, s2
	s_addc_u32 s1, s1, s3
	s_add_u32 s0, s0, s8
	s_addc_u32 s1, s1, 0
	s_add_i32 s34, s34, s14
	s_add_i32 s4, s4, s5
	v_lshl_add_u64 v[84:85], v[84:85], 0, s[16:17]
	s_cmpk_lt_i32 s34, 0x800
	v_add_co_u32_e32 v26, vcc, s26, v90
	s_nop 1
	v_addc_co_u32_e32 v27, vcc, -1, v91, vcc
	v_add_co_u32_e32 v118, vcc, s30, v90
	global_load_dword v26, v[26:27], off
	s_nop 0
	v_addc_co_u32_e32 v119, vcc, -1, v91, vcc
	global_load_dword v27, v[118:119], off offset:384
	global_load_dword v28, v[118:119], off offset:896
	global_load_dword v29, v[118:119], off offset:1408
	global_load_dword v30, v[118:119], off offset:1920
	global_load_dword v31, v[118:119], off offset:2432
	global_load_dword v32, v[118:119], off offset:2944
	global_load_dword v33, v[118:119], off offset:3456
	v_add_co_u32_e32 v42, vcc, s27, v90
	s_nop 1
	v_addc_co_u32_e32 v43, vcc, -1, v91, vcc
	v_add_co_u32_e32 v120, vcc, s31, v90
	global_load_dword v42, v[42:43], off
	s_nop 0
	v_addc_co_u32_e32 v121, vcc, -1, v91, vcc
	global_load_dword v43, v[120:121], off offset:384
	global_load_dword v44, v[120:121], off offset:896
	global_load_dword v45, v[120:121], off offset:1408
	global_load_dword v46, v[120:121], off offset:1920
	global_load_dword v47, v[120:121], off offset:2432
	global_load_dword v48, v[120:121], off offset:2944
	global_load_dword v49, v[120:121], off offset:3456
	s_waitcnt vmcnt(16) lgkmcnt(0)
	global_load_dword v41, v[114:115], off offset:3584
	global_load_dword v40, v[114:115], off offset:3072
	global_load_dword v39, v[114:115], off offset:2560
	global_load_dword v38, v[114:115], off offset:2048
	global_load_dword v37, v[114:115], off offset:1536
	global_load_dword v36, v[114:115], off offset:1024
	global_load_dword v35, v[114:115], off offset:512
	global_load_dword v34, v[114:115], off
	global_load_dword v145, v[58:59], off offset:3584
	global_load_dword v146, v[58:59], off offset:3072
	global_load_dword v143, v[58:59], off offset:2560
	global_load_dword v144, v[58:59], off offset:2048
	global_load_dword v141, v[58:59], off offset:1536
	global_load_dword v142, v[58:59], off offset:1024
	global_load_dword v139, v[58:59], off offset:512
	global_load_dword v140, v[58:59], off
	v_cvt_pk_bf16_f32 v2, v2, v3
	v_cvt_pk_bf16_f32 v3, v4, v5
	v_cvt_pk_bf16_f32 v4, v6, v7
	v_cvt_pk_bf16_f32 v5, v8, v9
	v_cvt_pk_bf16_f32 v18, v18, v19
	s_nop 0
	v_mfma_f32_32x32x16_bf16 v[2:17], v[50:53], v[2:5], 0
	v_cvt_pk_bf16_f32 v19, v20, v21
	v_cvt_pk_bf16_f32 v20, v22, v23
	v_cvt_pk_bf16_f32 v21, v24, v25
	s_nop 1
	v_mfma_f32_32x32x16_bf16 v[2:17], v[102:105], v[18:21], v[2:17]
	s_waitcnt vmcnt(24) lgkmcnt(0)
	global_load_dword v63, v[114:115], off offset:3712
	global_load_dword v62, v[114:115], off offset:3200
	global_load_dword v61, v[114:115], off offset:2688
	global_load_dword v60, v[114:115], off offset:2176
	global_load_dword v57, v[114:115], off offset:1664
	global_load_dword v56, v[114:115], off offset:1152
	global_load_dword v55, v[114:115], off offset:640
	global_load_dword v54, v[114:115], off offset:128
	global_load_dword v173, v[58:59], off offset:3712
	global_load_dword v176, v[58:59], off offset:3200
	global_load_dword v171, v[58:59], off offset:2688
	global_load_dword v174, v[58:59], off offset:2176
	global_load_dword v169, v[58:59], off offset:1664
	global_load_dword v172, v[58:59], off offset:1152
	global_load_dword v167, v[58:59], off offset:640
	global_load_dword v170, v[58:59], off offset:128
	global_load_dword v157, v[118:119], off offset:3584
	global_load_dword v160, v[118:119], off offset:3072
	global_load_dword v155, v[118:119], off offset:2560
	global_load_dword v158, v[118:119], off offset:2048
	global_load_dword v149, v[118:119], off offset:1536
	global_load_dword v156, v[118:119], off offset:1024
	global_load_dword v147, v[118:119], off offset:512
	global_load_dword v148, v[118:119], off
	v_cvt_pk_bf16_f32 v26, v26, v27
	v_cvt_pk_bf16_f32 v27, v28, v29
	v_cvt_pk_bf16_f32 v28, v30, v31
	v_cvt_pk_bf16_f32 v29, v32, v33
	s_nop 1
	v_mfma_f32_32x32x16_bf16 v[2:17], v[106:109], v[26:29], v[2:17]
	v_cmp_lt_i32_e32 vcc, v94, v95
	s_waitcnt vmcnt(20) lgkmcnt(0)
; #define MFMA32(a, b, c) __builtin_amdgcn_mfma_f32_32x32x16_bf16((a), (b), (c), 0, 0, 0)
; DI void gla_stage3(const Ctx& c0, int layer, int unit, int cb, LAS unsigned char* lds) {
;     ...
;     f32x16 o[4];
; #pragma unroll
;     for (int vb = 0; vb < 4; ++vb) {
;         o[vb] = f32x16{};
; #pragma unroll
;         for (int s = 0; s < 4; ++s) { const float* s0 = sp + (size_t)(16 * s + 8 * hi) * 128 + 32 * vb + r;
;             const bf16x8 bfv = pack8(s0[0], s0[128], s0[256], s0[384], s0[512], s0[640], s0[768], s0[896]);
;             o[vb] = MFMA32(qf[s], bfv, o[vb]); }
;         asm volatile("" ::: "memory");
;     }
;     ...
;     for (int vb = 0; vb < 4; ++vb) { const float g = gn[32 * vb + r];
	global_load_dword v127, v[114:115], off offset:3840
	global_load_dword v126, v[114:115], off offset:3328
	global_load_dword v125, v[114:115], off offset:2816
	global_load_dword v124, v[114:115], off offset:2304
	global_load_dword v123, v[114:115], off offset:1792
	global_load_dword v122, v[114:115], off offset:1280
	global_load_dword v117, v[114:115], off offset:768
	global_load_dword v116, v[114:115], off offset:256
	global_load_dword v214, v[58:59], off offset:3840
	global_load_dword v212, v[58:59], off offset:3328
	global_load_dword v205, v[58:59], off offset:2816
	global_load_dword v210, v[58:59], off offset:2304
	global_load_dword v203, v[58:59], off offset:1792
	global_load_dword v208, v[58:59], off offset:1280
	global_load_dword v201, v[58:59], off offset:768
	global_load_dword v206, v[58:59], off offset:256
	global_load_dword v199, v[120:121], off offset:3712
	global_load_dword v204, v[120:121], off offset:3200
	global_load_dword v197, v[120:121], off offset:2688
	global_load_dword v202, v[120:121], off offset:2176
	global_load_dword v195, v[120:121], off offset:1664
	global_load_dword v200, v[120:121], off offset:1152
	global_load_dword v183, v[120:121], off offset:640
	global_load_dword v198, v[120:121], off offset:128
	global_load_dword v181, v[118:119], off offset:3712
	global_load_dword v196, v[118:119], off offset:3200
	global_load_dword v179, v[118:119], off offset:2688
	global_load_dword v182, v[118:119], off offset:2176
	global_load_dword v177, v[118:119], off offset:1664
	global_load_dword v180, v[118:119], off offset:1152
	global_load_dword v175, v[118:119], off offset:640
	global_load_dword v178, v[118:119], off offset:128
	global_load_dword v165, v[120:121], off offset:3584
	global_load_dword v168, v[120:121], off offset:3072
	global_load_dword v163, v[120:121], off offset:2560
	global_load_dword v166, v[120:121], off offset:2048
	global_load_dword v161, v[120:121], off offset:1536
	global_load_dword v164, v[120:121], off offset:1024
	global_load_dword v159, v[120:121], off offset:512
	global_load_dword v162, v[120:121], off
	v_cvt_pk_bf16_f32 v42, v42, v43
	v_cvt_pk_bf16_f32 v43, v44, v45
	v_cvt_pk_bf16_f32 v44, v46, v47
	v_cvt_pk_bf16_f32 v45, v48, v49
	s_nop 1
	v_mfma_f32_32x32x16_bf16 v[2:17], v[110:113], v[42:45], v[2:17]
	s_waitcnt vmcnt(40) lgkmcnt(0)
	global_load_dword v238, v[82:83], off offset:896
	global_load_dword v236, v[82:83], off offset:768
	global_load_dword v234, v[82:83], off offset:640
	global_load_dword v232, v[82:83], off offset:512
	global_load_dword v90, v[90:91], off
	global_load_dword v230, v[120:121], off offset:3328
	global_load_dword v219, v[120:121], off offset:2816
	global_load_dword v228, v[120:121], off offset:2304
	global_load_dword v217, v[120:121], off offset:1792
	global_load_dword v226, v[120:121], off offset:1280
	global_load_dword v215, v[120:121], off offset:768
	global_load_dword v224, v[120:121], off offset:256
	global_load_dword v213, v[118:119], off offset:3840
	global_load_dword v222, v[118:119], off offset:3328
	global_load_dword v211, v[118:119], off offset:2816
	global_load_dword v220, v[118:119], off offset:2304
	global_load_dword v209, v[118:119], off offset:1792
	global_load_dword v218, v[118:119], off offset:1280
	global_load_dword v207, v[118:119], off offset:768
	global_load_dword v216, v[118:119], off offset:256
	v_cvt_pk_bf16_f32 v18, v140, v139
	v_cvt_pk_bf16_f32 v34, v34, v35
	v_cvt_pk_bf16_f32 v19, v142, v141
	v_cvt_pk_bf16_f32 v35, v36, v37
	v_cvt_pk_bf16_f32 v20, v144, v143
	v_cvt_pk_bf16_f32 v36, v38, v39
	v_cvt_pk_bf16_f32 v21, v146, v145
	v_cvt_pk_bf16_f32 v37, v40, v41
	s_nop 0
	v_mfma_f32_32x32x16_bf16 v[18:33], v[50:53], v[18:21], 0
	v_mfma_f32_32x32x16_bf16 v[18:33], v[102:105], v[34:37], v[18:33]
	s_waitcnt vmcnt(60) lgkmcnt(0)
	v_cvt_pk_bf16_f32 v34, v148, v147
	v_cvt_pk_bf16_f32 v35, v156, v149
	v_cvt_pk_bf16_f32 v36, v158, v155
	v_cvt_pk_bf16_f32 v37, v160, v157
	s_nop 1
	v_mfma_f32_32x32x16_bf16 v[18:33], v[106:109], v[34:37], v[18:33]
	s_waitcnt vmcnt(20) lgkmcnt(0)
	v_cvt_pk_bf16_f32 v34, v162, v159
	v_cvt_pk_bf16_f32 v35, v164, v161
	v_cvt_pk_bf16_f32 v36, v166, v163
	v_cvt_pk_bf16_f32 v37, v168, v165
	s_nop 1
	v_mfma_f32_32x32x16_bf16 v[18:33], v[110:113], v[34:37], v[18:33]
	s_waitcnt vmcnt(62) lgkmcnt(0)
	v_cvt_pk_bf16_f32 v34, v170, v167
	v_cvt_pk_bf16_f32 v54, v54, v55
	v_cvt_pk_bf16_f32 v35, v172, v169
	v_cvt_pk_bf16_f32 v55, v56, v57
	v_cvt_pk_bf16_f32 v36, v174, v171
	v_cvt_pk_bf16_f32 v56, v60, v61
	v_cvt_pk_bf16_f32 v37, v176, v173
	v_cvt_pk_bf16_f32 v57, v62, v63
	s_nop 0
	v_mfma_f32_32x32x16_bf16 v[34:49], v[50:53], v[34:37], 0
	v_mfma_f32_32x32x16_bf16 v[34:49], v[102:105], v[54:57], v[34:49]
	s_waitcnt vmcnt(28) lgkmcnt(0)
	v_cvt_pk_bf16_f32 v54, v178, v175
	v_cvt_pk_bf16_f32 v55, v180, v177
	v_cvt_pk_bf16_f32 v56, v182, v179
	v_cvt_pk_bf16_f32 v57, v196, v181
	s_nop 1
	v_mfma_f32_32x32x16_bf16 v[34:49], v[106:109], v[54:57], v[34:49]
	s_waitcnt vmcnt(36) lgkmcnt(0)
	v_cvt_pk_bf16_f32 v54, v198, v183
	v_cvt_pk_bf16_f32 v55, v200, v195
	v_cvt_pk_bf16_f32 v56, v202, v197
	v_cvt_pk_bf16_f32 v57, v204, v199
	s_nop 1
	v_mfma_f32_32x32x16_bf16 v[34:49], v[110:113], v[54:57], v[34:49]
	s_nop 0
	s_nop 0
	s_waitcnt vmcnt(44) lgkmcnt(0)
	v_cvt_pk_bf16_f32 v54, v206, v201
	v_cvt_pk_bf16_f32 v114, v116, v117
	v_cvt_pk_bf16_f32 v55, v208, v203
	v_cvt_pk_bf16_f32 v115, v122, v123
	v_cvt_pk_bf16_f32 v56, v210, v205
	v_cvt_pk_bf16_f32 v116, v124, v125
	v_cvt_pk_bf16_f32 v57, v212, v214
	v_cvt_pk_bf16_f32 v117, v126, v127
	s_nop 0
	v_mfma_f32_32x32x16_bf16 v[50:65], v[50:53], v[54:57], 0
	v_mfma_f32_32x32x16_bf16 v[50:65], v[102:105], v[114:117], v[50:65]
	s_waitcnt vmcnt(0) lgkmcnt(0)
; #define LAS __attribute__((address_space(3)))
; #define LDS_WAIT() asm volatile("s_waitcnt lgkmcnt(0)" ::: "memory")
; DI float bf2f(bf16 b) { return __uint_as_float(((unsigned)b) << 16); }
; DI void g3_tile_in(const bf16* g, LAS unsigned char* R, int lane) {
; #pragma unroll
;     for (int it = 0; it < 8; ++it) { const int row = 4 * it + (lane >> 4), ch = lane & 15;
;         *(LAS u32x4*)(R + row * G3_PITCH + ch * 16) = *(const u32x4*)(g + (size_t)row * 512 + ch * 8); }
;     LDS_WAIT();
; DI void gla_stage3(const Ctx& c0, int layer, int unit, int cb, LAS unsigned char* lds) {
;     ...
;     g3_tile_in((const bf16*)(c.ws + O_OINTRA) + row0 * 512 + h * 128, R, lane);
; #pragma unroll
;     for (int vb = 0; vb < 4; ++vb) {
; #pragma unroll
;         for (int rg = 0; rg < 16; ++rg) o[vb][rg] += bf2f(*(const LAS bf16*)(Re + ((rg & 3) + 8 * (rg >> 2)) * G3_PITCH + 64 * vb));
;         asm volatile("" ::: "memory");
;     }
	v_cvt_pk_bf16_f32 v102, v216, v207
	v_cvt_pk_bf16_f32 v103, v218, v209
	v_cvt_pk_bf16_f32 v104, v220, v211
	v_cvt_pk_bf16_f32 v105, v222, v213
	s_nop 1
	v_mfma_f32_32x32x16_bf16 v[50:65], v[106:109], v[102:105], v[50:65]
	s_nop 0
	s_waitcnt vmcnt(8) lgkmcnt(0)
	v_cvt_pk_bf16_f32 v102, v224, v215
	v_cvt_pk_bf16_f32 v103, v226, v217
	v_cvt_pk_bf16_f32 v104, v228, v219
	v_cvt_pk_bf16_f32 v105, v230, v90
	v_lshl_add_u64 v[90:91], s[0:1], 0, v[88:89]
	v_lshl_add_u64 v[106:107], v[90:91], 0, s[20:21]
	v_mfma_f32_32x32x16_bf16 v[50:65], v[110:113], v[102:105], v[50:65]
	v_lshl_add_u64 v[102:103], v[106:107], 0, v[66:67]
	global_load_dwordx4 v[102:105], v[102:103], off
	s_waitcnt vmcnt(0) lgkmcnt(0)
	v_lshl_add_u64 v[168:169], v[90:91], 0, s[22:23]
	v_lshl_add_u64 v[140:141], v[168:169], 0, v[70:71]
	global_load_dwordx4 v[174:177], v[140:141], off
	v_lshl_add_u64 v[140:141], v[106:107], 0, v[70:71]
	global_load_dwordx4 v[146:149], v[140:141], off
	v_lshl_add_u64 v[144:145], v[106:107], 0, v[68:69]
	global_load_dwordx4 v[140:143], v[144:145], off
	ds_write_b128 v92, v[102:105]
	s_waitcnt vmcnt(0) lgkmcnt(0)
	v_lshl_add_u64 v[144:145], v[168:169], 0, v[76:77]
	global_load_dwordx4 v[200:203], v[144:145], off
	v_lshl_add_u64 v[144:145], v[168:169], 0, v[74:75]
	global_load_dwordx4 v[196:199], v[144:145], off
	v_lshl_add_u64 v[144:145], v[168:169], 0, v[72:73]
	global_load_dwordx4 v[178:181], v[144:145], off
	v_lshl_add_u64 v[144:145], v[106:107], 0, v[74:75]
	global_load_dwordx4 v[156:159], v[144:145], off
	v_lshl_add_u64 v[102:103], v[106:107], 0, v[72:73]
	global_load_dwordx4 v[102:105], v[102:103], off
	ds_write_b128 v92, v[140:143] offset:1088
	s_waitcnt vmcnt(5) lgkmcnt(0)
	v_lshl_add_u64 v[140:141], v[168:169], 0, v[78:79]
	global_load_dwordx4 v[204:207], v[140:141], off
	v_lshl_add_u64 v[140:141], v[106:107], 0, v[78:79]
	global_load_dwordx4 v[160:163], v[140:141], off
	v_lshl_add_u64 v[144:145], v[106:107], 0, v[76:77]
	global_load_dwordx4 v[140:143], v[144:145], off
	ds_write_b128 v92, v[146:149] offset:2176
	s_waitcnt vmcnt(3) lgkmcnt(0)
	v_lshl_add_u64 v[144:145], v[168:169], 0, v[66:67]
	global_load_dwordx4 v[164:167], v[144:145], off
	v_lshl_add_u64 v[148:149], v[106:107], 0, v[80:81]
	global_load_dwordx4 v[144:147], v[148:149], off
	ds_write_b128 v92, v[102:105] offset:3264
	s_waitcnt vmcnt(6) lgkmcnt(0)
	v_lshl_add_u64 v[148:149], v[168:169], 0, v[68:69]
	global_load_dwordx4 v[170:173], v[148:149], off
	ds_write_b128 v92, v[156:159] offset:4352
	s_waitcnt vmcnt(3) lgkmcnt(0)
	ds_write_b128 v92, v[140:143] offset:5440
	s_waitcnt vmcnt(4) lgkmcnt(0)
	ds_write_b128 v92, v[160:163] offset:6528
	s_waitcnt vmcnt(1) lgkmcnt(0)
	ds_write_b128 v92, v[144:147] offset:7616
	s_waitcnt lgkmcnt(0)
	ds_read_u16 v138, v1
	ds_read_u16 v137, v1 offset:272
	ds_read_u16 v136, v1 offset:544
	ds_read_u16 v135, v1 offset:816
	ds_read_u16 v134, v1 offset:2176
	ds_read_u16 v133, v1 offset:2448
	ds_read_u16 v132, v1 offset:2720
	ds_read_u16 v131, v1 offset:2992
	s_waitcnt lgkmcnt(0)
	v_lshlrev_b32_e32 v138, 16, v138
	v_add_f32_e32 v138, v2, v138
	v_lshlrev_b32_e32 v137, 16, v137
	v_add_f32_e32 v137, v3, v137
	v_lshlrev_b32_e32 v136, 16, v136
	v_add_f32_e32 v136, v4, v136
	v_lshlrev_b32_e32 v135, 16, v135
	v_add_f32_e32 v135, v5, v135
	v_lshlrev_b32_e32 v134, 16, v134
	v_add_f32_e32 v134, v6, v134
	v_lshlrev_b32_e32 v133, 16, v133
	v_add_f32_e32 v133, v7, v133
	v_lshlrev_b32_e32 v132, 16, v132
	v_add_f32_e32 v132, v8, v132
	v_lshlrev_b32_e32 v131, 16, v131
	v_add_f32_e32 v131, v9, v131
	ds_read_u16 v130, v1 offset:4352
	ds_read_u16 v129, v1 offset:4624
	ds_read_u16 v128, v1 offset:4896
	ds_read_u16 v127, v1 offset:5168
	ds_read_u16 v126, v1 offset:6528
	ds_read_u16 v125, v1 offset:6800
	ds_read_u16 v124, v1 offset:7072
	s_waitcnt lgkmcnt(0)
	v_lshlrev_b32_e32 v130, 16, v130
	v_add_f32_e32 v130, v10, v130
	v_lshlrev_b32_e32 v129, 16, v129
	v_add_f32_e32 v129, v11, v129
	v_lshlrev_b32_e32 v128, 16, v128
	v_add_f32_e32 v128, v12, v128
	v_lshlrev_b32_e32 v127, 16, v127
	v_add_f32_e32 v127, v13, v127
	v_lshlrev_b32_e32 v126, 16, v126
	v_add_f32_e32 v126, v14, v126
	v_lshlrev_b32_e32 v125, 16, v125
	v_add_f32_e32 v125, v15, v125
	v_lshlrev_b32_e32 v124, 16, v124
	v_add_f32_e32 v124, v16, v124
	ds_read_u16 v2, v1 offset:7344
	s_waitcnt lgkmcnt(0)
	v_lshlrev_b32_e32 v2, 16, v2
	v_add_f32_e32 v123, v17, v2
	ds_read_u16 v122, v1 offset:64
	ds_read_u16 v121, v1 offset:336
	ds_read_u16 v120, v1 offset:608
	ds_read_u16 v119, v1 offset:880
	ds_read_u16 v118, v1 offset:2240
	ds_read_u16 v117, v1 offset:2512
	ds_read_u16 v116, v1 offset:2784
	ds_read_u16 v115, v1 offset:3056
	s_waitcnt lgkmcnt(0)
	v_lshlrev_b32_e32 v122, 16, v122
	v_add_f32_e32 v122, v18, v122
	v_lshlrev_b32_e32 v121, 16, v121
	v_add_f32_e32 v121, v19, v121
	v_lshlrev_b32_e32 v120, 16, v120
	v_add_f32_e32 v120, v20, v120
	v_lshlrev_b32_e32 v119, 16, v119
	v_add_f32_e32 v119, v21, v119
	v_lshlrev_b32_e32 v118, 16, v118
	v_add_f32_e32 v118, v22, v118
	v_lshlrev_b32_e32 v117, 16, v117
	v_add_f32_e32 v117, v23, v117
	v_lshlrev_b32_e32 v116, 16, v116
	v_add_f32_e32 v116, v24, v116
	v_lshlrev_b32_e32 v115, 16, v115
	v_add_f32_e32 v115, v25, v115
	ds_read_u16 v114, v1 offset:4416
	ds_read_u16 v113, v1 offset:4688
	ds_read_u16 v112, v1 offset:4960
	ds_read_u16 v111, v1 offset:5232
	ds_read_u16 v110, v1 offset:6592
	ds_read_u16 v109, v1 offset:6864
	ds_read_u16 v108, v1 offset:7136
	s_waitcnt lgkmcnt(0)
; #define LAS __attribute__((address_space(3)))
; DI float bf2f(bf16 b) { return __uint_as_float(((unsigned)b) << 16); }
; DI void gla_stage3(const Ctx& c0, int layer, int unit, int cb, LAS unsigned char* lds) {
;     ...
;     for (int vb = 0; vb < 4; ++vb) {
; #pragma unroll
;         for (int rg = 0; rg < 16; ++rg) o[vb][rg] += bf2f(*(const LAS bf16*)(Re + ((rg & 3) + 8 * (rg >> 2)) * G3_PITCH + 64 * vb));
;         asm volatile("" ::: "memory");
;     }
;     float rs[16];
; #pragma unroll
;     for (int rg = 0; rg < 16; ++rg) { float ss = o[0][rg] * o[0][rg] + o[1][rg] * o[1][rg] + o[2][rg] * o[2][rg] + o[3][rg] * o[3][rg];
;         ss += __shfl_xor(ss, 1); ss += __shfl_xor(ss, 2); ss += __shfl_xor(ss, 4); ss += __shfl_xor(ss, 8); ss += __shfl_xor(ss, 16);
;         rs[rg] = 1.f / sqrtf(ss * (1.f / 128.f) + EPS); }
	v_lshlrev_b32_e32 v114, 16, v114
	v_add_f32_e32 v114, v26, v114
	v_lshlrev_b32_e32 v113, 16, v113
	v_add_f32_e32 v113, v27, v113
	v_lshlrev_b32_e32 v112, 16, v112
	v_add_f32_e32 v112, v28, v112
	v_lshlrev_b32_e32 v111, 16, v111
	v_add_f32_e32 v111, v29, v111
	v_lshlrev_b32_e32 v110, 16, v110
	v_add_f32_e32 v110, v30, v110
	v_lshlrev_b32_e32 v109, 16, v109
	v_add_f32_e32 v109, v31, v109
	v_lshlrev_b32_e32 v108, 16, v108
	v_add_f32_e32 v108, v32, v108
	ds_read_u16 v2, v1 offset:7408
	s_waitcnt lgkmcnt(0)
	v_lshlrev_b32_e32 v2, 16, v2
	v_add_f32_e32 v107, v33, v2
	ds_read_u16 v2, v1 offset:128
	s_waitcnt lgkmcnt(0)
	v_lshlrev_b32_e32 v2, 16, v2
	v_add_f32_e32 v106, v34, v2
	ds_read_u16 v2, v1 offset:400
	s_waitcnt lgkmcnt(0)
	v_lshlrev_b32_e32 v2, 16, v2
	v_add_f32_e32 v105, v35, v2
	ds_read_u16 v2, v1 offset:672
	s_waitcnt lgkmcnt(0)
	v_lshlrev_b32_e32 v2, 16, v2
	v_add_f32_e32 v104, v36, v2
	ds_read_u16 v2, v1 offset:944
	s_waitcnt lgkmcnt(0)
	v_lshlrev_b32_e32 v2, 16, v2
	v_add_f32_e32 v103, v37, v2
	ds_read_u16 v2, v1 offset:2304
	s_waitcnt lgkmcnt(0)
	v_lshlrev_b32_e32 v2, 16, v2
	v_add_f32_e32 v102, v38, v2
	ds_read_u16 v2, v1 offset:2576
	s_waitcnt lgkmcnt(0)
	v_lshlrev_b32_e32 v2, 16, v2
	v_add_f32_e32 v39, v39, v2
	ds_read_u16 v2, v1 offset:2848
	s_waitcnt lgkmcnt(0)
	v_lshlrev_b32_e32 v2, 16, v2
	v_add_f32_e32 v38, v40, v2
	ds_read_u16 v2, v1 offset:3120
	s_waitcnt lgkmcnt(0)
	v_lshlrev_b32_e32 v2, 16, v2
	v_add_f32_e32 v37, v41, v2
	ds_read_u16 v36, v1 offset:4480
	ds_read_u16 v34, v1 offset:4752
	ds_read_u16 v33, v1 offset:5024
	ds_read_u16 v32, v1 offset:5296
	ds_read_u16 v30, v1 offset:6656
	ds_read_u16 v29, v1 offset:6928
	ds_read_u16 v28, v1 offset:7200
	s_waitcnt lgkmcnt(0)
	v_lshlrev_b32_e32 v36, 16, v36
	v_add_f32_e32 v36, v42, v36
	v_lshlrev_b32_e32 v34, 16, v34
	v_add_f32_e32 v34, v43, v34
	v_lshlrev_b32_e32 v33, 16, v33
	v_add_f32_e32 v33, v44, v33
	v_lshlrev_b32_e32 v32, 16, v32
	v_add_f32_e32 v32, v45, v32
	v_lshlrev_b32_e32 v30, 16, v30
	v_add_f32_e32 v30, v46, v30
	v_lshlrev_b32_e32 v29, 16, v29
	v_add_f32_e32 v29, v47, v29
	v_lshlrev_b32_e32 v28, 16, v28
	v_add_f32_e32 v28, v48, v28
	ds_read_u16 v2, v1 offset:7472
	s_waitcnt lgkmcnt(0)
	v_lshlrev_b32_e32 v2, 16, v2
	v_add_f32_e32 v26, v49, v2
	ds_read_u16 v19, v1 offset:192
	ds_read_u16 v18, v1 offset:464
	ds_read_u16 v17, v1 offset:736
	ds_read_u16 v16, v1 offset:1008
	ds_read_u16 v15, v1 offset:2368
	ds_read_u16 v14, v1 offset:2640
	ds_read_u16 v13, v1 offset:2912
	ds_read_u16 v12, v1 offset:3184
	s_waitcnt lgkmcnt(0)
	v_lshlrev_b32_e32 v19, 16, v19
	v_add_f32_e32 v19, v50, v19
	v_lshlrev_b32_e32 v18, 16, v18
	v_add_f32_e32 v18, v51, v18
	v_lshlrev_b32_e32 v17, 16, v17
	v_add_f32_e32 v17, v52, v17
	v_lshlrev_b32_e32 v16, 16, v16
	v_add_f32_e32 v16, v53, v16
	v_lshlrev_b32_e32 v15, 16, v15
	v_add_f32_e32 v15, v54, v15
	v_lshlrev_b32_e32 v14, 16, v14
	v_add_f32_e32 v14, v55, v14
	v_lshlrev_b32_e32 v13, 16, v13
	v_add_f32_e32 v13, v56, v13
	v_lshlrev_b32_e32 v12, 16, v12
	v_add_f32_e32 v12, v57, v12
	ds_read_u16 v11, v1 offset:4544
	ds_read_u16 v10, v1 offset:4816
	ds_read_u16 v9, v1 offset:5088
	ds_read_u16 v8, v1 offset:5360
	ds_read_u16 v7, v1 offset:6720
	ds_read_u16 v6, v1 offset:6992
	ds_read_u16 v5, v1 offset:7264
	s_waitcnt lgkmcnt(0)
	v_lshlrev_b32_e32 v11, 16, v11
	v_add_f32_e32 v11, v58, v11
	v_lshlrev_b32_e32 v10, 16, v10
	v_add_f32_e32 v10, v59, v10
	v_lshlrev_b32_e32 v9, 16, v9
	v_add_f32_e32 v9, v60, v9
	v_lshlrev_b32_e32 v8, 16, v8
	v_add_f32_e32 v8, v61, v8
	v_lshlrev_b32_e32 v7, 16, v7
	v_add_f32_e32 v7, v62, v7
	v_lshlrev_b32_e32 v6, 16, v6
	v_add_f32_e32 v6, v63, v6
	v_lshlrev_b32_e32 v5, 16, v5
	v_add_f32_e32 v5, v64, v5
	ds_read_u16 v2, v1 offset:7536
	s_waitcnt lgkmcnt(0)
	s_waitcnt lgkmcnt(0)
	v_lshlrev_b32_e32 v2, 16, v2
	v_add_f32_e32 v4, v65, v2
	v_cndmask_b32_e32 v2, v93, v94, vcc
	v_cmp_lt_i32_e32 vcc, v96, v95
	v_lshlrev_b32_e32 v2, 2, v2
	s_nop 0
	v_cndmask_b32_e32 v3, v93, v96, vcc
	v_cmp_lt_i32_e32 vcc, v97, v95
	v_lshlrev_b32_e32 v3, 2, v3
	s_nop 0
	v_cndmask_b32_e32 v20, v93, v97, vcc
	v_cmp_lt_i32_e32 vcc, v98, v95
	v_lshlrev_b32_e32 v20, 2, v20
	s_nop 0
	v_cndmask_b32_e32 v21, v93, v98, vcc
	v_cmp_lt_i32_e32 vcc, v99, v95
	v_lshlrev_b32_e32 v47, 2, v21
	s_nop 0
	v_cndmask_b32_e32 v21, v93, v99, vcc
	v_lshlrev_b32_e32 v48, 2, v21
	v_mul_f32_e32 v21, v122, v122
	v_fmac_f32_e32 v21, v138, v138
	v_fmac_f32_e32 v21, v106, v106
	v_fmac_f32_e32 v21, v19, v19
	s_nop 1
	v_add_f32_dpp v21, v21, v21 quad_perm:[1,0,3,2] row_mask:0xf bank_mask:0xf
	s_nop 1
	v_add_f32_dpp v21, v21, v21 quad_perm:[2,3,0,1] row_mask:0xf bank_mask:0xf
	s_nop 1
	v_add_f32_dpp v21, v21, v21 row_half_mirror row_mask:0xf bank_mask:0xf
	s_nop 1
	v_add_f32_dpp v21, v21, v21 row_mirror row_mask:0xf bank_mask:0xf
	v_mov_b32_e32 v22, v21
	v_mov_b32_e32 v23, v21
	s_nop 1
	v_permlane16_swap_b32_e32 v22, v23
	v_add_f32_e32 v21, v22, v23
	v_fmamk_f32 v21, v21, 0x3c000000, v100
	v_cmp_gt_f32_e32 vcc, s33, v21
	v_mul_f32_e32 v22, 0x4f800000, v21
	s_nop 0
	v_cndmask_b32_e32 v21, v21, v22, vcc
	v_sqrt_f32_e32 v22, v21
	s_nop 0
	v_add_u32_e32 v23, -1, v22
	v_fma_f32 v24, -v23, v22, v21
	v_cmp_ge_f32_e64 s[8:9], 0, v24
	v_add_u32_e32 v24, 1, v22
	s_nop 0
	v_cndmask_b32_e64 v23, v22, v23, s[8:9]
	v_fma_f32 v22, -v24, v22, v21
	v_cmp_lt_f32_e64 s[8:9], 0, v22
	s_nop 1
	v_cndmask_b32_e64 v22, v23, v24, s[8:9]
	v_mul_f32_e32 v23, 0x37800000, v22
	v_cndmask_b32_e32 v22, v22, v23, vcc
	v_cmp_class_f32_e32 vcc, v21, v101
	s_nop 1
	v_cndmask_b32_e32 v21, v22, v21, vcc
	s_nop 0
	v_div_scale_f32 v24, vcc, 1.0, v21, 1.0
	v_rcp_f32_e32 v46, v21
	v_mul_f32_e32 v21, v121, v121
; DI void gla_stage3(const Ctx& c0, int layer, int unit, int cb, LAS unsigned char* lds) {
;     ...
;     float rs[16];
; #pragma unroll
;     for (int rg = 0; rg < 16; ++rg) { float ss = o[0][rg] * o[0][rg] + o[1][rg] * o[1][rg] + o[2][rg] * o[2][rg] + o[3][rg] * o[3][rg];
;         ss += __shfl_xor(ss, 1); ss += __shfl_xor(ss, 2); ss += __shfl_xor(ss, 4); ss += __shfl_xor(ss, 8); ss += __shfl_xor(ss, 16);
;         rs[rg] = 1.f / sqrtf(ss * (1.f / 128.f) + EPS); }
	v_fmac_f32_e32 v21, v137, v137
	v_fmac_f32_e32 v21, v105, v105
	v_fmac_f32_e32 v21, v18, v18
	s_nop 1
	v_add_f32_dpp v21, v21, v21 quad_perm:[1,0,3,2] row_mask:0xf bank_mask:0xf
	v_mul_f32_e32 v19, v19, v46
	s_nop 1
	v_add_f32_dpp v21, v21, v21 quad_perm:[2,3,0,1] row_mask:0xf bank_mask:0xf
	s_nop 1
	v_add_f32_dpp v21, v21, v21 row_half_mirror row_mask:0xf bank_mask:0xf
	s_nop 1
	v_add_f32_dpp v21, v21, v21 row_mirror row_mask:0xf bank_mask:0xf
	v_mov_b32_e32 v22, v21
	v_mov_b32_e32 v23, v21
	s_nop 1
	v_permlane16_swap_b32_e32 v22, v23
	v_add_f32_e32 v21, v22, v23
	v_fmamk_f32 v21, v21, 0x3c000000, v100
	v_cmp_gt_f32_e32 vcc, s33, v21
	v_mul_f32_e32 v22, 0x4f800000, v21
	s_nop 0
	v_cndmask_b32_e32 v21, v21, v22, vcc
	v_sqrt_f32_e32 v22, v21
	s_nop 0
	v_add_u32_e32 v23, -1, v22
	v_fma_f32 v24, -v23, v22, v21
	v_cmp_ge_f32_e64 s[8:9], 0, v24
	v_add_u32_e32 v24, 1, v22
	s_nop 0
	v_cndmask_b32_e64 v23, v22, v23, s[8:9]
	v_fma_f32 v22, -v24, v22, v21
	v_cmp_lt_f32_e64 s[8:9], 0, v22
	s_nop 1
	v_cndmask_b32_e64 v22, v23, v24, s[8:9]
	v_mul_f32_e32 v23, 0x37800000, v22
	v_cndmask_b32_e32 v22, v22, v23, vcc
	v_cmp_class_f32_e32 vcc, v21, v101
	s_nop 1
	v_cndmask_b32_e32 v21, v22, v21, vcc
	s_nop 0
	v_div_scale_f32 v24, vcc, 1.0, v21, 1.0
	v_rcp_f32_e32 v45, v21
	v_mul_f32_e32 v21, v120, v120
	v_fmac_f32_e32 v21, v136, v136
	v_fmac_f32_e32 v21, v104, v104
	v_fmac_f32_e32 v21, v17, v17
	s_nop 1
	v_add_f32_dpp v21, v21, v21 quad_perm:[1,0,3,2] row_mask:0xf bank_mask:0xf
	v_mul_f32_e32 v18, v18, v45
	s_nop 1
	v_add_f32_dpp v21, v21, v21 quad_perm:[2,3,0,1] row_mask:0xf bank_mask:0xf
	s_nop 1
	v_add_f32_dpp v21, v21, v21 row_half_mirror row_mask:0xf bank_mask:0xf
	s_nop 1
	v_add_f32_dpp v21, v21, v21 row_mirror row_mask:0xf bank_mask:0xf
	v_mov_b32_e32 v22, v21
	v_mov_b32_e32 v23, v21
	s_nop 1
	v_permlane16_swap_b32_e32 v22, v23
	v_add_f32_e32 v21, v22, v23
	v_fmamk_f32 v21, v21, 0x3c000000, v100
	v_cmp_gt_f32_e32 vcc, s33, v21
	v_mul_f32_e32 v22, 0x4f800000, v21
	s_nop 0
	v_cndmask_b32_e32 v21, v21, v22, vcc
	v_sqrt_f32_e32 v22, v21
	s_nop 0
	v_add_u32_e32 v23, -1, v22
	v_fma_f32 v24, -v23, v22, v21
	v_cmp_ge_f32_e64 s[8:9], 0, v24
	v_add_u32_e32 v24, 1, v22
	s_nop 0
	v_cndmask_b32_e64 v23, v22, v23, s[8:9]
	v_fma_f32 v22, -v24, v22, v21
	v_cmp_lt_f32_e64 s[8:9], 0, v22
	s_nop 1
	v_cndmask_b32_e64 v22, v23, v24, s[8:9]
	v_mul_f32_e32 v23, 0x37800000, v22
	v_cndmask_b32_e32 v22, v22, v23, vcc
	v_cmp_class_f32_e32 vcc, v21, v101
	s_nop 1
	v_cndmask_b32_e32 v21, v22, v21, vcc
	s_nop 0
	v_div_scale_f32 v24, vcc, 1.0, v21, 1.0
	v_rcp_f32_e32 v44, v21
	v_mul_f32_e32 v21, v119, v119
	v_fmac_f32_e32 v21, v135, v135
	v_fmac_f32_e32 v21, v103, v103
	v_fmac_f32_e32 v21, v16, v16
	s_nop 1
	v_add_f32_dpp v21, v21, v21 quad_perm:[1,0,3,2] row_mask:0xf bank_mask:0xf
	v_mul_f32_e32 v17, v17, v44
	s_nop 1
	v_add_f32_dpp v21, v21, v21 quad_perm:[2,3,0,1] row_mask:0xf bank_mask:0xf
	s_nop 1
	v_add_f32_dpp v21, v21, v21 row_half_mirror row_mask:0xf bank_mask:0xf
	s_nop 1
	v_add_f32_dpp v21, v21, v21 row_mirror row_mask:0xf bank_mask:0xf
	v_mov_b32_e32 v22, v21
	v_mov_b32_e32 v23, v21
	s_nop 1
	v_permlane16_swap_b32_e32 v22, v23
	v_add_f32_e32 v21, v22, v23
	v_fmamk_f32 v21, v21, 0x3c000000, v100
	v_cmp_gt_f32_e32 vcc, s33, v21
	v_mul_f32_e32 v22, 0x4f800000, v21
	s_nop 0
	v_cndmask_b32_e32 v21, v21, v22, vcc
	v_sqrt_f32_e32 v22, v21
	s_nop 0
	v_add_u32_e32 v23, -1, v22
	v_fma_f32 v24, -v23, v22, v21
	v_cmp_ge_f32_e64 s[8:9], 0, v24
	v_add_u32_e32 v24, 1, v22
	s_nop 0
	v_cndmask_b32_e64 v23, v22, v23, s[8:9]
	v_fma_f32 v22, -v24, v22, v21
	v_cmp_lt_f32_e64 s[8:9], 0, v22
	s_nop 1
	v_cndmask_b32_e64 v22, v23, v24, s[8:9]
	v_mul_f32_e32 v23, 0x37800000, v22
	v_cndmask_b32_e32 v22, v22, v23, vcc
	v_cmp_class_f32_e32 vcc, v21, v101
	s_nop 1
	v_cndmask_b32_e32 v21, v22, v21, vcc
	s_nop 0
	v_div_scale_f32 v24, vcc, 1.0, v21, 1.0
	v_rcp_f32_e32 v43, v21
	v_mul_f32_e32 v21, v118, v118
	v_fmac_f32_e32 v21, v134, v134
	v_fmac_f32_e32 v21, v102, v102
	v_fmac_f32_e32 v21, v15, v15
	s_nop 1
	v_add_f32_dpp v21, v21, v21 quad_perm:[1,0,3,2] row_mask:0xf bank_mask:0xf
	v_mul_f32_e32 v16, v16, v43
	s_nop 1
	v_add_f32_dpp v21, v21, v21 quad_perm:[2,3,0,1] row_mask:0xf bank_mask:0xf
	s_nop 1
	v_add_f32_dpp v21, v21, v21 row_half_mirror row_mask:0xf bank_mask:0xf
	s_nop 1
	v_add_f32_dpp v21, v21, v21 row_mirror row_mask:0xf bank_mask:0xf
	v_mov_b32_e32 v22, v21
	v_mov_b32_e32 v23, v21
	s_nop 1
	v_permlane16_swap_b32_e32 v22, v23
	v_add_f32_e32 v21, v22, v23
	v_fmamk_f32 v21, v21, 0x3c000000, v100
	v_cmp_gt_f32_e32 vcc, s33, v21
	v_mul_f32_e32 v22, 0x4f800000, v21
	s_nop 0
	v_cndmask_b32_e32 v21, v21, v22, vcc
	v_sqrt_f32_e32 v22, v21
	s_nop 0
	v_add_u32_e32 v23, -1, v22
	v_fma_f32 v24, -v23, v22, v21
	v_cmp_ge_f32_e64 s[8:9], 0, v24
	v_add_u32_e32 v24, 1, v22
	s_nop 0
	v_cndmask_b32_e64 v23, v22, v23, s[8:9]
	v_fma_f32 v22, -v24, v22, v21
	v_cmp_lt_f32_e64 s[8:9], 0, v22
	s_nop 1
	v_cndmask_b32_e64 v22, v23, v24, s[8:9]
	v_mul_f32_e32 v23, 0x37800000, v22
	v_cndmask_b32_e32 v22, v22, v23, vcc
	v_cmp_class_f32_e32 vcc, v21, v101
	s_nop 1
	v_cndmask_b32_e32 v21, v22, v21, vcc
	s_nop 0
	v_div_scale_f32 v24, vcc, 1.0, v21, 1.0
	v_rcp_f32_e32 v42, v21
	v_mul_f32_e32 v21, v117, v117
	v_fmac_f32_e32 v21, v133, v133
	v_fmac_f32_e32 v21, v39, v39
	v_fmac_f32_e32 v21, v14, v14
	s_nop 1
	v_add_f32_dpp v21, v21, v21 quad_perm:[1,0,3,2] row_mask:0xf bank_mask:0xf
	v_mul_f32_e32 v15, v15, v42
	s_nop 1
	v_add_f32_dpp v21, v21, v21 quad_perm:[2,3,0,1] row_mask:0xf bank_mask:0xf
	s_nop 1
	v_add_f32_dpp v21, v21, v21 row_half_mirror row_mask:0xf bank_mask:0xf
	s_nop 1
	v_add_f32_dpp v21, v21, v21 row_mirror row_mask:0xf bank_mask:0xf
; DI void gla_stage3(const Ctx& c0, int layer, int unit, int cb, LAS unsigned char* lds) {
;     ...
;     float rs[16];
; #pragma unroll
;     for (int rg = 0; rg < 16; ++rg) { float ss = o[0][rg] * o[0][rg] + o[1][rg] * o[1][rg] + o[2][rg] * o[2][rg] + o[3][rg] * o[3][rg];
;         ss += __shfl_xor(ss, 1); ss += __shfl_xor(ss, 2); ss += __shfl_xor(ss, 4); ss += __shfl_xor(ss, 8); ss += __shfl_xor(ss, 16);
;         rs[rg] = 1.f / sqrtf(ss * (1.f / 128.f) + EPS); }
	v_mov_b32_e32 v22, v21
	v_mov_b32_e32 v23, v21
	s_nop 1
	v_permlane16_swap_b32_e32 v22, v23
	v_add_f32_e32 v21, v22, v23
	v_fmamk_f32 v21, v21, 0x3c000000, v100
	v_cmp_gt_f32_e32 vcc, s33, v21
	v_mul_f32_e32 v22, 0x4f800000, v21
	s_nop 0
	v_cndmask_b32_e32 v21, v21, v22, vcc
	v_sqrt_f32_e32 v22, v21
	s_nop 0
	v_add_u32_e32 v23, -1, v22
	v_fma_f32 v24, -v23, v22, v21
	v_cmp_ge_f32_e64 s[8:9], 0, v24
	v_add_u32_e32 v24, 1, v22
	s_nop 0
	v_cndmask_b32_e64 v23, v22, v23, s[8:9]
	v_fma_f32 v22, -v24, v22, v21
	v_cmp_lt_f32_e64 s[8:9], 0, v22
	s_nop 1
	v_cndmask_b32_e64 v22, v23, v24, s[8:9]
	v_mul_f32_e32 v23, 0x37800000, v22
	v_cndmask_b32_e32 v22, v22, v23, vcc
	v_cmp_class_f32_e32 vcc, v21, v101
	s_nop 1
	v_cndmask_b32_e32 v21, v22, v21, vcc
	s_nop 0
	v_div_scale_f32 v24, vcc, 1.0, v21, 1.0
	v_rcp_f32_e32 v41, v21
	v_mul_f32_e32 v21, v116, v116
	v_fmac_f32_e32 v21, v132, v132
	v_fmac_f32_e32 v21, v38, v38
	v_fmac_f32_e32 v21, v13, v13
	s_nop 1
	v_add_f32_dpp v21, v21, v21 quad_perm:[1,0,3,2] row_mask:0xf bank_mask:0xf
	v_mul_f32_e32 v39, v39, v41
	v_mul_f32_e32 v14, v14, v41
	s_nop 1
	v_add_f32_dpp v21, v21, v21 quad_perm:[2,3,0,1] row_mask:0xf bank_mask:0xf
	s_nop 1
	v_add_f32_dpp v21, v21, v21 row_half_mirror row_mask:0xf bank_mask:0xf
	s_nop 1
	v_add_f32_dpp v21, v21, v21 row_mirror row_mask:0xf bank_mask:0xf
	v_mov_b32_e32 v22, v21
	v_mov_b32_e32 v23, v21
	s_nop 1
	v_permlane16_swap_b32_e32 v22, v23
	v_add_f32_e32 v21, v22, v23
	v_fmamk_f32 v21, v21, 0x3c000000, v100
	v_cmp_gt_f32_e32 vcc, s33, v21
	v_mul_f32_e32 v22, 0x4f800000, v21
	s_nop 0
	v_cndmask_b32_e32 v21, v21, v22, vcc
	v_sqrt_f32_e32 v22, v21
	s_nop 0
	v_add_u32_e32 v23, -1, v22
	v_fma_f32 v24, -v23, v22, v21
	v_cmp_ge_f32_e64 s[8:9], 0, v24
	v_add_u32_e32 v24, 1, v22
	s_nop 0
	v_cndmask_b32_e64 v23, v22, v23, s[8:9]
	v_fma_f32 v22, -v24, v22, v21
	v_cmp_lt_f32_e64 s[8:9], 0, v22
	s_nop 1
	v_cndmask_b32_e64 v22, v23, v24, s[8:9]
	v_mul_f32_e32 v23, 0x37800000, v22
	v_cndmask_b32_e32 v22, v22, v23, vcc
	v_cmp_class_f32_e32 vcc, v21, v101
	s_nop 1
	v_cndmask_b32_e32 v21, v22, v21, vcc
	s_nop 0
	v_div_scale_f32 v24, vcc, 1.0, v21, 1.0
	v_rcp_f32_e32 v40, v21
	v_mul_f32_e32 v21, v115, v115
	v_fmac_f32_e32 v21, v131, v131
	v_fmac_f32_e32 v21, v37, v37
	v_fmac_f32_e32 v21, v12, v12
	s_nop 1
	v_add_f32_dpp v21, v21, v21 quad_perm:[1,0,3,2] row_mask:0xf bank_mask:0xf
	v_mul_f32_e32 v38, v38, v40
	v_mul_f32_e32 v13, v13, v40
	s_nop 1
	v_add_f32_dpp v21, v21, v21 quad_perm:[2,3,0,1] row_mask:0xf bank_mask:0xf
	s_nop 1
	v_add_f32_dpp v21, v21, v21 row_half_mirror row_mask:0xf bank_mask:0xf
	s_nop 1
	v_add_f32_dpp v21, v21, v21 row_mirror row_mask:0xf bank_mask:0xf
	v_mov_b32_e32 v22, v21
	v_mov_b32_e32 v23, v21
	s_nop 1
	v_permlane16_swap_b32_e32 v22, v23
	v_add_f32_e32 v21, v22, v23
	v_fmamk_f32 v21, v21, 0x3c000000, v100
	v_cmp_gt_f32_e32 vcc, s33, v21
	v_mul_f32_e32 v22, 0x4f800000, v21
	s_nop 0
	v_cndmask_b32_e32 v21, v21, v22, vcc
	v_sqrt_f32_e32 v22, v21
	s_nop 0
	v_add_u32_e32 v23, -1, v22
	v_fma_f32 v24, -v23, v22, v21
	v_cmp_ge_f32_e64 s[8:9], 0, v24
	v_add_u32_e32 v24, 1, v22
	s_nop 0
	v_cndmask_b32_e64 v23, v22, v23, s[8:9]
	v_fma_f32 v22, -v24, v22, v21
	v_cmp_lt_f32_e64 s[8:9], 0, v22
	s_nop 1
	v_cndmask_b32_e64 v22, v23, v24, s[8:9]
	v_mul_f32_e32 v23, 0x37800000, v22
	v_cndmask_b32_e32 v22, v22, v23, vcc
	v_cmp_class_f32_e32 vcc, v21, v101
	s_nop 1
	v_cndmask_b32_e32 v21, v22, v21, vcc
	s_nop 0
	v_div_scale_f32 v24, vcc, 1.0, v21, 1.0
	v_rcp_f32_e32 v35, v21
	v_mul_f32_e32 v21, v114, v114
	v_fmac_f32_e32 v21, v130, v130
	v_fmac_f32_e32 v21, v36, v36
	v_fmac_f32_e32 v21, v11, v11
	s_nop 1
	v_add_f32_dpp v21, v21, v21 quad_perm:[1,0,3,2] row_mask:0xf bank_mask:0xf
	v_mul_f32_e32 v37, v37, v35
	v_mul_f32_e32 v12, v12, v35
	s_nop 1
	v_add_f32_dpp v21, v21, v21 quad_perm:[2,3,0,1] row_mask:0xf bank_mask:0xf
	s_nop 1
	v_add_f32_dpp v21, v21, v21 row_half_mirror row_mask:0xf bank_mask:0xf
	s_nop 1
	v_add_f32_dpp v21, v21, v21 row_mirror row_mask:0xf bank_mask:0xf
	v_mov_b32_e32 v22, v21
	v_mov_b32_e32 v23, v21
	s_nop 1
	v_permlane16_swap_b32_e32 v22, v23
	v_add_f32_e32 v21, v22, v23
	v_fmamk_f32 v21, v21, 0x3c000000, v100
	v_cmp_gt_f32_e32 vcc, s33, v21
	v_mul_f32_e32 v22, 0x4f800000, v21
	s_nop 0
	v_cndmask_b32_e32 v21, v21, v22, vcc
	v_sqrt_f32_e32 v22, v21
	s_nop 0
	v_add_u32_e32 v23, -1, v22
	v_fma_f32 v24, -v23, v22, v21
	v_cmp_ge_f32_e64 s[8:9], 0, v24
	v_add_u32_e32 v24, 1, v22
	s_nop 0
	v_cndmask_b32_e64 v23, v22, v23, s[8:9]
	v_fma_f32 v22, -v24, v22, v21
	v_cmp_lt_f32_e64 s[8:9], 0, v22
	s_nop 1
	v_cndmask_b32_e64 v22, v23, v24, s[8:9]
	v_mul_f32_e32 v23, 0x37800000, v22
	v_cndmask_b32_e32 v22, v22, v23, vcc
	v_cmp_class_f32_e32 vcc, v21, v101
	s_nop 1
	v_cndmask_b32_e32 v21, v22, v21, vcc
	s_nop 0
	v_div_scale_f32 v24, vcc, 1.0, v21, 1.0
	v_rcp_f32_e32 v31, v21
	v_mul_f32_e32 v21, v113, v113
	v_fmac_f32_e32 v21, v129, v129
	v_fmac_f32_e32 v21, v34, v34
	v_fmac_f32_e32 v21, v10, v10
	s_nop 1
	v_add_f32_dpp v21, v21, v21 quad_perm:[1,0,3,2] row_mask:0xf bank_mask:0xf
	v_mul_f32_e32 v36, v36, v31
	v_mul_f32_e32 v11, v11, v31
	s_nop 1
	v_add_f32_dpp v21, v21, v21 quad_perm:[2,3,0,1] row_mask:0xf bank_mask:0xf
	s_nop 1
	v_add_f32_dpp v21, v21, v21 row_half_mirror row_mask:0xf bank_mask:0xf
	s_nop 1
	v_add_f32_dpp v21, v21, v21 row_mirror row_mask:0xf bank_mask:0xf
	v_mov_b32_e32 v22, v21
	v_mov_b32_e32 v23, v21
	s_nop 1
	v_permlane16_swap_b32_e32 v22, v23
	v_add_f32_e32 v21, v22, v23
	v_fmamk_f32 v21, v21, 0x3c000000, v100
	v_cmp_gt_f32_e32 vcc, s33, v21
	v_mul_f32_e32 v22, 0x4f800000, v21
	s_nop 0
	v_cndmask_b32_e32 v21, v21, v22, vcc
	v_sqrt_f32_e32 v22, v21
	s_nop 0
; DI void gla_stage3(const Ctx& c0, int layer, int unit, int cb, LAS unsigned char* lds) {
;     ...
;     float rs[16];
; #pragma unroll
;     for (int rg = 0; rg < 16; ++rg) { float ss = o[0][rg] * o[0][rg] + o[1][rg] * o[1][rg] + o[2][rg] * o[2][rg] + o[3][rg] * o[3][rg];
;         ss += __shfl_xor(ss, 1); ss += __shfl_xor(ss, 2); ss += __shfl_xor(ss, 4); ss += __shfl_xor(ss, 8); ss += __shfl_xor(ss, 16);
;         rs[rg] = 1.f / sqrtf(ss * (1.f / 128.f) + EPS); }
	v_add_u32_e32 v23, -1, v22
	v_fma_f32 v24, -v23, v22, v21
	v_cmp_ge_f32_e64 s[8:9], 0, v24
	v_add_u32_e32 v24, 1, v22
	s_nop 0
	v_cndmask_b32_e64 v23, v22, v23, s[8:9]
	v_fma_f32 v22, -v24, v22, v21
	v_cmp_lt_f32_e64 s[8:9], 0, v22
	s_nop 1
	v_cndmask_b32_e64 v22, v23, v24, s[8:9]
	v_mul_f32_e32 v23, 0x37800000, v22
	v_cndmask_b32_e32 v22, v22, v23, vcc
	v_cmp_class_f32_e32 vcc, v21, v101
	s_nop 1
	v_cndmask_b32_e32 v21, v22, v21, vcc
	s_nop 0
	v_div_scale_f32 v24, vcc, 1.0, v21, 1.0
	v_rcp_f32_e32 v27, v21
	v_mul_f32_e32 v21, v112, v112
	v_fmac_f32_e32 v21, v128, v128
	v_fmac_f32_e32 v21, v33, v33
	v_fmac_f32_e32 v21, v9, v9
	s_nop 1
	v_add_f32_dpp v21, v21, v21 quad_perm:[1,0,3,2] row_mask:0xf bank_mask:0xf
	v_mul_f32_e32 v34, v34, v27
	v_mul_f32_e32 v10, v10, v27
	s_nop 1
	v_add_f32_dpp v21, v21, v21 quad_perm:[2,3,0,1] row_mask:0xf bank_mask:0xf
	s_nop 1
	v_add_f32_dpp v21, v21, v21 row_half_mirror row_mask:0xf bank_mask:0xf
	s_nop 1
	v_add_f32_dpp v21, v21, v21 row_mirror row_mask:0xf bank_mask:0xf
	v_mov_b32_e32 v22, v21
	v_mov_b32_e32 v23, v21
	s_nop 1
	v_permlane16_swap_b32_e32 v22, v23
	v_add_f32_e32 v21, v22, v23
	v_fmamk_f32 v21, v21, 0x3c000000, v100
	v_cmp_gt_f32_e32 vcc, s33, v21
	v_mul_f32_e32 v22, 0x4f800000, v21
	s_nop 0
	v_cndmask_b32_e32 v21, v21, v22, vcc
	v_sqrt_f32_e32 v22, v21
	s_nop 0
	v_add_u32_e32 v23, -1, v22
	v_fma_f32 v24, -v23, v22, v21
	v_cmp_ge_f32_e64 s[8:9], 0, v24
	v_add_u32_e32 v24, 1, v22
	s_nop 0
	v_cndmask_b32_e64 v23, v22, v23, s[8:9]
	v_fma_f32 v22, -v24, v22, v21
	v_cmp_lt_f32_e64 s[8:9], 0, v22
	s_nop 1
	v_cndmask_b32_e64 v22, v23, v24, s[8:9]
	v_mul_f32_e32 v23, 0x37800000, v22
	v_cndmask_b32_e32 v22, v22, v23, vcc
	v_cmp_class_f32_e32 vcc, v21, v101
	s_nop 1
	v_cndmask_b32_e32 v21, v22, v21, vcc
	s_nop 0
	v_div_scale_f32 v24, vcc, 1.0, v21, 1.0
	v_rcp_f32_e32 v25, v21
	v_mul_f32_e32 v21, v111, v111
	v_fmac_f32_e32 v21, v127, v127
	v_fmac_f32_e32 v21, v32, v32
	v_fmac_f32_e32 v21, v8, v8
	s_nop 1
	v_add_f32_dpp v21, v21, v21 quad_perm:[1,0,3,2] row_mask:0xf bank_mask:0xf
	v_mul_f32_e32 v33, v33, v25
	v_mul_f32_e32 v9, v9, v25
	s_nop 1
	v_add_f32_dpp v21, v21, v21 quad_perm:[2,3,0,1] row_mask:0xf bank_mask:0xf
	s_nop 1
	v_add_f32_dpp v21, v21, v21 row_half_mirror row_mask:0xf bank_mask:0xf
	s_nop 1
	v_add_f32_dpp v21, v21, v21 row_mirror row_mask:0xf bank_mask:0xf
	v_mov_b32_e32 v22, v21
	v_mov_b32_e32 v23, v21
	s_nop 1
	v_permlane16_swap_b32_e32 v22, v23
	v_add_f32_e32 v21, v22, v23
	v_fmamk_f32 v21, v21, 0x3c000000, v100
	v_cmp_gt_f32_e32 vcc, s33, v21
	v_mul_f32_e32 v22, 0x4f800000, v21
	s_nop 0
	v_cndmask_b32_e32 v21, v21, v22, vcc
	v_sqrt_f32_e32 v22, v21
	s_nop 0
	v_add_u32_e32 v23, -1, v22
	v_fma_f32 v24, -v23, v22, v21
	v_cmp_ge_f32_e64 s[8:9], 0, v24
	v_add_u32_e32 v24, 1, v22
	s_nop 0
	v_cndmask_b32_e64 v23, v22, v23, s[8:9]
	v_fma_f32 v22, -v24, v22, v21
	v_cmp_lt_f32_e64 s[8:9], 0, v22
	s_nop 1
	v_cndmask_b32_e64 v22, v23, v24, s[8:9]
	v_mul_f32_e32 v23, 0x37800000, v22
	v_cndmask_b32_e32 v22, v22, v23, vcc
	v_cmp_class_f32_e32 vcc, v21, v101
	s_nop 1
	v_cndmask_b32_e32 v21, v22, v21, vcc
	s_nop 0
	v_div_scale_f32 v24, vcc, 1.0, v21, 1.0
	v_rcp_f32_e32 v24, v21
	v_mul_f32_e32 v21, v110, v110
	v_fmac_f32_e32 v21, v126, v126
	v_fmac_f32_e32 v21, v30, v30
	v_fmac_f32_e32 v21, v7, v7
	s_nop 1
	v_add_f32_dpp v21, v21, v21 quad_perm:[1,0,3,2] row_mask:0xf bank_mask:0xf
	v_mul_f32_e32 v32, v32, v24
	v_mul_f32_e32 v8, v8, v24
	s_nop 1
	v_add_f32_dpp v21, v21, v21 quad_perm:[2,3,0,1] row_mask:0xf bank_mask:0xf
	s_nop 1
	v_add_f32_dpp v21, v21, v21 row_half_mirror row_mask:0xf bank_mask:0xf
	s_nop 1
	v_add_f32_dpp v21, v21, v21 row_mirror row_mask:0xf bank_mask:0xf
	v_mov_b32_e32 v22, v21
	v_mov_b32_e32 v23, v21
	s_nop 1
	v_permlane16_swap_b32_e32 v22, v23
	v_add_f32_e32 v21, v22, v23
	v_fmamk_f32 v21, v21, 0x3c000000, v100
	v_cmp_gt_f32_e32 vcc, s33, v21
	v_mul_f32_e32 v22, 0x4f800000, v21
	s_nop 0
	v_cndmask_b32_e32 v21, v21, v22, vcc
	v_sqrt_f32_e32 v22, v21
	s_nop 0
	v_add_u32_e32 v23, -1, v22
	v_fma_f32 v49, -v23, v22, v21
	v_cmp_ge_f32_e64 s[8:9], 0, v49
	v_add_u32_e32 v49, 1, v22
	s_nop 0
	v_cndmask_b32_e64 v23, v22, v23, s[8:9]
	v_fma_f32 v22, -v49, v22, v21
	v_cmp_lt_f32_e64 s[8:9], 0, v22
	s_nop 1
	v_cndmask_b32_e64 v22, v23, v49, s[8:9]
	v_mul_f32_e32 v23, 0x37800000, v22
	v_cndmask_b32_e32 v22, v22, v23, vcc
	v_cmp_class_f32_e32 vcc, v21, v101
	s_nop 1
	v_cndmask_b32_e32 v21, v22, v21, vcc
	s_nop 0
	v_div_scale_f32 v49, vcc, 1.0, v21, 1.0
	v_rcp_f32_e32 v23, v21
	v_mul_f32_e32 v21, v109, v109
	v_fmac_f32_e32 v21, v125, v125
	v_fmac_f32_e32 v21, v29, v29
	v_fmac_f32_e32 v21, v6, v6
	s_nop 1
	v_add_f32_dpp v21, v21, v21 quad_perm:[1,0,3,2] row_mask:0xf bank_mask:0xf
	v_mul_f32_e32 v30, v30, v23
	v_mul_f32_e32 v7, v7, v23
	s_nop 1
	v_add_f32_dpp v21, v21, v21 quad_perm:[2,3,0,1] row_mask:0xf bank_mask:0xf
	s_nop 1
	v_add_f32_dpp v21, v21, v21 row_half_mirror row_mask:0xf bank_mask:0xf
	s_nop 1
	v_add_f32_dpp v21, v21, v21 row_mirror row_mask:0xf bank_mask:0xf
	v_mov_b32_e32 v22, v21
	v_mov_b32_e32 v49, v21
	s_nop 1
	v_permlane16_swap_b32_e32 v22, v49
	v_add_f32_e32 v21, v22, v49
	v_fmamk_f32 v21, v21, 0x3c000000, v100
	v_cmp_gt_f32_e32 vcc, s33, v21
	v_mul_f32_e32 v22, 0x4f800000, v21
	s_nop 0
	v_cndmask_b32_e32 v21, v21, v22, vcc
	v_sqrt_f32_e32 v22, v21
	s_nop 0
	v_add_u32_e32 v49, -1, v22
	v_fma_f32 v50, -v49, v22, v21
	v_cmp_ge_f32_e64 s[8:9], 0, v50
	v_add_u32_e32 v50, 1, v22
	s_nop 0
	v_cndmask_b32_e64 v49, v22, v49, s[8:9]
	v_fma_f32 v22, -v50, v22, v21
	v_cmp_lt_f32_e64 s[8:9], 0, v22
	s_nop 1
	v_cndmask_b32_e64 v22, v49, v50, s[8:9]
	v_mul_f32_e32 v49, 0x37800000, v22
; #define LAS __attribute__((address_space(3)))
; #define LDS_WAIT() asm volatile("s_waitcnt lgkmcnt(0)" ::: "memory")
; DI unsigned cvtpk(float lo, float hi) { f32x2 v = {lo, hi}; bf16x2_t b = __builtin_convertvector(v, bf16x2_t); return __builtin_bit_cast(unsigned, b); }
; DI float bf2f(bf16 b) { return __uint_as_float(((unsigned)b) << 16); }
; DI float siluf_(float x) { return x / (1.f + __expf(-x)); }
; DI void gla_stage3(const Ctx& c0, int layer, int unit, int cb, LAS unsigned char* lds) {
;     ...
;     float rs[16];
; #pragma unroll
;     for (int rg = 0; rg < 16; ++rg) { float ss = o[0][rg] * o[0][rg] + o[1][rg] * o[1][rg] + o[2][rg] * o[2][rg] + o[3][rg] * o[3][rg];
;         ss += __shfl_xor(ss, 1); ss += __shfl_xor(ss, 2); ss += __shfl_xor(ss, 4); ss += __shfl_xor(ss, 8); ss += __shfl_xor(ss, 16);
;         rs[rg] = 1.f / sqrtf(ss * (1.f / 128.f) + EPS); }
;     LDS_WAIT();
;     g3_tile_in((const bf16*)(c.ws + O_GR) + row0 * 512 + h * 128, R, lane);
; #pragma unroll
;     for (int vb = 0; vb < 4; ++vb) { const float g = gn[32 * vb + r];
; #pragma unroll
;         for (int rg = 0; rg < 16; ++rg) { LAS bf16* e = (LAS bf16*)(R + (4 * hi) * G3_PITCH + r * 2 + ((rg & 3) + 8 * (rg >> 2)) * G3_PITCH + 64 * vb);
;             const float z = bf2f(*e);
;             *e = (bf16)(cvtpk(o[vb][rg] * rs[rg] * g * siluf_(z), 0.f) & 0xffffu); }
	v_cndmask_b32_e32 v22, v22, v49, vcc
	v_cmp_class_f32_e32 vcc, v21, v101
	s_nop 1
	v_cndmask_b32_e32 v21, v22, v21, vcc
	s_nop 0
	v_div_scale_f32 v50, vcc, 1.0, v21, 1.0
	v_rcp_f32_e32 v22, v21
	v_mul_f32_e32 v21, v108, v108
	v_fmac_f32_e32 v21, v124, v124
	v_fmac_f32_e32 v21, v28, v28
	v_fmac_f32_e32 v21, v5, v5
	s_nop 1
	v_add_f32_dpp v21, v21, v21 quad_perm:[1,0,3,2] row_mask:0xf bank_mask:0xf
	v_mul_f32_e32 v29, v29, v22
	v_mul_f32_e32 v6, v6, v22
	s_nop 1
	v_add_f32_dpp v21, v21, v21 quad_perm:[2,3,0,1] row_mask:0xf bank_mask:0xf
	s_nop 1
	v_add_f32_dpp v21, v21, v21 row_half_mirror row_mask:0xf bank_mask:0xf
	s_nop 1
	v_add_f32_dpp v21, v21, v21 row_mirror row_mask:0xf bank_mask:0xf
	v_mov_b32_e32 v49, v21
	v_mov_b32_e32 v50, v21
	s_nop 1
	v_permlane16_swap_b32_e32 v49, v50
	v_add_f32_e32 v21, v49, v50
	v_fmamk_f32 v21, v21, 0x3c000000, v100
	v_cmp_gt_f32_e32 vcc, s33, v21
	v_mul_f32_e32 v49, 0x4f800000, v21
	s_nop 0
	v_cndmask_b32_e32 v21, v21, v49, vcc
	v_sqrt_f32_e32 v49, v21
	s_nop 0
	v_add_u32_e32 v50, -1, v49
	v_fma_f32 v51, -v50, v49, v21
	v_cmp_ge_f32_e64 s[8:9], 0, v51
	v_add_u32_e32 v51, 1, v49
	s_nop 0
	v_cndmask_b32_e64 v50, v49, v50, s[8:9]
	v_fma_f32 v49, -v51, v49, v21
	v_cmp_lt_f32_e64 s[8:9], 0, v49
	s_nop 1
	v_cndmask_b32_e64 v49, v50, v51, s[8:9]
	v_mul_f32_e32 v50, 0x37800000, v49
	v_cndmask_b32_e32 v49, v49, v50, vcc
	v_cmp_class_f32_e32 vcc, v21, v101
	s_nop 1
	v_cndmask_b32_e32 v21, v49, v21, vcc
	s_nop 0
	v_div_scale_f32 v51, vcc, 1.0, v21, 1.0
	v_rcp_f32_e32 v21, v21
	v_mul_f32_e32 v49, v107, v107
	v_fmac_f32_e32 v49, v123, v123
	v_fmac_f32_e32 v49, v26, v26
	v_fmac_f32_e32 v49, v4, v4
	ds_bpermute_b32 v2, v2, v49
	v_mul_f32_e32 v28, v28, v21
	v_mul_f32_e32 v5, v5, v21
	s_waitcnt lgkmcnt(0)
	v_add_f32_e32 v2, v49, v2
	ds_bpermute_b32 v3, v3, v2
	s_waitcnt lgkmcnt(0)
	v_add_f32_e32 v2, v2, v3
	ds_bpermute_b32 v3, v20, v2
	s_waitcnt lgkmcnt(0)
	v_add_f32_e32 v2, v2, v3
	ds_bpermute_b32 v3, v47, v2
	s_waitcnt lgkmcnt(0)
	v_add_f32_e32 v2, v2, v3
	ds_bpermute_b32 v3, v48, v2
	s_waitcnt lgkmcnt(0)
	v_add_f32_e32 v2, v2, v3
	v_fmamk_f32 v2, v2, 0x3c000000, v100
	v_cmp_gt_f32_e32 vcc, s33, v2
	v_mul_f32_e32 v3, 0x4f800000, v2
	s_nop 0
	v_cndmask_b32_e32 v2, v2, v3, vcc
	v_sqrt_f32_e32 v3, v2
	s_nop 0
	v_add_u32_e32 v20, -1, v3
	v_fma_f32 v47, -v20, v3, v2
	v_cmp_ge_f32_e64 s[8:9], 0, v47
	v_add_u32_e32 v47, 1, v3
	s_nop 0
	v_cndmask_b32_e64 v20, v3, v20, s[8:9]
	v_fma_f32 v3, -v47, v3, v2
	v_cmp_lt_f32_e64 s[8:9], 0, v3
	s_nop 1
	v_cndmask_b32_e64 v3, v20, v47, s[8:9]
	v_mul_f32_e32 v20, 0x37800000, v3
	v_cndmask_b32_e32 v3, v3, v20, vcc
	v_cmp_class_f32_e32 vcc, v2, v101
	s_nop 1
	v_cndmask_b32_e32 v2, v3, v2, vcc
	s_nop 0
	v_rcp_f32_e32 v20, v2
	v_mul_f32_e32 v47, v138, v46
	v_mul_f32_e32 v26, v26, v20
	v_mul_f32_e32 v4, v4, v20
	s_waitcnt vmcnt(2) lgkmcnt(0)
	ds_write_b128 v92, v[164:167]
	s_waitcnt vmcnt(0) lgkmcnt(0)
	ds_write_b128 v92, v[170:173] offset:1088
	s_waitcnt vmcnt(13) lgkmcnt(0)
	ds_write_b128 v92, v[174:177] offset:2176
	s_waitcnt vmcnt(8) lgkmcnt(0)
	ds_write_b128 v92, v[178:181] offset:3264
	s_waitcnt vmcnt(9) lgkmcnt(0)
	ds_write_b128 v92, v[196:199] offset:4352
	s_waitcnt vmcnt(10) lgkmcnt(0)
	ds_write_b128 v92, v[200:203] offset:5440
	v_lshl_add_u64 v[2:3], v[168:169], 0, v[80:81]
	s_waitcnt vmcnt(5) lgkmcnt(0)
	ds_write_b128 v92, v[204:207] offset:6528
	global_load_dwordx4 v[48:51], v[2:3], off
	s_waitcnt vmcnt(0) lgkmcnt(0)
	ds_write_b128 v92, v[48:51] offset:7616
	s_waitcnt lgkmcnt(0)
	ds_read_u16 v3, v1
	s_waitcnt lgkmcnt(0)
	v_lshlrev_b32_e32 v3, 16, v3
	v_mul_f32_e32 v48, 0xbfb8aa3b, v3
	v_exp_f32_e32 v48, v48
	s_waitcnt vmcnt(0)
	v_mul_f32_e32 v47, v47, v232
	v_add_f32_e32 v48, 1.0, v48
	v_rcp_f32_e32 v49, v48
	s_nop 0
	v_mul_f32_e32 v3, v3, v49
	v_mul_f32_e32 v3, v47, v3
	v_cvt_pk_bf16_f32 v3, v3, v3
	ds_write_b16 v1, v3
	ds_read_u16 v3, v1 offset:272
	s_waitcnt lgkmcnt(0)
	v_lshlrev_b32_e32 v3, 16, v3
	v_mul_f32_e32 v48, 0xbfb8aa3b, v3
	v_exp_f32_e32 v48, v48
	v_mul_f32_e32 v47, v137, v45
	v_add_f32_e32 v48, 1.0, v48
	v_rcp_f32_e32 v49, v48
	v_mul_f32_e32 v47, v47, v232
	v_mul_f32_e32 v3, v3, v49
	v_mul_f32_e32 v3, v47, v3
	v_cvt_pk_bf16_f32 v3, v3, v3
	ds_write_b16 v1, v3 offset:272
	ds_read_u16 v3, v1 offset:544
	s_waitcnt lgkmcnt(0)
	v_lshlrev_b32_e32 v3, 16, v3
	v_mul_f32_e32 v48, 0xbfb8aa3b, v3
	v_exp_f32_e32 v48, v48
	v_mul_f32_e32 v47, v136, v44
	v_add_f32_e32 v48, 1.0, v48
	v_rcp_f32_e32 v49, v48
	v_mul_f32_e32 v47, v47, v232
	v_mul_f32_e32 v3, v3, v49
	v_mul_f32_e32 v3, v47, v3
	v_cvt_pk_bf16_f32 v3, v3, v3
	ds_write_b16 v1, v3 offset:544
	ds_read_u16 v3, v1 offset:816
	s_waitcnt lgkmcnt(0)
	v_lshlrev_b32_e32 v3, 16, v3
	v_mul_f32_e32 v48, 0xbfb8aa3b, v3
	v_exp_f32_e32 v48, v48
	v_mul_f32_e32 v47, v135, v43
	v_add_f32_e32 v48, 1.0, v48
	v_rcp_f32_e32 v49, v48
	v_mul_f32_e32 v47, v47, v232
	v_mul_f32_e32 v3, v3, v49
	v_mul_f32_e32 v3, v47, v3
	v_cvt_pk_bf16_f32 v3, v3, v3
	ds_write_b16 v1, v3 offset:816
	ds_read_u16 v3, v1 offset:2176
	s_waitcnt lgkmcnt(0)
	v_lshlrev_b32_e32 v3, 16, v3
	v_mul_f32_e32 v48, 0xbfb8aa3b, v3
	v_exp_f32_e32 v48, v48
	v_mul_f32_e32 v47, v134, v42
	v_add_f32_e32 v48, 1.0, v48
	v_rcp_f32_e32 v49, v48
	v_mul_f32_e32 v47, v47, v232
	v_mul_f32_e32 v3, v3, v49
	v_mul_f32_e32 v3, v47, v3
	v_cvt_pk_bf16_f32 v3, v3, v3
	ds_write_b16 v1, v3 offset:2176
	ds_read_u16 v3, v1 offset:2448
	s_waitcnt lgkmcnt(0)
	v_lshlrev_b32_e32 v3, 16, v3
	v_mul_f32_e32 v48, 0xbfb8aa3b, v3
	v_exp_f32_e32 v48, v48
	v_mul_f32_e32 v47, v133, v41
	v_add_f32_e32 v48, 1.0, v48
	v_rcp_f32_e32 v49, v48
	v_mul_f32_e32 v47, v47, v232
	v_mul_f32_e32 v3, v3, v49
	v_mul_f32_e32 v3, v47, v3
	v_cvt_pk_bf16_f32 v3, v3, v3
	ds_write_b16 v1, v3 offset:2448
	ds_read_u16 v3, v1 offset:2720
	s_waitcnt lgkmcnt(0)
; #define LAS __attribute__((address_space(3)))
; DI unsigned cvtpk(float lo, float hi) { f32x2 v = {lo, hi}; bf16x2_t b = __builtin_convertvector(v, bf16x2_t); return __builtin_bit_cast(unsigned, b); }
; DI float bf2f(bf16 b) { return __uint_as_float(((unsigned)b) << 16); }
; DI float siluf_(float x) { return x / (1.f + __expf(-x)); }
; DI void gla_stage3(const Ctx& c0, int layer, int unit, int cb, LAS unsigned char* lds) {
;     ...
;     for (int vb = 0; vb < 4; ++vb) { const float g = gn[32 * vb + r];
; #pragma unroll
;         for (int rg = 0; rg < 16; ++rg) { LAS bf16* e = (LAS bf16*)(R + (4 * hi) * G3_PITCH + r * 2 + ((rg & 3) + 8 * (rg >> 2)) * G3_PITCH + 64 * vb);
;             const float z = bf2f(*e);
;             *e = (bf16)(cvtpk(o[vb][rg] * rs[rg] * g * siluf_(z), 0.f) & 0xffffu); }
	v_lshlrev_b32_e32 v3, 16, v3
	v_mul_f32_e32 v48, 0xbfb8aa3b, v3
	v_exp_f32_e32 v48, v48
	v_mul_f32_e32 v47, v132, v40
	v_add_f32_e32 v48, 1.0, v48
	v_rcp_f32_e32 v49, v48
	v_mul_f32_e32 v47, v47, v232
	v_mul_f32_e32 v3, v3, v49
	v_mul_f32_e32 v3, v47, v3
	v_cvt_pk_bf16_f32 v3, v3, v3
	ds_write_b16 v1, v3 offset:2720
	ds_read_u16 v3, v1 offset:2992
	s_waitcnt lgkmcnt(0)
	v_lshlrev_b32_e32 v3, 16, v3
	v_mul_f32_e32 v48, 0xbfb8aa3b, v3
	v_exp_f32_e32 v48, v48
	v_mul_f32_e32 v47, v131, v35
	v_add_f32_e32 v48, 1.0, v48
	v_rcp_f32_e32 v49, v48
	v_mul_f32_e32 v47, v47, v232
	v_mul_f32_e32 v3, v3, v49
	v_mul_f32_e32 v3, v47, v3
	v_cvt_pk_bf16_f32 v3, v3, v3
	ds_write_b16 v1, v3 offset:2992
	ds_read_u16 v3, v1 offset:4352
	s_waitcnt lgkmcnt(0)
	v_lshlrev_b32_e32 v3, 16, v3
	v_mul_f32_e32 v48, 0xbfb8aa3b, v3
	v_exp_f32_e32 v48, v48
	v_mul_f32_e32 v47, v130, v31
	v_add_f32_e32 v48, 1.0, v48
	v_rcp_f32_e32 v49, v48
	v_mul_f32_e32 v47, v47, v232
	v_mul_f32_e32 v3, v3, v49
	v_mul_f32_e32 v3, v47, v3
	v_cvt_pk_bf16_f32 v3, v3, v3
	ds_write_b16 v1, v3 offset:4352
	ds_read_u16 v3, v1 offset:4624
	s_waitcnt lgkmcnt(0)
	v_lshlrev_b32_e32 v3, 16, v3
	v_mul_f32_e32 v48, 0xbfb8aa3b, v3
	v_exp_f32_e32 v48, v48
	v_mul_f32_e32 v47, v129, v27
	v_add_f32_e32 v48, 1.0, v48
	v_rcp_f32_e32 v49, v48
	v_mul_f32_e32 v47, v47, v232
	v_mul_f32_e32 v3, v3, v49
	v_mul_f32_e32 v3, v47, v3
	v_cvt_pk_bf16_f32 v3, v3, v3
	ds_write_b16 v1, v3 offset:4624
	ds_read_u16 v3, v1 offset:4896
	s_waitcnt lgkmcnt(0)
	v_lshlrev_b32_e32 v3, 16, v3
	v_mul_f32_e32 v48, 0xbfb8aa3b, v3
	v_exp_f32_e32 v48, v48
	v_mul_f32_e32 v47, v128, v25
	v_add_f32_e32 v48, 1.0, v48
	v_rcp_f32_e32 v49, v48
	v_mul_f32_e32 v47, v47, v232
	v_mul_f32_e32 v3, v3, v49
	v_mul_f32_e32 v3, v47, v3
	v_cvt_pk_bf16_f32 v3, v3, v3
	ds_write_b16 v1, v3 offset:4896
	ds_read_u16 v3, v1 offset:5168
	s_waitcnt lgkmcnt(0)
	v_lshlrev_b32_e32 v3, 16, v3
	v_mul_f32_e32 v48, 0xbfb8aa3b, v3
	v_exp_f32_e32 v48, v48
	v_mul_f32_e32 v47, v127, v24
	v_add_f32_e32 v48, 1.0, v48
	v_rcp_f32_e32 v49, v48
	v_mul_f32_e32 v47, v47, v232
	v_mul_f32_e32 v3, v3, v49
	v_mul_f32_e32 v3, v47, v3
	v_cvt_pk_bf16_f32 v3, v3, v3
	ds_write_b16 v1, v3 offset:5168
	ds_read_u16 v3, v1 offset:6528
	s_waitcnt lgkmcnt(0)
	v_lshlrev_b32_e32 v3, 16, v3
	v_mul_f32_e32 v48, 0xbfb8aa3b, v3
	v_exp_f32_e32 v48, v48
	v_mul_f32_e32 v47, v126, v23
	v_add_f32_e32 v48, 1.0, v48
	v_rcp_f32_e32 v49, v48
	v_mul_f32_e32 v47, v47, v232
	v_mul_f32_e32 v3, v3, v49
	v_mul_f32_e32 v3, v47, v3
	v_cvt_pk_bf16_f32 v3, v3, v3
	ds_write_b16 v1, v3 offset:6528
	ds_read_u16 v3, v1 offset:6800
	s_waitcnt lgkmcnt(0)
	v_lshlrev_b32_e32 v3, 16, v3
	v_mul_f32_e32 v48, 0xbfb8aa3b, v3
	v_exp_f32_e32 v48, v48
	v_mul_f32_e32 v47, v125, v22
	v_add_f32_e32 v48, 1.0, v48
	v_rcp_f32_e32 v49, v48
	v_mul_f32_e32 v47, v47, v232
	v_mul_f32_e32 v3, v3, v49
	v_mul_f32_e32 v3, v47, v3
	v_cvt_pk_bf16_f32 v3, v3, v3
	ds_write_b16 v1, v3 offset:6800
	ds_read_u16 v3, v1 offset:7072
	s_waitcnt lgkmcnt(0)
	v_lshlrev_b32_e32 v3, 16, v3
	v_mul_f32_e32 v48, 0xbfb8aa3b, v3
	v_exp_f32_e32 v48, v48
	v_mul_f32_e32 v47, v124, v21
	v_add_f32_e32 v48, 1.0, v48
	v_rcp_f32_e32 v49, v48
	v_mul_f32_e32 v47, v47, v232
	v_mul_f32_e32 v3, v3, v49
	v_mul_f32_e32 v3, v47, v3
	v_cvt_pk_bf16_f32 v3, v3, v3
	ds_write_b16 v1, v3 offset:7072
	ds_read_u16 v3, v1 offset:7344
	v_mul_f32_e32 v47, v123, v20
	v_mul_f32_e32 v2, v47, v232
	s_waitcnt lgkmcnt(0)
	v_lshlrev_b32_e32 v3, 16, v3
	v_mul_f32_e32 v47, 0xbfb8aa3b, v3
	v_exp_f32_e32 v47, v47
	s_nop 0
	v_add_f32_e32 v47, 1.0, v47
	v_div_scale_f32 v48, s[0:1], v47, v47, v3
	s_nop 0
	v_rcp_f32_e32 v48, v47
	s_nop 0
	v_mul_f32_e32 v3, v3, v48
	v_mul_f32_e32 v2, v2, v3
	v_cvt_pk_bf16_f32 v2, v2, s0
	ds_write_b16 v1, v2 offset:7344
	ds_read_u16 v3, v1 offset:64
	v_mul_f32_e32 v47, v122, v46
	s_waitcnt lgkmcnt(0)
	v_lshlrev_b32_e32 v3, 16, v3
	v_mul_f32_e32 v48, 0xbfb8aa3b, v3
	v_exp_f32_e32 v48, v48
	s_waitcnt vmcnt(0)
	v_mul_f32_e32 v47, v47, v234
	v_add_f32_e32 v48, 1.0, v48
	v_rcp_f32_e32 v49, v48
	s_nop 0
	v_mul_f32_e32 v3, v3, v49
	v_mul_f32_e32 v3, v47, v3
	v_cvt_pk_bf16_f32 v3, v3, v3
	ds_write_b16 v1, v3 offset:64
	ds_read_u16 v3, v1 offset:336
	s_waitcnt lgkmcnt(0)
	v_lshlrev_b32_e32 v3, 16, v3
	v_mul_f32_e32 v48, 0xbfb8aa3b, v3
	v_exp_f32_e32 v48, v48
	v_mul_f32_e32 v47, v121, v45
	v_add_f32_e32 v48, 1.0, v48
	v_rcp_f32_e32 v49, v48
	v_mul_f32_e32 v47, v47, v234
	v_mul_f32_e32 v3, v3, v49
	v_mul_f32_e32 v3, v47, v3
	v_cvt_pk_bf16_f32 v3, v3, v3
	ds_write_b16 v1, v3 offset:336
	ds_read_u16 v3, v1 offset:608
	s_waitcnt lgkmcnt(0)
	v_lshlrev_b32_e32 v3, 16, v3
	v_mul_f32_e32 v48, 0xbfb8aa3b, v3
	v_exp_f32_e32 v48, v48
	v_mul_f32_e32 v47, v120, v44
	v_add_f32_e32 v48, 1.0, v48
	v_rcp_f32_e32 v49, v48
	v_mul_f32_e32 v47, v47, v234
	v_mul_f32_e32 v3, v3, v49
	v_mul_f32_e32 v3, v47, v3
	v_cvt_pk_bf16_f32 v3, v3, v3
	ds_write_b16 v1, v3 offset:608
	ds_read_u16 v3, v1 offset:880
	s_waitcnt lgkmcnt(0)
	v_lshlrev_b32_e32 v3, 16, v3
	v_mul_f32_e32 v48, 0xbfb8aa3b, v3
	v_exp_f32_e32 v48, v48
	v_mul_f32_e32 v47, v119, v43
	v_add_f32_e32 v48, 1.0, v48
	v_rcp_f32_e32 v49, v48
	v_mul_f32_e32 v47, v47, v234
	v_mul_f32_e32 v3, v3, v49
	v_mul_f32_e32 v3, v47, v3
	v_cvt_pk_bf16_f32 v3, v3, v3
	ds_write_b16 v1, v3 offset:880
	ds_read_u16 v3, v1 offset:2240
	s_waitcnt lgkmcnt(0)
	v_lshlrev_b32_e32 v3, 16, v3
	v_mul_f32_e32 v48, 0xbfb8aa3b, v3
	v_exp_f32_e32 v48, v48
	v_mul_f32_e32 v47, v118, v42
	v_add_f32_e32 v48, 1.0, v48
	v_rcp_f32_e32 v49, v48
	v_mul_f32_e32 v47, v47, v234
	v_mul_f32_e32 v3, v3, v49
	v_mul_f32_e32 v3, v47, v3
	v_cvt_pk_bf16_f32 v3, v3, v3
	ds_write_b16 v1, v3 offset:2240
	ds_read_u16 v3, v1 offset:2512
	s_waitcnt lgkmcnt(0)
; #define LAS __attribute__((address_space(3)))
; DI unsigned cvtpk(float lo, float hi) { f32x2 v = {lo, hi}; bf16x2_t b = __builtin_convertvector(v, bf16x2_t); return __builtin_bit_cast(unsigned, b); }
; DI float bf2f(bf16 b) { return __uint_as_float(((unsigned)b) << 16); }
; DI float siluf_(float x) { return x / (1.f + __expf(-x)); }
; DI void gla_stage3(const Ctx& c0, int layer, int unit, int cb, LAS unsigned char* lds) {
;     ...
;     for (int vb = 0; vb < 4; ++vb) { const float g = gn[32 * vb + r];
; #pragma unroll
;         for (int rg = 0; rg < 16; ++rg) { LAS bf16* e = (LAS bf16*)(R + (4 * hi) * G3_PITCH + r * 2 + ((rg & 3) + 8 * (rg >> 2)) * G3_PITCH + 64 * vb);
;             const float z = bf2f(*e);
;             *e = (bf16)(cvtpk(o[vb][rg] * rs[rg] * g * siluf_(z), 0.f) & 0xffffu); }
	v_lshlrev_b32_e32 v3, 16, v3
	v_mul_f32_e32 v48, 0xbfb8aa3b, v3
	v_exp_f32_e32 v48, v48
	v_mul_f32_e32 v47, v117, v41
	v_add_f32_e32 v48, 1.0, v48
	v_rcp_f32_e32 v49, v48
	v_mul_f32_e32 v47, v47, v234
	v_mul_f32_e32 v3, v3, v49
	v_mul_f32_e32 v3, v47, v3
	v_cvt_pk_bf16_f32 v3, v3, v3
	ds_write_b16 v1, v3 offset:2512
	ds_read_u16 v3, v1 offset:2784
	s_waitcnt lgkmcnt(0)
	v_lshlrev_b32_e32 v3, 16, v3
	v_mul_f32_e32 v48, 0xbfb8aa3b, v3
	v_exp_f32_e32 v48, v48
	v_mul_f32_e32 v47, v116, v40
	v_add_f32_e32 v48, 1.0, v48
	v_rcp_f32_e32 v49, v48
	v_mul_f32_e32 v47, v47, v234
	v_mul_f32_e32 v3, v3, v49
	v_mul_f32_e32 v3, v47, v3
	v_cvt_pk_bf16_f32 v3, v3, v3
	ds_write_b16 v1, v3 offset:2784
	ds_read_u16 v3, v1 offset:3056
	s_waitcnt lgkmcnt(0)
	v_lshlrev_b32_e32 v3, 16, v3
	v_mul_f32_e32 v48, 0xbfb8aa3b, v3
	v_exp_f32_e32 v48, v48
	v_mul_f32_e32 v47, v115, v35
	v_add_f32_e32 v48, 1.0, v48
	v_rcp_f32_e32 v49, v48
	v_mul_f32_e32 v47, v47, v234
	v_mul_f32_e32 v3, v3, v49
	v_mul_f32_e32 v3, v47, v3
	v_cvt_pk_bf16_f32 v3, v3, v3
	ds_write_b16 v1, v3 offset:3056
	ds_read_u16 v3, v1 offset:4416
	s_waitcnt lgkmcnt(0)
	v_lshlrev_b32_e32 v3, 16, v3
	v_mul_f32_e32 v48, 0xbfb8aa3b, v3
	v_exp_f32_e32 v48, v48
	v_mul_f32_e32 v47, v114, v31
	v_add_f32_e32 v48, 1.0, v48
	v_rcp_f32_e32 v49, v48
	v_mul_f32_e32 v47, v47, v234
	v_mul_f32_e32 v3, v3, v49
	v_mul_f32_e32 v3, v47, v3
	v_cvt_pk_bf16_f32 v3, v3, v3
	ds_write_b16 v1, v3 offset:4416
	ds_read_u16 v3, v1 offset:4688
	s_waitcnt lgkmcnt(0)
	v_lshlrev_b32_e32 v3, 16, v3
	v_mul_f32_e32 v48, 0xbfb8aa3b, v3
	v_exp_f32_e32 v48, v48
	v_mul_f32_e32 v47, v113, v27
	v_add_f32_e32 v48, 1.0, v48
	v_rcp_f32_e32 v49, v48
	v_mul_f32_e32 v47, v47, v234
	v_mul_f32_e32 v3, v3, v49
	v_mul_f32_e32 v3, v47, v3
	v_cvt_pk_bf16_f32 v3, v3, v3
	ds_write_b16 v1, v3 offset:4688
	ds_read_u16 v3, v1 offset:4960
	s_waitcnt lgkmcnt(0)
	v_lshlrev_b32_e32 v3, 16, v3
	v_mul_f32_e32 v48, 0xbfb8aa3b, v3
	v_exp_f32_e32 v48, v48
	v_mul_f32_e32 v47, v112, v25
	v_add_f32_e32 v48, 1.0, v48
	v_rcp_f32_e32 v49, v48
	v_mul_f32_e32 v47, v47, v234
	v_mul_f32_e32 v3, v3, v49
	v_mul_f32_e32 v3, v47, v3
	v_cvt_pk_bf16_f32 v3, v3, v3
	ds_write_b16 v1, v3 offset:4960
	ds_read_u16 v3, v1 offset:5232
	s_waitcnt lgkmcnt(0)
	v_lshlrev_b32_e32 v3, 16, v3
	v_mul_f32_e32 v48, 0xbfb8aa3b, v3
	v_exp_f32_e32 v48, v48
	v_mul_f32_e32 v47, v111, v24
	v_add_f32_e32 v48, 1.0, v48
	v_rcp_f32_e32 v49, v48
	v_mul_f32_e32 v47, v47, v234
	v_mul_f32_e32 v3, v3, v49
	v_mul_f32_e32 v3, v47, v3
	v_cvt_pk_bf16_f32 v3, v3, v3
	ds_write_b16 v1, v3 offset:5232
	ds_read_u16 v3, v1 offset:6592
	s_waitcnt lgkmcnt(0)
	v_lshlrev_b32_e32 v3, 16, v3
	v_mul_f32_e32 v48, 0xbfb8aa3b, v3
	v_exp_f32_e32 v48, v48
	v_mul_f32_e32 v47, v110, v23
	v_add_f32_e32 v48, 1.0, v48
	v_rcp_f32_e32 v49, v48
	v_mul_f32_e32 v47, v47, v234
	v_mul_f32_e32 v3, v3, v49
	v_mul_f32_e32 v3, v47, v3
	v_cvt_pk_bf16_f32 v3, v3, v3
	ds_write_b16 v1, v3 offset:6592
	ds_read_u16 v3, v1 offset:6864
	s_waitcnt lgkmcnt(0)
	v_lshlrev_b32_e32 v3, 16, v3
	v_mul_f32_e32 v48, 0xbfb8aa3b, v3
	v_exp_f32_e32 v48, v48
	v_mul_f32_e32 v47, v109, v22
	v_add_f32_e32 v48, 1.0, v48
	v_rcp_f32_e32 v49, v48
	v_mul_f32_e32 v47, v47, v234
	v_mul_f32_e32 v3, v3, v49
	v_mul_f32_e32 v3, v47, v3
	v_cvt_pk_bf16_f32 v3, v3, v3
	ds_write_b16 v1, v3 offset:6864
	ds_read_u16 v3, v1 offset:7136
	s_waitcnt lgkmcnt(0)
	v_lshlrev_b32_e32 v3, 16, v3
	v_mul_f32_e32 v48, 0xbfb8aa3b, v3
	v_exp_f32_e32 v48, v48
	v_mul_f32_e32 v47, v108, v21
	v_add_f32_e32 v48, 1.0, v48
	v_rcp_f32_e32 v49, v48
	v_mul_f32_e32 v47, v47, v234
	v_mul_f32_e32 v3, v3, v49
	v_mul_f32_e32 v3, v47, v3
	v_cvt_pk_bf16_f32 v3, v3, v3
	ds_write_b16 v1, v3 offset:7136
	ds_read_u16 v3, v1 offset:7408
	v_mul_f32_e32 v47, v107, v20
	v_mul_f32_e32 v2, v47, v234
	s_waitcnt lgkmcnt(0)
	v_lshlrev_b32_e32 v3, 16, v3
	v_mul_f32_e32 v47, 0xbfb8aa3b, v3
	v_exp_f32_e32 v47, v47
	s_nop 0
	v_add_f32_e32 v47, 1.0, v47
	v_div_scale_f32 v48, s[0:1], v47, v47, v3
	s_nop 0
	v_rcp_f32_e32 v48, v47
	s_nop 0
	v_mul_f32_e32 v3, v3, v48
	v_mul_f32_e32 v2, v2, v3
	v_cvt_pk_bf16_f32 v2, v2, s0
	ds_write_b16 v1, v2 offset:7408
	ds_read_u16 v3, v1 offset:128
	v_mul_f32_e32 v47, v106, v46
	s_waitcnt lgkmcnt(0)
	v_lshlrev_b32_e32 v3, 16, v3
	v_mul_f32_e32 v48, 0xbfb8aa3b, v3
	v_exp_f32_e32 v48, v48
	s_waitcnt vmcnt(0)
	v_mul_f32_e32 v47, v47, v236
	v_add_f32_e32 v48, 1.0, v48
	v_div_scale_f32 v49, s[0:1], v48, v48, v3
	v_mul_f32_e32 v39, v39, v236
	v_mul_f32_e32 v38, v38, v236
	v_mul_f32_e32 v37, v37, v236
	v_rcp_f32_e32 v49, v48
	s_nop 0
	v_mul_f32_e32 v3, v3, v49
	v_mul_f32_e32 v3, v47, v3
	v_cvt_pk_bf16_f32 v3, v3, s0
	ds_write_b16 v1, v3 offset:128
	ds_read_u16 v3, v1 offset:400
	v_mul_f32_e32 v47, v105, v45
	v_mul_f32_e32 v47, v47, v236
	v_mul_f32_e32 v36, v36, v236
	v_mul_f32_e32 v34, v34, v236
	s_waitcnt lgkmcnt(0)
	v_lshlrev_b32_e32 v3, 16, v3
	v_mul_f32_e32 v48, 0xbfb8aa3b, v3
	v_exp_f32_e32 v48, v48
	v_mul_f32_e32 v33, v33, v236
	v_mul_f32_e32 v32, v32, v236
	v_mul_f32_e32 v30, v30, v236
	v_add_f32_e32 v48, 1.0, v48
	v_div_scale_f32 v49, s[0:1], v48, v48, v3
	v_mul_f32_e32 v29, v29, v236
	v_mul_f32_e32 v28, v28, v236
	v_rcp_f32_e32 v49, v48
	s_nop 0
	v_mul_f32_e32 v3, v3, v49
	v_mul_f32_e32 v3, v47, v3
	v_cvt_pk_bf16_f32 v3, v3, s0
	ds_write_b16 v1, v3 offset:400
	ds_read_u16 v3, v1 offset:672
	s_waitcnt lgkmcnt(0)
	v_lshlrev_b32_e32 v3, 16, v3
	v_mul_f32_e32 v48, 0xbfb8aa3b, v3
	v_exp_f32_e32 v48, v48
	v_mul_f32_e32 v47, v104, v44
	v_add_f32_e32 v48, 1.0, v48
	v_rcp_f32_e32 v49, v48
	v_mul_f32_e32 v47, v47, v236
	v_mul_f32_e32 v3, v3, v49
	v_mul_f32_e32 v3, v47, v3
	v_cvt_pk_bf16_f32 v3, v3, v3
	ds_write_b16 v1, v3 offset:672
	ds_read_u16 v3, v1 offset:944
	s_waitcnt lgkmcnt(0)
; #define LAS __attribute__((address_space(3)))
; DI unsigned cvtpk(float lo, float hi) { f32x2 v = {lo, hi}; bf16x2_t b = __builtin_convertvector(v, bf16x2_t); return __builtin_bit_cast(unsigned, b); }
; DI float bf2f(bf16 b) { return __uint_as_float(((unsigned)b) << 16); }
; DI float siluf_(float x) { return x / (1.f + __expf(-x)); }
; DI void gla_stage3(const Ctx& c0, int layer, int unit, int cb, LAS unsigned char* lds) {
;     ...
;     for (int vb = 0; vb < 4; ++vb) { const float g = gn[32 * vb + r];
; #pragma unroll
;         for (int rg = 0; rg < 16; ++rg) { LAS bf16* e = (LAS bf16*)(R + (4 * hi) * G3_PITCH + r * 2 + ((rg & 3) + 8 * (rg >> 2)) * G3_PITCH + 64 * vb);
;             const float z = bf2f(*e);
;             *e = (bf16)(cvtpk(o[vb][rg] * rs[rg] * g * siluf_(z), 0.f) & 0xffffu); }
	v_lshlrev_b32_e32 v3, 16, v3
	v_mul_f32_e32 v48, 0xbfb8aa3b, v3
	v_exp_f32_e32 v48, v48
	v_mul_f32_e32 v47, v103, v43
	v_add_f32_e32 v48, 1.0, v48
	v_rcp_f32_e32 v49, v48
	v_mul_f32_e32 v47, v47, v236
	v_mul_f32_e32 v3, v3, v49
	v_mul_f32_e32 v3, v47, v3
	v_cvt_pk_bf16_f32 v3, v3, v3
	ds_write_b16 v1, v3 offset:944
	ds_read_u16 v3, v1 offset:2304
	v_mul_f32_e32 v47, v102, v42
	v_mul_f32_e32 v47, v47, v236
	v_mul_f32_e32 v2, v26, v236
	s_waitcnt lgkmcnt(0)
	v_lshlrev_b32_e32 v3, 16, v3
	v_mul_f32_e32 v48, 0xbfb8aa3b, v3
	v_exp_f32_e32 v48, v48
	s_nop 0
	v_add_f32_e32 v48, 1.0, v48
	v_rcp_f32_e32 v49, v48
	s_nop 0
	v_mul_f32_e32 v3, v3, v49
	v_mul_f32_e32 v3, v47, v3
	v_cvt_pk_bf16_f32 v3, v3, v3
	ds_write_b16 v1, v3 offset:2304
	ds_read_u16 v3, v1 offset:2576
	s_waitcnt lgkmcnt(0)
	v_lshlrev_b32_e32 v3, 16, v3
	v_mul_f32_e32 v47, 0xbfb8aa3b, v3
	v_exp_f32_e32 v47, v47
	s_nop 0
	v_add_f32_e32 v47, 1.0, v47
	v_rcp_f32_e32 v48, v47
	s_nop 0
	v_mul_f32_e32 v3, v3, v48
	v_mul_f32_e32 v3, v39, v3
	v_cvt_pk_bf16_f32 v3, v3, v3
	ds_write_b16 v1, v3 offset:2576
	ds_read_u16 v3, v1 offset:2848
	s_waitcnt lgkmcnt(0)
	v_lshlrev_b32_e32 v3, 16, v3
	v_mul_f32_e32 v39, 0xbfb8aa3b, v3
	v_exp_f32_e32 v39, v39
	s_nop 0
	v_add_f32_e32 v39, 1.0, v39
	v_rcp_f32_e32 v47, v39
	s_nop 0
	v_mul_f32_e32 v3, v3, v47
	v_mul_f32_e32 v3, v38, v3
	v_cvt_pk_bf16_f32 v3, v3, v3
	ds_write_b16 v1, v3 offset:2848
	ds_read_u16 v3, v1 offset:3120
	s_waitcnt lgkmcnt(0)
	v_lshlrev_b32_e32 v3, 16, v3
	v_mul_f32_e32 v38, 0xbfb8aa3b, v3
	v_exp_f32_e32 v38, v38
	s_nop 0
	v_add_f32_e32 v38, 1.0, v38
	v_rcp_f32_e32 v39, v38
	s_nop 0
	v_mul_f32_e32 v3, v3, v39
	v_mul_f32_e32 v3, v37, v3
	v_cvt_pk_bf16_f32 v3, v3, v3
	ds_write_b16 v1, v3 offset:3120
	ds_read_u16 v3, v1 offset:4480
	s_waitcnt lgkmcnt(0)
	v_lshlrev_b32_e32 v3, 16, v3
	v_mul_f32_e32 v37, 0xbfb8aa3b, v3
	v_exp_f32_e32 v37, v37
	s_nop 0
	v_add_f32_e32 v37, 1.0, v37
	v_rcp_f32_e32 v38, v37
	s_nop 0
	v_mul_f32_e32 v3, v3, v38
	v_mul_f32_e32 v3, v36, v3
	v_cvt_pk_bf16_f32 v3, v3, v3
	ds_write_b16 v1, v3 offset:4480
	ds_read_u16 v3, v1 offset:4752
	s_waitcnt lgkmcnt(0)
	v_lshlrev_b32_e32 v3, 16, v3
	v_mul_f32_e32 v36, 0xbfb8aa3b, v3
	v_exp_f32_e32 v36, v36
	s_nop 0
	v_add_f32_e32 v36, 1.0, v36
	v_rcp_f32_e32 v37, v36
	s_nop 0
	v_mul_f32_e32 v3, v3, v37
	v_mul_f32_e32 v3, v34, v3
	v_cvt_pk_bf16_f32 v3, v3, v3
	ds_write_b16 v1, v3 offset:4752
	ds_read_u16 v3, v1 offset:5024
	s_waitcnt lgkmcnt(0)
	v_lshlrev_b32_e32 v3, 16, v3
	v_mul_f32_e32 v34, 0xbfb8aa3b, v3
	v_exp_f32_e32 v34, v34
	s_nop 0
	v_add_f32_e32 v34, 1.0, v34
	v_rcp_f32_e32 v36, v34
	s_nop 0
	v_mul_f32_e32 v3, v3, v36
	v_mul_f32_e32 v3, v33, v3
	v_cvt_pk_bf16_f32 v3, v3, v3
	ds_write_b16 v1, v3 offset:5024
	ds_read_u16 v3, v1 offset:5296
	s_waitcnt lgkmcnt(0)
	v_lshlrev_b32_e32 v3, 16, v3
	v_mul_f32_e32 v33, 0xbfb8aa3b, v3
	v_exp_f32_e32 v33, v33
	s_nop 0
	v_add_f32_e32 v33, 1.0, v33
	v_rcp_f32_e32 v34, v33
	s_nop 0
	v_mul_f32_e32 v3, v3, v34
	v_mul_f32_e32 v3, v32, v3
	v_cvt_pk_bf16_f32 v3, v3, v3
	ds_write_b16 v1, v3 offset:5296
	ds_read_u16 v3, v1 offset:6656
	s_waitcnt lgkmcnt(0)
	v_lshlrev_b32_e32 v3, 16, v3
	v_mul_f32_e32 v32, 0xbfb8aa3b, v3
	v_exp_f32_e32 v32, v32
	s_nop 0
	v_add_f32_e32 v32, 1.0, v32
	v_rcp_f32_e32 v33, v32
	s_nop 0
	v_mul_f32_e32 v3, v3, v33
	v_mul_f32_e32 v3, v30, v3
	v_cvt_pk_bf16_f32 v3, v3, v3
	ds_write_b16 v1, v3 offset:6656
	ds_read_u16 v3, v1 offset:6928
	s_waitcnt lgkmcnt(0)
	v_lshlrev_b32_e32 v3, 16, v3
	v_mul_f32_e32 v30, 0xbfb8aa3b, v3
	v_exp_f32_e32 v30, v30
	s_nop 0
	v_add_f32_e32 v30, 1.0, v30
	v_rcp_f32_e32 v32, v30
	s_nop 0
	v_mul_f32_e32 v3, v3, v32
	v_mul_f32_e32 v3, v29, v3
	v_cvt_pk_bf16_f32 v3, v3, v3
	ds_write_b16 v1, v3 offset:6928
	ds_read_u16 v3, v1 offset:7200
	s_waitcnt lgkmcnt(0)
	v_lshlrev_b32_e32 v3, 16, v3
	v_mul_f32_e32 v29, 0xbfb8aa3b, v3
	v_exp_f32_e32 v29, v29
	s_nop 0
	v_add_f32_e32 v29, 1.0, v29
	v_rcp_f32_e32 v30, v29
	s_nop 0
	v_mul_f32_e32 v3, v3, v30
	v_mul_f32_e32 v3, v28, v3
	v_cvt_pk_bf16_f32 v3, v3, v3
	ds_write_b16 v1, v3 offset:7200
	ds_read_u16 v3, v1 offset:7472
	s_waitcnt lgkmcnt(0)
	v_lshlrev_b32_e32 v3, 16, v3
	v_mul_f32_e32 v26, 0xbfb8aa3b, v3
	v_exp_f32_e32 v26, v26
	s_nop 0
	v_add_f32_e32 v26, 1.0, v26
	v_div_scale_f32 v28, s[0:1], v26, v26, v3
	s_nop 0
	v_rcp_f32_e32 v28, v26
	s_nop 0
	v_mul_f32_e32 v3, v3, v28
	v_mul_f32_e32 v2, v2, v3
	v_cvt_pk_bf16_f32 v2, v2, s0
	ds_write_b16 v1, v2 offset:7472
	ds_read_u16 v3, v1 offset:192
	s_waitcnt lgkmcnt(0)
	v_lshlrev_b32_e32 v3, 16, v3
	v_mul_f32_e32 v26, 0xbfb8aa3b, v3
	v_exp_f32_e32 v26, v26
	s_waitcnt vmcnt(31)
	v_mul_f32_e32 v19, v19, v238
	v_add_f32_e32 v26, 1.0, v26
	v_div_scale_f32 v28, s[0:1], v26, v26, v3
	v_mul_f32_e32 v18, v18, v238
	v_mul_f32_e32 v17, v17, v238
	v_mul_f32_e32 v16, v16, v238
	v_rcp_f32_e32 v28, v26
	s_nop 0
	v_mul_f32_e32 v3, v3, v28
	v_mul_f32_e32 v3, v19, v3
	v_cvt_pk_bf16_f32 v3, v3, s0
	ds_write_b16 v1, v3 offset:192
	ds_read_u16 v3, v1 offset:464
	v_mul_f32_e32 v15, v15, v238
	v_mul_f32_e32 v14, v14, v238
	v_mul_f32_e32 v13, v13, v238
	v_mul_f32_e32 v12, v12, v238
	s_waitcnt lgkmcnt(0)
	v_lshlrev_b32_e32 v3, 16, v3
	v_mul_f32_e32 v19, 0xbfb8aa3b, v3
	v_exp_f32_e32 v19, v19
	v_mul_f32_e32 v11, v11, v238
	v_mul_f32_e32 v10, v10, v238
	v_mul_f32_e32 v9, v9, v238
	v_add_f32_e32 v19, 1.0, v19
	v_div_scale_f32 v26, s[0:1], v19, v19, v3
	v_mul_f32_e32 v8, v8, v238
	v_mul_f32_e32 v7, v7, v238
	v_mul_f32_e32 v6, v6, v238
	v_rcp_f32_e32 v26, v19
	s_nop 0
	v_mul_f32_e32 v3, v3, v26
	v_mul_f32_e32 v3, v18, v3
	v_cvt_pk_bf16_f32 v3, v3, s0
	ds_write_b16 v1, v3 offset:464
	ds_read_u16 v3, v1 offset:736
	v_mul_f32_e32 v5, v5, v238
	v_mul_f32_e32 v2, v4, v238
	s_waitcnt lgkmcnt(0)
; #define LAS __attribute__((address_space(3)))
; #define LDS_WAIT() asm volatile("s_waitcnt lgkmcnt(0)" ::: "memory")
; DI unsigned cvtpk(float lo, float hi) { f32x2 v = {lo, hi}; bf16x2_t b = __builtin_convertvector(v, bf16x2_t); return __builtin_bit_cast(unsigned, b); }
; DI float bf2f(bf16 b) { return __uint_as_float(((unsigned)b) << 16); }
; DI float siluf_(float x) { return x / (1.f + __expf(-x)); }
; DI void g3_tile_out(bf16* g, const LAS unsigned char* R, int lane) {
;     LDS_WAIT();
; #pragma unroll
;     for (int it = 0; it < 8; ++it) { const int row = 4 * it + (lane >> 4), ch = lane & 15;
;         *(u32x4*)(g + (size_t)row * 512 + ch * 8) = *(const LAS u32x4*)(R + row * G3_PITCH + ch * 16); }
;     LDS_WAIT();
; }
; DI void gla_stage3(const Ctx& c0, int layer, int unit, int cb, LAS unsigned char* lds) {
;     ...
;     for (int vb = 0; vb < 4; ++vb) { const float g = gn[32 * vb + r];
; #pragma unroll
;         for (int rg = 0; rg < 16; ++rg) { LAS bf16* e = (LAS bf16*)(R + (4 * hi) * G3_PITCH + r * 2 + ((rg & 3) + 8 * (rg >> 2)) * G3_PITCH + 64 * vb);
;             const float z = bf2f(*e);
;             *e = (bf16)(cvtpk(o[vb][rg] * rs[rg] * g * siluf_(z), 0.f) & 0xffffu); }
;         asm volatile("" ::: "memory"); }
;     g3_tile_out((bf16*)(c.ws + O_OGLA) + row0 * 512 + h * 128, R, lane);
	v_lshlrev_b32_e32 v3, 16, v3
	v_mul_f32_e32 v18, 0xbfb8aa3b, v3
	v_exp_f32_e32 v18, v18
	s_nop 0
	v_add_f32_e32 v18, 1.0, v18
	v_rcp_f32_e32 v19, v18
	s_nop 0
	v_mul_f32_e32 v3, v3, v19
	v_mul_f32_e32 v3, v17, v3
	v_cvt_pk_bf16_f32 v3, v3, v3
	ds_write_b16 v1, v3 offset:736
	ds_read_u16 v3, v1 offset:1008
	s_waitcnt lgkmcnt(0)
	v_lshlrev_b32_e32 v3, 16, v3
	v_mul_f32_e32 v17, 0xbfb8aa3b, v3
	v_exp_f32_e32 v17, v17
	s_nop 0
	v_add_f32_e32 v17, 1.0, v17
	v_rcp_f32_e32 v18, v17
	s_nop 0
	v_mul_f32_e32 v3, v3, v18
	v_mul_f32_e32 v3, v16, v3
	v_cvt_pk_bf16_f32 v3, v3, v3
	ds_write_b16 v1, v3 offset:1008
	ds_read_u16 v3, v1 offset:2368
	s_waitcnt lgkmcnt(0)
	v_lshlrev_b32_e32 v3, 16, v3
	v_mul_f32_e32 v16, 0xbfb8aa3b, v3
	v_exp_f32_e32 v16, v16
	s_nop 0
	v_add_f32_e32 v16, 1.0, v16
	v_rcp_f32_e32 v17, v16
	s_nop 0
	v_mul_f32_e32 v3, v3, v17
	v_mul_f32_e32 v3, v15, v3
	v_cvt_pk_bf16_f32 v3, v3, v3
	ds_write_b16 v1, v3 offset:2368
	ds_read_u16 v3, v1 offset:2640
	s_waitcnt lgkmcnt(0)
	v_lshlrev_b32_e32 v3, 16, v3
	v_mul_f32_e32 v15, 0xbfb8aa3b, v3
	v_exp_f32_e32 v15, v15
	s_nop 0
	v_add_f32_e32 v15, 1.0, v15
	v_rcp_f32_e32 v16, v15
	s_nop 0
	v_mul_f32_e32 v3, v3, v16
	v_mul_f32_e32 v3, v14, v3
	v_cvt_pk_bf16_f32 v3, v3, v3
	ds_write_b16 v1, v3 offset:2640
	ds_read_u16 v3, v1 offset:2912
	s_waitcnt lgkmcnt(0)
	v_lshlrev_b32_e32 v3, 16, v3
	v_mul_f32_e32 v14, 0xbfb8aa3b, v3
	v_exp_f32_e32 v14, v14
	s_nop 0
	v_add_f32_e32 v14, 1.0, v14
	v_rcp_f32_e32 v15, v14
	s_nop 0
	v_mul_f32_e32 v3, v3, v15
	v_mul_f32_e32 v3, v13, v3
	v_cvt_pk_bf16_f32 v3, v3, v3
	ds_write_b16 v1, v3 offset:2912
	ds_read_u16 v3, v1 offset:3184
	s_waitcnt lgkmcnt(0)
	v_lshlrev_b32_e32 v3, 16, v3
	v_mul_f32_e32 v13, 0xbfb8aa3b, v3
	v_exp_f32_e32 v13, v13
	s_nop 0
	v_add_f32_e32 v13, 1.0, v13
	v_rcp_f32_e32 v14, v13
	s_nop 0
	v_mul_f32_e32 v3, v3, v14
	v_mul_f32_e32 v3, v12, v3
	v_cvt_pk_bf16_f32 v3, v3, v3
	ds_write_b16 v1, v3 offset:3184
	ds_read_u16 v3, v1 offset:4544
	s_waitcnt lgkmcnt(0)
	v_lshlrev_b32_e32 v3, 16, v3
	v_mul_f32_e32 v12, 0xbfb8aa3b, v3
	v_exp_f32_e32 v12, v12
	s_nop 0
	v_add_f32_e32 v12, 1.0, v12
	v_rcp_f32_e32 v13, v12
	s_nop 0
	v_mul_f32_e32 v3, v3, v13
	v_mul_f32_e32 v3, v11, v3
	v_cvt_pk_bf16_f32 v3, v3, v3
	ds_write_b16 v1, v3 offset:4544
	ds_read_u16 v3, v1 offset:4816
	s_waitcnt lgkmcnt(0)
	v_lshlrev_b32_e32 v3, 16, v3
	v_mul_f32_e32 v11, 0xbfb8aa3b, v3
	v_exp_f32_e32 v11, v11
	s_nop 0
	v_add_f32_e32 v11, 1.0, v11
	v_rcp_f32_e32 v12, v11
	s_nop 0
	v_mul_f32_e32 v3, v3, v12
	v_mul_f32_e32 v3, v10, v3
	v_cvt_pk_bf16_f32 v3, v3, v3
	ds_write_b16 v1, v3 offset:4816
	ds_read_u16 v3, v1 offset:5088
	s_waitcnt lgkmcnt(0)
	v_lshlrev_b32_e32 v3, 16, v3
	v_mul_f32_e32 v10, 0xbfb8aa3b, v3
	v_exp_f32_e32 v10, v10
	s_nop 0
	v_add_f32_e32 v10, 1.0, v10
	v_rcp_f32_e32 v11, v10
	s_nop 0
	v_mul_f32_e32 v3, v3, v11
	v_mul_f32_e32 v3, v9, v3
	v_cvt_pk_bf16_f32 v3, v3, v3
	ds_write_b16 v1, v3 offset:5088
	ds_read_u16 v3, v1 offset:5360
	s_waitcnt lgkmcnt(0)
	v_lshlrev_b32_e32 v3, 16, v3
	v_mul_f32_e32 v9, 0xbfb8aa3b, v3
	v_exp_f32_e32 v9, v9
	s_nop 0
	v_add_f32_e32 v9, 1.0, v9
	v_rcp_f32_e32 v10, v9
	s_nop 0
	v_mul_f32_e32 v3, v3, v10
	v_mul_f32_e32 v3, v8, v3
	v_cvt_pk_bf16_f32 v3, v3, v3
	ds_write_b16 v1, v3 offset:5360
	ds_read_u16 v3, v1 offset:6720
	s_waitcnt lgkmcnt(0)
	v_lshlrev_b32_e32 v3, 16, v3
	v_mul_f32_e32 v8, 0xbfb8aa3b, v3
	v_exp_f32_e32 v8, v8
	s_nop 0
	v_add_f32_e32 v8, 1.0, v8
	v_rcp_f32_e32 v9, v8
	s_nop 0
	v_mul_f32_e32 v3, v3, v9
	v_mul_f32_e32 v3, v7, v3
	v_cvt_pk_bf16_f32 v3, v3, v3
	ds_write_b16 v1, v3 offset:6720
	ds_read_u16 v3, v1 offset:6992
	s_waitcnt lgkmcnt(0)
	v_lshlrev_b32_e32 v3, 16, v3
	v_mul_f32_e32 v7, 0xbfb8aa3b, v3
	v_exp_f32_e32 v7, v7
	s_nop 0
	v_add_f32_e32 v7, 1.0, v7
	v_rcp_f32_e32 v8, v7
	s_nop 0
	v_mul_f32_e32 v3, v3, v8
	v_mul_f32_e32 v3, v6, v3
	v_cvt_pk_bf16_f32 v3, v3, v3
	ds_write_b16 v1, v3 offset:6992
	ds_read_u16 v3, v1 offset:7264
	s_waitcnt lgkmcnt(0)
	v_lshlrev_b32_e32 v3, 16, v3
	v_mul_f32_e32 v6, 0xbfb8aa3b, v3
	v_exp_f32_e32 v6, v6
	s_nop 0
	v_add_f32_e32 v6, 1.0, v6
	v_rcp_f32_e32 v7, v6
	s_nop 0
	v_mul_f32_e32 v3, v3, v7
	v_mul_f32_e32 v3, v5, v3
	v_cvt_pk_bf16_f32 v3, v3, v3
	ds_write_b16 v1, v3 offset:7264
	ds_read_u16 v3, v1 offset:7536
	s_waitcnt lgkmcnt(0)
	v_lshlrev_b32_e32 v3, 16, v3
	v_mul_f32_e32 v4, 0xbfb8aa3b, v3
	v_exp_f32_e32 v4, v4
	s_nop 0
	v_add_f32_e32 v4, 1.0, v4
	v_div_scale_f32 v5, s[0:1], v4, v4, v3
	s_nop 0
	v_rcp_f32_e32 v5, v4
	s_nop 0
	v_mul_f32_e32 v3, v3, v5
	v_mul_f32_e32 v2, v2, v3
	v_cvt_pk_bf16_f32 v2, v2, s0
	ds_write_b16 v1, v2 offset:7536
	s_waitcnt lgkmcnt(0)
	ds_read_b128 v[2:5], v92
	v_lshl_add_u64 v[6:7], v[90:91], 0, s[24:25]
	v_lshl_add_u64 v[8:9], v[6:7], 0, v[66:67]
	s_waitcnt lgkmcnt(0)
	global_store_dwordx4 v[8:9], v[2:5], off
	ds_read_b128 v[2:5], v92 offset:1088
	v_lshl_add_u64 v[8:9], v[6:7], 0, v[68:69]
	s_waitcnt lgkmcnt(0)
	global_store_dwordx4 v[8:9], v[2:5], off
	ds_read_b128 v[2:5], v92 offset:2176
	v_lshl_add_u64 v[8:9], v[6:7], 0, v[70:71]
	s_waitcnt lgkmcnt(0)
	global_store_dwordx4 v[8:9], v[2:5], off
	ds_read_b128 v[2:5], v92 offset:3264
	v_lshl_add_u64 v[8:9], v[6:7], 0, v[72:73]
	s_waitcnt lgkmcnt(0)
	global_store_dwordx4 v[8:9], v[2:5], off
	ds_read_b128 v[2:5], v92 offset:4352
	v_lshl_add_u64 v[8:9], v[6:7], 0, v[74:75]
	s_waitcnt lgkmcnt(0)
	global_store_dwordx4 v[8:9], v[2:5], off
	ds_read_b128 v[2:5], v92 offset:5440
	v_lshl_add_u64 v[8:9], v[6:7], 0, v[76:77]
	s_waitcnt lgkmcnt(0)
	global_store_dwordx4 v[8:9], v[2:5], off
	ds_read_b128 v[2:5], v92 offset:6528
	v_lshl_add_u64 v[8:9], v[6:7], 0, v[78:79]
	v_lshl_add_u64 v[6:7], v[6:7], 0, v[80:81]
	s_waitcnt lgkmcnt(0)
	global_store_dwordx4 v[8:9], v[2:5], off
	ds_read_b128 v[2:5], v92 offset:7616
	s_waitcnt lgkmcnt(0)
	global_store_dwordx4 v[6:7], v[2:5], off
	s_waitcnt lgkmcnt(0)
	s_cbranch_scc1 .LBB0_1216
